# v7: v4 + write-through (sc1) tile stores in the GEMM epilogues of P1 P2 P4 P8 P9 P11 (less dirty L2 at the grid barrier's release fence)
# baseline (speedup 1.0000x reference)
; __host__ __device__ __forceinline__ size_t blk(int r, int k, int K) { return (((size_t)((r >> 8) * (K >> 6) + (k >> 6))) << 14) + (size_t)(((r & 255) << 6) + (k & 63)); }
; __device__ __forceinline__ unsigned pk2(float lo, float hi) { f32x2 v = {lo, hi}; bf16x2_t b = __builtin_convertvector(v, bf16x2_t); return __builtin_bit_cast(unsigned, b); }
; __device__ __forceinline__ float fsilu(float x) { return x * fsigmoid(x); }
;     __device__ __forceinline__ void operator()(const f32x4 (&acc)[2][2][4][2], const Unit& u, int wr, int wc, int fr, int fq) const {
;     ...
;             for (int m = 0; m < 4; ++m) { const int row = row0 + ai * HALF + m * 16; bf16_t* rowp = O + blk(row, col0, ldc);
;                 const float rs = ssq ? 1.0f / sqrtf(ssq[row] * (1.0f / D) + RMS_EPS) : 1.0f;
;                 const f32x4 a0 = acc[ai][0][m][0] * rs, a1 = acc[ai][0][m][1] * rs, b0 = acc[ai][1][m][0] * rs, b1 = acc[ai][1][m][1] * rs;
;                 u32x4 w; w.x = pk2(fsilu(a0[0]) * b0[0], fsilu(a0[1]) * b0[1]); w.y = pk2(fsilu(a0[2]) * b0[2], fsilu(a0[3]) * b0[3]);
;                 w.z = pk2(fsilu(a1[0]) * b1[0], fsilu(a1[1]) * b1[1]); w.w = pk2(fsilu(a1[2]) * b1[2], fsilu(a1[3]) * b1[3]);
.LBB0_118:
	v_mul_f32_e32 v154, 0xbfb8aa3b, v126
	v_exp_f32_e32 v156, v154
	v_mul_f32_e32 v154, 0xbfb8aa3b, v127
	v_exp_f32_e32 v157, v154
	v_mul_f32_e32 v158, 0xbfb8aa3b, v128
	v_mul_f32_e32 v159, 0xbfb8aa3b, v129
	v_exp_f32_e32 v158, v158
	v_exp_f32_e32 v159, v159
	v_add_f32_e32 v156, 1.0, v156
	v_add_f32_e32 v157, 1.0, v157
	v_rcp_f32_e32 v156, v156
	v_rcp_f32_e32 v157, v157
	v_add_f32_e32 v158, 1.0, v158
	v_add_f32_e32 v159, 1.0, v159
	v_rcp_f32_e32 v158, v158
	v_rcp_f32_e32 v159, v159
	v_pk_mul_f32 v[126:127], v[126:127], v[156:157]
	s_lshl_b32 s19, s46, 8
	v_pk_mul_f32 v[122:123], v[126:127], v[122:123]
	v_pk_mul_f32 v[126:127], v[128:129], v[158:159]
	v_cvt_pk_bf16_f32 v122, v122, v123
	v_mul_f32_e32 v123, 0xbfb8aa3b, v118
	v_pk_mul_f32 v[124:125], v[126:127], v[124:125]
	v_exp_f32_e32 v126, v123
	v_mul_f32_e32 v123, 0xbfb8aa3b, v119
	v_exp_f32_e32 v127, v123
	v_cvt_pk_bf16_f32 v123, v124, v125
	v_add_f32_e32 v124, 1.0, v126
	v_mul_f32_e32 v126, 0xbfb8aa3b, v120
	v_add_f32_e32 v125, 1.0, v127
	v_mul_f32_e32 v127, 0xbfb8aa3b, v121
	v_exp_f32_e32 v126, v126
	v_exp_f32_e32 v127, v127
	v_rcp_f32_e32 v124, v124
	v_rcp_f32_e32 v125, v125
	v_add_f32_e32 v126, 1.0, v126
	v_add_f32_e32 v127, 1.0, v127
	v_rcp_f32_e32 v126, v126
	v_rcp_f32_e32 v127, v127
	v_pk_mul_f32 v[118:119], v[118:119], v[124:125]
	s_add_i32 s25, s19, s56
	v_pk_mul_f32 v[114:115], v[118:119], v[114:115]
	s_lshl_b32 s19, s47, 7
	v_cvt_pk_bf16_f32 v124, v114, v115
	v_pk_mul_f32 v[114:115], v[120:121], v[126:127]
	v_or_b32_e32 v160, s25, v1
	v_pk_mul_f32 v[114:115], v[114:115], v[116:117]
	v_mul_f32_e32 v116, 0xbfb8aa3b, v112
	v_cvt_pk_bf16_f32 v125, v114, v115
	v_mul_f32_e32 v114, 0xbfb8aa3b, v110
	v_mul_f32_e32 v115, 0xbfb8aa3b, v111
	v_exp_f32_e32 v114, v114
	v_exp_f32_e32 v115, v115
	v_mul_f32_e32 v117, 0xbfb8aa3b, v113
	v_exp_f32_e32 v116, v116
	v_exp_f32_e32 v117, v117
	v_add_f32_e32 v114, 1.0, v114
	v_add_f32_e32 v115, 1.0, v115
	v_rcp_f32_e32 v114, v114
	v_rcp_f32_e32 v115, v115
	v_add_f32_e32 v116, 1.0, v116
	v_add_f32_e32 v117, 1.0, v117
	v_rcp_f32_e32 v116, v116
	v_rcp_f32_e32 v117, v117
	v_pk_mul_f32 v[110:111], v[110:111], v[114:115]
	s_or_b32 s19, s19, s57
	v_pk_mul_f32 v[106:107], v[110:111], v[106:107]
	v_pk_mul_f32 v[110:111], v[112:113], v[116:117]
	v_cvt_pk_bf16_f32 v106, v106, v107
	v_mul_f32_e32 v107, 0xbfb8aa3b, v102
	v_pk_mul_f32 v[108:109], v[110:111], v[108:109]
	v_exp_f32_e32 v110, v107
	v_mul_f32_e32 v107, 0xbfb8aa3b, v103
	v_exp_f32_e32 v111, v107
	v_cvt_pk_bf16_f32 v107, v108, v109
	v_add_f32_e32 v108, 1.0, v110
	v_mul_f32_e32 v110, 0xbfb8aa3b, v104
	v_add_f32_e32 v109, 1.0, v111
	v_mul_f32_e32 v111, 0xbfb8aa3b, v105
	v_exp_f32_e32 v110, v110
	v_exp_f32_e32 v111, v111
	v_rcp_f32_e32 v108, v108
	v_rcp_f32_e32 v109, v109
	v_add_f32_e32 v110, 1.0, v110
	v_add_f32_e32 v111, 1.0, v111
	v_rcp_f32_e32 v110, v110
	v_rcp_f32_e32 v111, v111
	v_pk_mul_f32 v[102:103], v[102:103], v[108:109]
	s_ashr_i32 s25, s25, 8
	v_pk_mul_f32 v[98:99], v[102:103], v[98:99]
	s_ashr_i32 s19, s19, 6
	v_cvt_pk_bf16_f32 v108, v98, v99
	v_pk_mul_f32 v[98:99], v[104:105], v[110:111]
	s_mulk_i32 s25, 0xac
	v_pk_mul_f32 v[98:99], v[98:99], v[100:101]
	v_mul_f32_e32 v100, 0xbfb8aa3b, v96
	v_cvt_pk_bf16_f32 v109, v98, v99
	v_mul_f32_e32 v98, 0xbfb8aa3b, v94
	v_mul_f32_e32 v99, 0xbfb8aa3b, v95
	v_exp_f32_e32 v98, v98
	v_exp_f32_e32 v99, v99
	v_mul_f32_e32 v101, 0xbfb8aa3b, v97
	v_exp_f32_e32 v100, v100
	v_exp_f32_e32 v101, v101
	v_add_f32_e32 v98, 1.0, v98
	v_add_f32_e32 v99, 1.0, v99
	v_rcp_f32_e32 v98, v98
	v_rcp_f32_e32 v99, v99
	v_add_f32_e32 v100, 1.0, v100
	v_add_f32_e32 v101, 1.0, v101
	v_rcp_f32_e32 v100, v100
	v_rcp_f32_e32 v101, v101
	v_pk_mul_f32 v[94:95], v[94:95], v[98:99]
	s_add_i32 s46, s25, s19
	v_pk_mul_f32 v[90:91], v[94:95], v[90:91]
	v_pk_mul_f32 v[94:95], v[96:97], v[100:101]
	v_cvt_pk_bf16_f32 v90, v90, v91
	v_mul_f32_e32 v91, 0xbfb8aa3b, v86
	v_pk_mul_f32 v[92:93], v[94:95], v[92:93]
	v_exp_f32_e32 v94, v91
	v_mul_f32_e32 v91, 0xbfb8aa3b, v87
	v_exp_f32_e32 v95, v91
	v_cvt_pk_bf16_f32 v91, v92, v93
	v_add_f32_e32 v92, 1.0, v94
	v_mul_f32_e32 v94, 0xbfb8aa3b, v88
	v_add_f32_e32 v93, 1.0, v95
	v_mul_f32_e32 v95, 0xbfb8aa3b, v89
	v_exp_f32_e32 v94, v94
	v_exp_f32_e32 v95, v95
	v_rcp_f32_e32 v92, v92
	v_rcp_f32_e32 v93, v93
	v_add_f32_e32 v94, 1.0, v94
	v_add_f32_e32 v95, 1.0, v95
	v_rcp_f32_e32 v94, v94
	v_rcp_f32_e32 v95, v95
	v_pk_mul_f32 v[86:87], v[86:87], v[92:93]
	s_ashr_i32 s47, s46, 31
	v_pk_mul_f32 v[82:83], v[86:87], v[82:83]
	v_mul_f32_e32 v86, 0xbfb8aa3b, v80
	v_cvt_pk_bf16_f32 v92, v82, v83
	v_pk_mul_f32 v[82:83], v[88:89], v[94:95]
	v_mul_f32_e32 v87, 0xbfb8aa3b, v81
	v_pk_mul_f32 v[82:83], v[82:83], v[84:85]
	v_mul_f32_e32 v84, 0xbfb8aa3b, v78
	v_mul_f32_e32 v85, 0xbfb8aa3b, v79
	v_exp_f32_e32 v84, v84
	v_exp_f32_e32 v85, v85
	v_exp_f32_e32 v86, v86
	v_exp_f32_e32 v87, v87
	v_add_f32_e32 v84, 1.0, v84
	v_add_f32_e32 v85, 1.0, v85
	v_rcp_f32_e32 v84, v84
	v_rcp_f32_e32 v85, v85
	v_add_f32_e32 v86, 1.0, v86
	v_add_f32_e32 v87, 1.0, v87
	v_rcp_f32_e32 v86, v86
	v_rcp_f32_e32 v87, v87
	v_pk_mul_f32 v[78:79], v[78:79], v[84:85]
	v_lshlrev_b32_e32 v153, 6, v160
	v_pk_mul_f32 v[74:75], v[78:79], v[74:75]
	v_pk_mul_f32 v[78:79], v[80:81], v[86:87]
	v_cvt_pk_bf16_f32 v74, v74, v75
	v_mul_f32_e32 v75, 0xbfb8aa3b, v70
	v_pk_mul_f32 v[76:77], v[78:79], v[76:77]
	v_exp_f32_e32 v78, v75
	v_mul_f32_e32 v75, 0xbfb8aa3b, v71
	v_exp_f32_e32 v79, v75
	v_cvt_pk_bf16_f32 v75, v76, v77
	v_add_f32_e32 v76, 1.0, v78
	v_mul_f32_e32 v78, 0xbfb8aa3b, v72
	v_add_f32_e32 v77, 1.0, v79
	v_mul_f32_e32 v79, 0xbfb8aa3b, v73
	v_exp_f32_e32 v78, v78
	v_exp_f32_e32 v79, v79
; __host__ __device__ __forceinline__ size_t blk(int r, int k, int K) { return (((size_t)((r >> 8) * (K >> 6) + (k >> 6))) << 14) + (size_t)(((r & 255) << 6) + (k & 63)); }
; __device__ __forceinline__ unsigned pk2(float lo, float hi) { f32x2 v = {lo, hi}; bf16x2_t b = __builtin_convertvector(v, bf16x2_t); return __builtin_bit_cast(unsigned, b); }
; __device__ __forceinline__ float fsilu(float x) { return x * fsigmoid(x); }
;     __device__ __forceinline__ void operator()(const f32x4 (&acc)[2][2][4][2], const Unit& u, int wr, int wc, int fr, int fq) const {
;     ...
;             for (int m = 0; m < 4; ++m) { const int row = row0 + ai * HALF + m * 16; bf16_t* rowp = O + blk(row, col0, ldc);
;                 const float rs = ssq ? 1.0f / sqrtf(ssq[row] * (1.0f / D) + RMS_EPS) : 1.0f;
;                 const f32x4 a0 = acc[ai][0][m][0] * rs, a1 = acc[ai][0][m][1] * rs, b0 = acc[ai][1][m][0] * rs, b1 = acc[ai][1][m][1] * rs;
;                 u32x4 w; w.x = pk2(fsilu(a0[0]) * b0[0], fsilu(a0[1]) * b0[1]); w.y = pk2(fsilu(a0[2]) * b0[2], fsilu(a0[3]) * b0[3]);
;                 w.z = pk2(fsilu(a1[0]) * b1[0], fsilu(a1[1]) * b1[1]); w.w = pk2(fsilu(a1[2]) * b1[2], fsilu(a1[3]) * b1[3]);
;                 *(u32x4*)rowp = w; }
	v_rcp_f32_e32 v76, v76
	v_rcp_f32_e32 v77, v77
	v_add_f32_e32 v78, 1.0, v78
	v_add_f32_e32 v79, 1.0, v79
	v_rcp_f32_e32 v78, v78
	v_rcp_f32_e32 v79, v79
	v_pk_mul_f32 v[70:71], v[70:71], v[76:77]
	s_lshl_b64 s[46:47], s[46:47], 15
	v_pk_mul_f32 v[66:67], v[70:71], v[66:67]
	v_and_or_b32 v138, v153, s63, v149
	v_cvt_pk_bf16_f32 v76, v66, v67
	v_pk_mul_f32 v[66:67], v[72:73], v[78:79]
	s_add_u32 s46, s20, s46
	v_pk_mul_f32 v[66:67], v[66:67], v[68:69]
	v_add_u32_e32 v68, 0x80, v160
	v_cvt_pk_bf16_f32 v77, v66, v67
	v_lshrrev_b32_e32 v66, 8, v68
	v_lshlrev_b32_e32 v68, 6, v68
	s_addc_u32 s47, s21, s47
	v_lshlrev_b32_e32 v138, 1, v138
	v_and_or_b32 v68, v68, s63, v149
	v_lshl_add_u64 v[154:155], s[46:47], 0, v[138:139]
	global_store_dwordx4 v138, v[122:125], s[46:47] sc1
	global_store_dwordx4 v138, v[106:109], s[46:47] offset:2048 sc1
	v_lshlrev_b32_e32 v138, 1, v68
	v_mul_f32_e32 v68, 0xbfb8aa3b, v62
	v_exp_f32_e32 v70, v68
	v_mul_f32_e32 v68, 0xbfb8aa3b, v63
	v_exp_f32_e32 v71, v68
	v_mul_f32_e32 v72, 0xbfb8aa3b, v64
	v_mul_f32_e32 v73, 0xbfb8aa3b, v65
	v_exp_f32_e32 v72, v72
	v_exp_f32_e32 v73, v73
	v_add_f32_e32 v70, 1.0, v70
	v_add_f32_e32 v71, 1.0, v71
	v_rcp_f32_e32 v70, v70
	v_rcp_f32_e32 v71, v71
	v_add_f32_e32 v72, 1.0, v72
	v_add_f32_e32 v73, 1.0, v73
	v_rcp_f32_e32 v72, v72
	v_rcp_f32_e32 v73, v73
	v_pk_mul_f32 v[62:63], v[62:63], v[70:71]
	v_mov_b32_e32 v67, s19
	v_pk_mul_f32 v[58:59], v[62:63], v[58:59]
	v_pk_mul_f32 v[62:63], v[64:65], v[72:73]
	v_cvt_pk_bf16_f32 v58, v58, v59
	v_mul_f32_e32 v59, 0xbfb8aa3b, v54
	v_pk_mul_f32 v[60:61], v[62:63], v[60:61]
	v_exp_f32_e32 v62, v59
	v_mul_f32_e32 v59, 0xbfb8aa3b, v55
	v_exp_f32_e32 v63, v59
	v_cvt_pk_bf16_f32 v59, v60, v61
	v_add_f32_e32 v60, 1.0, v62
	v_mul_f32_e32 v62, 0xbfb8aa3b, v56
	v_add_f32_e32 v61, 1.0, v63
	v_mul_f32_e32 v63, 0xbfb8aa3b, v57
	v_exp_f32_e32 v62, v62
	v_exp_f32_e32 v63, v63
	v_rcp_f32_e32 v60, v60
	v_rcp_f32_e32 v61, v61
	v_add_f32_e32 v62, 1.0, v62
	v_add_f32_e32 v63, 1.0, v63
	v_rcp_f32_e32 v62, v62
	v_rcp_f32_e32 v63, v63
	v_pk_mul_f32 v[54:55], v[54:55], v[60:61]
	s_movk_i32 s19, 0xac
	v_pk_mul_f32 v[50:51], v[54:55], v[50:51]
	v_mad_i32_i24 v66, v66, s19, v67
	v_cvt_pk_bf16_f32 v60, v50, v51
	v_pk_mul_f32 v[50:51], v[56:57], v[62:63]
	v_ashrrev_i32_e32 v67, 31, v66
	v_pk_mul_f32 v[50:51], v[50:51], v[52:53]
	v_lshlrev_b64 v[66:67], 15, v[66:67]
	v_cvt_pk_bf16_f32 v61, v50, v51
	v_add_u32_e32 v50, 0x2400, v153
	s_movk_i32 s19, 0x37c0
	v_lshl_add_u64 v[66:67], s[20:21], 0, v[66:67]
	v_and_or_b32 v50, v50, s19, v149
	v_lshl_add_u64 v[68:69], v[66:67], 0, v[138:139]
	v_lshlrev_b32_e32 v138, 1, v50
	v_mul_f32_e32 v50, 0xbfb8aa3b, v46
	v_exp_f32_e32 v52, v50
	v_mul_f32_e32 v50, 0xbfb8aa3b, v47
	v_exp_f32_e32 v53, v50
	v_mul_f32_e32 v54, 0xbfb8aa3b, v48
	v_mul_f32_e32 v55, 0xbfb8aa3b, v49
	v_exp_f32_e32 v54, v54
	v_exp_f32_e32 v55, v55
	v_add_f32_e32 v52, 1.0, v52
	v_add_f32_e32 v53, 1.0, v53
	v_rcp_f32_e32 v52, v52
	v_rcp_f32_e32 v53, v53
	v_add_f32_e32 v54, 1.0, v54
	v_add_f32_e32 v55, 1.0, v55
	v_rcp_f32_e32 v54, v54
	v_rcp_f32_e32 v55, v55
	v_pk_mul_f32 v[46:47], v[46:47], v[52:53]
	s_movk_i32 s19, 0x3bc0
	v_pk_mul_f32 v[42:43], v[46:47], v[42:43]
	v_pk_mul_f32 v[46:47], v[48:49], v[54:55]
	v_cvt_pk_bf16_f32 v42, v42, v43
	v_mul_f32_e32 v43, 0xbfb8aa3b, v38
	v_pk_mul_f32 v[44:45], v[46:47], v[44:45]
	v_exp_f32_e32 v46, v43
	v_mul_f32_e32 v43, 0xbfb8aa3b, v39
	v_exp_f32_e32 v47, v43
	v_cvt_pk_bf16_f32 v43, v44, v45
	v_add_f32_e32 v44, 1.0, v46
	v_mul_f32_e32 v46, 0xbfb8aa3b, v40
	v_add_f32_e32 v45, 1.0, v47
	v_mul_f32_e32 v47, 0xbfb8aa3b, v41
	v_exp_f32_e32 v46, v46
	v_exp_f32_e32 v47, v47
	v_rcp_f32_e32 v44, v44
	v_rcp_f32_e32 v45, v45
	v_add_f32_e32 v46, 1.0, v46
	v_add_f32_e32 v47, 1.0, v47
	v_rcp_f32_e32 v46, v46
	v_rcp_f32_e32 v47, v47
	v_pk_mul_f32 v[38:39], v[38:39], v[44:45]
	v_lshl_add_u64 v[50:51], v[66:67], 0, v[138:139]
; __host__ __device__ __forceinline__ size_t blk(int r, int k, int K) { return (((size_t)((r >> 8) * (K >> 6) + (k >> 6))) << 14) + (size_t)(((r & 255) << 6) + (k & 63)); }
; __device__ __forceinline__ unsigned pk2(float lo, float hi) { f32x2 v = {lo, hi}; bf16x2_t b = __builtin_convertvector(v, bf16x2_t); return __builtin_bit_cast(unsigned, b); }
; __device__ __forceinline__ float fsilu(float x) { return x * fsigmoid(x); }
;     __device__ __forceinline__ void operator()(const f32x4 (&acc)[2][2][4][2], const Unit& u, int wr, int wc, int fr, int fq) const {
;     ...
;             for (int m = 0; m < 4; ++m) { const int row = row0 + ai * HALF + m * 16; bf16_t* rowp = O + blk(row, col0, ldc);
;                 const float rs = ssq ? 1.0f / sqrtf(ssq[row] * (1.0f / D) + RMS_EPS) : 1.0f;
;                 const f32x4 a0 = acc[ai][0][m][0] * rs, a1 = acc[ai][0][m][1] * rs, b0 = acc[ai][1][m][0] * rs, b1 = acc[ai][1][m][1] * rs;
;                 u32x4 w; w.x = pk2(fsilu(a0[0]) * b0[0], fsilu(a0[1]) * b0[1]); w.y = pk2(fsilu(a0[2]) * b0[2], fsilu(a0[3]) * b0[3]);
;                 w.z = pk2(fsilu(a1[0]) * b1[0], fsilu(a1[1]) * b1[1]); w.w = pk2(fsilu(a1[2]) * b1[2], fsilu(a1[3]) * b1[3]);
;                 *(u32x4*)rowp = w; }
	v_pk_mul_f32 v[34:35], v[38:39], v[34:35]
	v_mul_f32_e32 v38, 0xbfb8aa3b, v32
	v_cvt_pk_bf16_f32 v44, v34, v35
	v_pk_mul_f32 v[34:35], v[40:41], v[46:47]
	v_mul_f32_e32 v39, 0xbfb8aa3b, v33
	v_pk_mul_f32 v[34:35], v[34:35], v[36:37]
	v_exp_f32_e32 v38, v38
	v_cvt_pk_bf16_f32 v45, v34, v35
	v_add_u32_e32 v34, 0x2800, v153
	v_and_or_b32 v34, v34, s19, v149
	v_lshlrev_b32_e32 v138, 1, v34
	v_mul_f32_e32 v34, 0xbfb8aa3b, v30
	v_exp_f32_e32 v36, v34
	v_mul_f32_e32 v34, 0xbfb8aa3b, v31
	v_exp_f32_e32 v37, v34
	v_exp_f32_e32 v39, v39
	v_add_f32_e32 v36, 1.0, v36
	v_rcp_f32_e32 v36, v36
	v_add_f32_e32 v37, 1.0, v37
	v_rcp_f32_e32 v37, v37
	v_add_f32_e32 v38, 1.0, v38
	v_add_f32_e32 v39, 1.0, v39
	v_rcp_f32_e32 v38, v38
	v_rcp_f32_e32 v39, v39
	v_pk_mul_f32 v[30:31], v[30:31], v[36:37]
	s_movk_i32 s19, 0x3fc0
	v_pk_mul_f32 v[26:27], v[30:31], v[26:27]
	v_pk_mul_f32 v[30:31], v[32:33], v[38:39]
	v_cvt_pk_bf16_f32 v26, v26, v27
	v_mul_f32_e32 v27, 0xbfb8aa3b, v22
	v_pk_mul_f32 v[28:29], v[30:31], v[28:29]
	v_exp_f32_e32 v30, v27
	v_mul_f32_e32 v27, 0xbfb8aa3b, v23
	v_exp_f32_e32 v31, v27
	v_cvt_pk_bf16_f32 v27, v28, v29
	v_add_f32_e32 v28, 1.0, v30
	v_mul_f32_e32 v30, 0xbfb8aa3b, v24
	v_add_f32_e32 v29, 1.0, v31
	v_mul_f32_e32 v31, 0xbfb8aa3b, v25
	v_exp_f32_e32 v30, v30
	v_exp_f32_e32 v31, v31
	v_rcp_f32_e32 v28, v28
	v_rcp_f32_e32 v29, v29
	v_add_f32_e32 v30, 1.0, v30
	v_add_f32_e32 v31, 1.0, v31
	v_rcp_f32_e32 v30, v30
	v_rcp_f32_e32 v31, v31
	v_pk_mul_f32 v[22:23], v[22:23], v[28:29]
	v_lshl_add_u64 v[34:35], v[66:67], 0, v[138:139]
	v_pk_mul_f32 v[18:19], v[22:23], v[18:19]
	v_mul_f32_e32 v22, 0xbfb8aa3b, v16
	v_cvt_pk_bf16_f32 v28, v18, v19
	v_pk_mul_f32 v[18:19], v[24:25], v[30:31]
	v_mul_f32_e32 v23, 0xbfb8aa3b, v17
	v_pk_mul_f32 v[18:19], v[18:19], v[20:21]
	v_exp_f32_e32 v22, v22
	v_cvt_pk_bf16_f32 v29, v18, v19
	v_add_u32_e32 v18, 0x2c00, v153
	v_and_or_b32 v18, v18, s19, v149
	v_lshlrev_b32_e32 v138, 1, v18
	v_mul_f32_e32 v18, 0xbfb8aa3b, v14
	v_exp_f32_e32 v20, v18
	v_mul_f32_e32 v18, 0xbfb8aa3b, v15
	v_exp_f32_e32 v21, v18
	v_exp_f32_e32 v23, v23
	v_add_f32_e32 v20, 1.0, v20
	v_rcp_f32_e32 v20, v20
	v_add_f32_e32 v21, 1.0, v21
	v_rcp_f32_e32 v21, v21
	v_add_f32_e32 v22, 1.0, v22
	v_add_f32_e32 v23, 1.0, v23
	v_rcp_f32_e32 v22, v22
	v_rcp_f32_e32 v23, v23
	v_pk_mul_f32 v[14:15], v[14:15], v[20:21]
	s_movk_i32 s25, 0x1000
	v_pk_mul_f32 v[10:11], v[14:15], v[10:11]
	v_pk_mul_f32 v[14:15], v[16:17], v[22:23]
	v_cvt_pk_bf16_f32 v10, v10, v11
	v_mul_f32_e32 v11, 0xbfb8aa3b, v6
	v_pk_mul_f32 v[12:13], v[14:15], v[12:13]
	v_exp_f32_e32 v14, v11
	v_mul_f32_e32 v11, 0xbfb8aa3b, v7
	v_exp_f32_e32 v15, v11
	v_cvt_pk_bf16_f32 v11, v12, v13
	v_add_f32_e32 v12, 1.0, v14
	v_mul_f32_e32 v14, 0xbfb8aa3b, v8
	v_add_f32_e32 v13, 1.0, v15
	v_mul_f32_e32 v15, 0xbfb8aa3b, v9
	v_exp_f32_e32 v14, v14
	v_exp_f32_e32 v15, v15
	v_rcp_f32_e32 v12, v12
	v_rcp_f32_e32 v13, v13
	v_add_f32_e32 v14, 1.0, v14
	v_add_f32_e32 v15, 1.0, v15
	v_rcp_f32_e32 v14, v14
	v_rcp_f32_e32 v15, v15
	v_pk_mul_f32 v[6:7], v[6:7], v[12:13]
	v_cvt_pk_bf16_f32 v93, v82, v83
	v_pk_mul_f32 v[2:3], v[6:7], v[2:3]
	v_add_co_u32_e32 v82, vcc, s25, v154
	v_cvt_pk_bf16_f32 v12, v2, v3
	v_pk_mul_f32 v[2:3], v[8:9], v[14:15]
	v_addc_co_u32_e32 v83, vcc, 0, v155, vcc
	v_pk_mul_f32 v[2:3], v[2:3], v[4:5]
	v_lshl_add_u64 v[18:19], v[66:67], 0, v[138:139]
	v_cvt_pk_bf16_f32 v13, v2, v3
	s_andn2_b64 vcc, exec, s[0:1]
	s_mov_b64 s[0:1], -1
	global_store_dwordx4 v[82:83], v[90:93], off sc1
	global_store_dwordx4 v[82:83], v[74:77], off offset:2048 sc1
	global_store_dwordx4 v[68:69], v[58:61], off sc1
	global_store_dwordx4 v[50:51], v[42:45], off sc1
	global_store_dwordx4 v[34:35], v[26:29], off sc1
	global_store_dwordx4 v[18:19], v[10:13], off sc1
	s_cbranch_vccnz .LBB0_111
	s_andn2_b64 vcc, exec, s[10:11]
	s_cbranch_vccnz .LBB0_110
	s_barrier
	s_branch .LBB0_110

; __host__ __device__ __forceinline__ size_t blk(int r, int k, int K) { return (((size_t)((r >> 8) * (K >> 6) + (k >> 6))) << 14) + (size_t)(((r & 255) << 6) + (k & 63)); }
; __device__ __forceinline__ float bflo(unsigned w) { return __uint_as_float(w << 16); }
; __device__ __forceinline__ float bfhi(unsigned w) { return __uint_as_float(w & 0xffff0000u); }
; __device__ __forceinline__ unsigned pk2(float lo, float hi) { f32x2 v = {lo, hi}; bf16x2_t b = __builtin_convertvector(v, bf16x2_t); return __builtin_bit_cast(unsigned, b); }
;     __device__ __forceinline__ void operator()(const f32x4 (&acc)[2][2][4][2], const Unit& u, int wr, int wc, int fr, int fq) const {
;     ...
;             for (int m = 0; m < 4; ++m) { const int row = row0 + ai * HALF + m * 16; const size_t off = (size_t)row * D + col0; float s = 0.f;
; #pragma unroll
;                 for (int bj = 0; bj < 2; ++bj) {
;                     f32x4 v0, v1;
;                     if (MODE == 0) { v0 = *(const f32x4*)(base + off + bj * HALF); v1 = *(const f32x4*)(base + off + bj * HALF + 4); }
;                     else { const u32x4 r = *(const u32x4*)(bb + blk(row, col0 + bj * HALF, D)); v0 = (f32x4){bflo(r.x), bfhi(r.x), bflo(r.y), bfhi(r.y)}; v1 = (f32x4){bflo(r.z), bfhi(r.z), bflo(r.w), bfhi(r.w)}; }
;                     v0 += acc[ai][bj][m][0] * alpha; v1 += acc[ai][bj][m][1] * alpha;
;                     if (MODE == 2) { *(f32x4*)(out + off + bj * HALF) = v0; *(f32x4*)(out + off + bj * HALF + 4) = v1; }
;                     else {
;                         s += (v0[0] * v0[0] + v0[1] * v0[1]) + (v0[2] * v0[2] + v0[3] * v0[3]) + (v1[0] * v1[0] + v1[1] * v1[1]) + (v1[2] * v1[2] + v1[3] * v1[3]);
;                         u32x4 w; w.x = pk2(v0[0], v0[1]); w.y = pk2(v0[2], v0[3]); w.z = pk2(v1[0], v1[1]); w.w = pk2(v1[2], v1[3]); *(u32x4*)(xb + blk(row, col0 + bj * HALF, D)) = w; } }
;                 if (MODE != 2) { s += __shfl_xor(s, 16); s += __shfl_xor(s, 32); if (fq == 0) unsafeAtomicAdd(ssq + row, s); } }
.LBB0_203:
	s_lshl_b32 s44, s73, 8
	s_add_i32 s44, s44, s35
	v_or_b32_e32 v150, s44, v1
	s_lshl_b32 s45, s72, 8
	s_or_b32 s45, s45, s56
	v_ashrrev_i32_e32 v151, 31, v150
	v_or_b32_e32 v148, s45, v152
	v_lshlrev_b64 v[158:159], 14, v[150:151]
	v_ashrrev_i32_e32 v149, 31, v148
	v_lshl_add_u64 v[158:159], s[8:9], 0, v[158:159]
	v_lshl_add_u64 v[168:169], v[148:149], 2, v[158:159]
	global_load_dwordx4 v[160:163], v[168:169], off
	global_load_dwordx4 v[164:167], v[168:169], off offset:16
	s_ashr_i32 s44, s44, 2
	s_ashr_i32 s50, s45, 6
	s_and_b32 s46, s44, 0xffffffc0
	s_add_i32 s44, s46, s50
	v_bitop3_b32 v158, s45, 56, v152 bitop3:0xc8
	s_ashr_i32 s45, s44, 31
	v_lshlrev_b32_e32 v138, 6, v150
	s_lshl_b64 s[44:45], s[44:45], 15
	v_and_or_b32 v138, v138, s62, v158
	s_add_u32 s44, s42, s44
	v_lshlrev_b32_e32 v138, 1, v138
	s_addc_u32 s45, s43, s45
	v_xor_b32_e32 v159, 32, v157
	s_or_b32 s51, s50, 2
	s_add_i32 s46, s46, s51
	s_ashr_i32 s47, s46, 31
	s_lshl_b64 s[46:47], s[46:47], 15
	s_add_u32 s46, s42, s46
	s_addc_u32 s47, s43, s47
	s_waitcnt vmcnt(0)
	v_pk_fma_f32 v[128:129], v[128:129], 0.5, v[162:163] op_sel_hi:[1,0,1]
	v_pk_fma_f32 v[170:171], v[126:127], 0.5, v[160:161] op_sel_hi:[1,0,1]
	v_pk_fma_f32 v[166:167], v[124:125], 0.5, v[166:167] op_sel_hi:[1,0,1]
	v_pk_fma_f32 v[164:165], v[122:123], 0.5, v[164:165] op_sel_hi:[1,0,1]
	v_cvt_pk_bf16_f32 v122, v170, v171
	v_cvt_pk_bf16_f32 v123, v128, v129
	v_cvt_pk_bf16_f32 v124, v164, v165
	v_cvt_pk_bf16_f32 v125, v166, v167
	global_store_dwordx4 v138, v[122:125], s[44:45] sc1
	global_load_dwordx4 v[124:127], v[168:169], off offset:512
	s_nop 0
	global_load_dwordx4 v[160:163], v[168:169], off offset:528
	v_and_b32_e32 v123, 64, v157
	v_xor_b32_e32 v122, 16, v157
	v_add_u32_e32 v123, 64, v123
	v_cmp_lt_i32_e32 vcc, v122, v123
	v_mul_f32_e32 v129, v129, v129
	v_fmac_f32_e32 v129, v128, v128
	v_cndmask_b32_e32 v122, v157, v122, vcc
	v_cmp_lt_i32_e32 vcc, v159, v123
	v_lshlrev_b32_e32 v123, 2, v122
	v_mul_f32_e32 v165, v165, v165
	v_cndmask_b32_e32 v159, v157, v159, vcc
	v_lshlrev_b32_e32 v122, 2, v159
	v_mul_f32_e32 v159, v171, v171
	v_fmac_f32_e32 v159, v170, v170
	v_add_f32_e32 v128, v159, v129
	v_mul_f32_e32 v167, v167, v167
	v_fmac_f32_e32 v165, v164, v164
	v_fmac_f32_e32 v167, v166, v166
	v_add_f32_e32 v128, v165, v128
	v_add_f32_e32 v128, v167, v128
	s_waitcnt vmcnt(1)
	v_pk_fma_f32 v[120:121], v[120:121], 0.5, v[126:127] op_sel_hi:[1,0,1]
	v_pk_fma_f32 v[118:119], v[118:119], 0.5, v[124:125] op_sel_hi:[1,0,1]
	s_waitcnt vmcnt(0)
	v_pk_fma_f32 v[114:115], v[114:115], 0.5, v[160:161] op_sel_hi:[1,0,1]
	v_mul_f32_e32 v126, v119, v119
	v_mul_f32_e32 v127, v121, v121
	v_pk_fma_f32 v[124:125], v[116:117], 0.5, v[162:163] op_sel_hi:[1,0,1]
	v_mul_f32_e32 v129, v115, v115
	v_fmac_f32_e32 v126, v118, v118
	v_fmac_f32_e32 v127, v120, v120
	v_mul_f32_e32 v159, v125, v125
	v_cvt_pk_bf16_f32 v116, v118, v119
	v_fmac_f32_e32 v129, v114, v114
	v_add_f32_e32 v118, v126, v127
	v_fmac_f32_e32 v159, v124, v124
	v_add_f32_e32 v118, v129, v118
	v_add_f32_e32 v118, v159, v118
	v_cvt_pk_bf16_f32 v117, v120, v121
	v_add_f32_e32 v120, v128, v118
	v_cvt_pk_bf16_f32 v118, v114, v115
	ds_bpermute_b32 v114, v123, v120
	v_cvt_pk_bf16_f32 v119, v124, v125
	global_store_dwordx4 v138, v[116:119], s[46:47] sc1
	s_waitcnt lgkmcnt(0)
	v_add_f32_e32 v114, v120, v114
	ds_bpermute_b32 v115, v122, v114
	s_and_saveexec_b64 s[48:49], s[0:1]
	s_cbranch_execz .LBB0_205
	v_lshl_add_u64 v[116:117], v[150:151], 2, s[10:11]
	s_waitcnt lgkmcnt(0)
	v_add_f32_e32 v114, v114, v115
	global_atomic_add_f32 v[116:117], v114, off
.LBB0_205:
	s_or_b64 exec, exec, s[48:49]
	v_or_b32_e32 v114, 16, v150
	s_waitcnt lgkmcnt(0)
	v_ashrrev_i32_e32 v115, 31, v114
	v_lshlrev_b64 v[116:117], 14, v[114:115]
	v_lshl_add_u64 v[116:117], s[8:9], 0, v[116:117]
	v_lshl_add_u64 v[120:121], v[148:149], 2, v[116:117]
	global_load_dwordx4 v[116:119], v[120:121], off
	global_load_dwordx4 v[124:127], v[120:121], off offset:16
	v_lshlrev_b32_e32 v128, 6, v114
	v_and_or_b32 v128, v128, s63, v158
	v_lshlrev_b32_e32 v128, 1, v128
	s_waitcnt vmcnt(1)
	v_pk_fma_f32 v[118:119], v[112:113], 0.5, v[118:119] op_sel_hi:[1,0,1]
	v_pk_fma_f32 v[116:117], v[110:111], 0.5, v[116:117] op_sel_hi:[1,0,1]
	s_waitcnt vmcnt(0)
	v_pk_fma_f32 v[126:127], v[108:109], 0.5, v[126:127] op_sel_hi:[1,0,1]
	v_pk_fma_f32 v[124:125], v[106:107], 0.5, v[124:125] op_sel_hi:[1,0,1]
	v_cvt_pk_bf16_f32 v106, v116, v117
	v_cvt_pk_bf16_f32 v107, v118, v119
	v_cvt_pk_bf16_f32 v108, v124, v125
	v_cvt_pk_bf16_f32 v109, v126, v127
	global_store_dwordx4 v128, v[106:109], s[44:45] sc1
	global_load_dwordx4 v[106:109], v[120:121], off offset:512
	s_nop 0
	global_load_dwordx4 v[110:113], v[120:121], off offset:528
	v_mul_f32_e32 v117, v117, v117
	v_mul_f32_e32 v119, v119, v119
	v_mul_f32_e32 v120, v125, v125
	v_fmac_f32_e32 v117, v116, v116
	v_fmac_f32_e32 v119, v118, v118
	v_mul_f32_e32 v121, v127, v127
	v_fmac_f32_e32 v120, v124, v124
	v_add_f32_e32 v116, v117, v119
	v_fmac_f32_e32 v121, v126, v126
	v_add_f32_e32 v116, v120, v116
	v_add_f32_e32 v116, v121, v116
	s_waitcnt vmcnt(1)
	v_pk_fma_f32 v[104:105], v[104:105], 0.5, v[108:109] op_sel_hi:[1,0,1]
	v_pk_fma_f32 v[102:103], v[102:103], 0.5, v[106:107] op_sel_hi:[1,0,1]
	s_waitcnt vmcnt(0)
	v_pk_fma_f32 v[108:109], v[98:99], 0.5, v[110:111] op_sel_hi:[1,0,1]
	v_mul_f32_e32 v98, v103, v103
	v_mul_f32_e32 v99, v105, v105
	v_pk_fma_f32 v[106:107], v[100:101], 0.5, v[112:113] op_sel_hi:[1,0,1]
	v_mul_f32_e32 v100, v109, v109
	v_fmac_f32_e32 v98, v102, v102
	v_fmac_f32_e32 v99, v104, v104
	v_mul_f32_e32 v101, v107, v107
	v_fmac_f32_e32 v100, v108, v108
	v_add_f32_e32 v98, v98, v99
	v_add_f32_e32 v98, v100, v98
	v_fmac_f32_e32 v101, v106, v106
	v_add_f32_e32 v98, v101, v98
	v_add_f32_e32 v98, v116, v98
	ds_bpermute_b32 v99, v123, v98
	v_cvt_pk_bf16_f32 v100, v102, v103
	v_cvt_pk_bf16_f32 v101, v104, v105
	v_cvt_pk_bf16_f32 v102, v108, v109
	v_cvt_pk_bf16_f32 v103, v106, v107
	s_waitcnt lgkmcnt(0)
	v_add_f32_e32 v98, v98, v99
	ds_bpermute_b32 v99, v122, v98
	global_store_dwordx4 v128, v[100:103], s[46:47] sc1
	s_and_saveexec_b64 s[48:49], s[0:1]
	s_cbranch_execz .LBB0_207
	v_lshl_add_u64 v[100:101], v[114:115], 2, s[10:11]
	s_waitcnt lgkmcnt(0)
	v_add_f32_e32 v98, v98, v99
	global_atomic_add_f32 v[100:101], v98, off
; __host__ __device__ __forceinline__ size_t blk(int r, int k, int K) { return (((size_t)((r >> 8) * (K >> 6) + (k >> 6))) << 14) + (size_t)(((r & 255) << 6) + (k & 63)); }
; __device__ __forceinline__ float bflo(unsigned w) { return __uint_as_float(w << 16); }
; __device__ __forceinline__ float bfhi(unsigned w) { return __uint_as_float(w & 0xffff0000u); }
; __device__ __forceinline__ unsigned pk2(float lo, float hi) { f32x2 v = {lo, hi}; bf16x2_t b = __builtin_convertvector(v, bf16x2_t); return __builtin_bit_cast(unsigned, b); }
;     __device__ __forceinline__ void operator()(const f32x4 (&acc)[2][2][4][2], const Unit& u, int wr, int wc, int fr, int fq) const {
;     ...
;             for (int m = 0; m < 4; ++m) { const int row = row0 + ai * HALF + m * 16; const size_t off = (size_t)row * D + col0; float s = 0.f;
; #pragma unroll
;                 for (int bj = 0; bj < 2; ++bj) {
;                     f32x4 v0, v1;
;                     if (MODE == 0) { v0 = *(const f32x4*)(base + off + bj * HALF); v1 = *(const f32x4*)(base + off + bj * HALF + 4); }
;                     else { const u32x4 r = *(const u32x4*)(bb + blk(row, col0 + bj * HALF, D)); v0 = (f32x4){bflo(r.x), bfhi(r.x), bflo(r.y), bfhi(r.y)}; v1 = (f32x4){bflo(r.z), bfhi(r.z), bflo(r.w), bfhi(r.w)}; }
;                     v0 += acc[ai][bj][m][0] * alpha; v1 += acc[ai][bj][m][1] * alpha;
;                     if (MODE == 2) { *(f32x4*)(out + off + bj * HALF) = v0; *(f32x4*)(out + off + bj * HALF + 4) = v1; }
;                     else {
;                         s += (v0[0] * v0[0] + v0[1] * v0[1]) + (v0[2] * v0[2] + v0[3] * v0[3]) + (v1[0] * v1[0] + v1[1] * v1[1]) + (v1[2] * v1[2] + v1[3] * v1[3]);
;                         u32x4 w; w.x = pk2(v0[0], v0[1]); w.y = pk2(v0[2], v0[3]); w.z = pk2(v1[0], v1[1]); w.w = pk2(v1[2], v1[3]); *(u32x4*)(xb + blk(row, col0 + bj * HALF, D)) = w; } }
;                 if (MODE != 2) { s += __shfl_xor(s, 16); s += __shfl_xor(s, 32); if (fq == 0) unsafeAtomicAdd(ssq + row, s); } }
.LBB0_207:
	s_or_b64 exec, exec, s[48:49]
	v_or_b32_e32 v98, 32, v150
	s_waitcnt lgkmcnt(0)
	v_ashrrev_i32_e32 v99, 31, v98
	v_lshlrev_b64 v[100:101], 14, v[98:99]
	v_lshl_add_u64 v[100:101], s[8:9], 0, v[100:101]
	v_lshl_add_u64 v[108:109], v[148:149], 2, v[100:101]
	global_load_dwordx4 v[100:103], v[108:109], off
	global_load_dwordx4 v[104:107], v[108:109], off offset:16
	v_lshlrev_b32_e32 v110, 6, v98
	v_and_or_b32 v110, v110, s64, v158
	v_lshlrev_b32_e32 v110, 1, v110
	s_waitcnt vmcnt(1)
	v_pk_fma_f32 v[102:103], v[96:97], 0.5, v[102:103] op_sel_hi:[1,0,1]
	v_pk_fma_f32 v[100:101], v[94:95], 0.5, v[100:101] op_sel_hi:[1,0,1]
	s_waitcnt vmcnt(0)
	v_pk_fma_f32 v[106:107], v[92:93], 0.5, v[106:107] op_sel_hi:[1,0,1]
	v_pk_fma_f32 v[104:105], v[90:91], 0.5, v[104:105] op_sel_hi:[1,0,1]
	v_cvt_pk_bf16_f32 v90, v100, v101
	v_cvt_pk_bf16_f32 v91, v102, v103
	v_cvt_pk_bf16_f32 v92, v104, v105
	v_cvt_pk_bf16_f32 v93, v106, v107
	global_store_dwordx4 v110, v[90:93], s[44:45] sc1
	global_load_dwordx4 v[90:93], v[108:109], off offset:512
	s_nop 0
	global_load_dwordx4 v[94:97], v[108:109], off offset:528
	v_mul_f32_e32 v101, v101, v101
	v_mul_f32_e32 v103, v103, v103
	v_mul_f32_e32 v105, v105, v105
	v_fmac_f32_e32 v101, v100, v100
	v_fmac_f32_e32 v103, v102, v102
	v_mul_f32_e32 v107, v107, v107
	v_fmac_f32_e32 v105, v104, v104
	v_add_f32_e32 v100, v101, v103
	v_fmac_f32_e32 v107, v106, v106
	v_add_f32_e32 v100, v105, v100
	v_add_f32_e32 v100, v107, v100
	s_waitcnt vmcnt(1)
	v_pk_fma_f32 v[88:89], v[88:89], 0.5, v[92:93] op_sel_hi:[1,0,1]
	v_pk_fma_f32 v[86:87], v[86:87], 0.5, v[90:91] op_sel_hi:[1,0,1]
	s_waitcnt vmcnt(0)
	v_pk_fma_f32 v[92:93], v[82:83], 0.5, v[94:95] op_sel_hi:[1,0,1]
	v_mul_f32_e32 v82, v87, v87
	v_mul_f32_e32 v83, v89, v89
	v_pk_fma_f32 v[90:91], v[84:85], 0.5, v[96:97] op_sel_hi:[1,0,1]
	v_mul_f32_e32 v84, v93, v93
	v_fmac_f32_e32 v82, v86, v86
	v_fmac_f32_e32 v83, v88, v88
	v_mul_f32_e32 v85, v91, v91
	v_fmac_f32_e32 v84, v92, v92
	v_add_f32_e32 v82, v82, v83
	v_add_f32_e32 v82, v84, v82
	v_fmac_f32_e32 v85, v90, v90
	v_add_f32_e32 v82, v85, v82
	v_add_f32_e32 v82, v100, v82
	ds_bpermute_b32 v83, v123, v82
	v_cvt_pk_bf16_f32 v84, v86, v87
	v_cvt_pk_bf16_f32 v85, v88, v89
	v_cvt_pk_bf16_f32 v86, v92, v93
	v_cvt_pk_bf16_f32 v87, v90, v91
	s_waitcnt lgkmcnt(0)
	v_add_f32_e32 v82, v82, v83
	ds_bpermute_b32 v83, v122, v82
	global_store_dwordx4 v110, v[84:87], s[46:47] sc1
	s_and_saveexec_b64 s[48:49], s[0:1]
	s_cbranch_execz .LBB0_209
	v_lshl_add_u64 v[84:85], v[98:99], 2, s[10:11]
	s_waitcnt lgkmcnt(0)
	v_add_f32_e32 v82, v82, v83
	global_atomic_add_f32 v[84:85], v82, off
.LBB0_209:
	s_or_b64 exec, exec, s[48:49]
	v_or_b32_e32 v82, 48, v150
	s_waitcnt lgkmcnt(0)
	v_ashrrev_i32_e32 v83, 31, v82
	v_lshlrev_b64 v[84:85], 14, v[82:83]
	v_lshl_add_u64 v[84:85], s[8:9], 0, v[84:85]
	v_lshl_add_u64 v[92:93], v[148:149], 2, v[84:85]
	global_load_dwordx4 v[84:87], v[92:93], off
	global_load_dwordx4 v[88:91], v[92:93], off offset:16
	v_lshlrev_b32_e32 v94, 6, v82
	v_and_or_b32 v94, v94, s65, v158
	v_lshlrev_b32_e32 v94, 1, v94
	s_waitcnt vmcnt(1)
	v_pk_fma_f32 v[86:87], v[80:81], 0.5, v[86:87] op_sel_hi:[1,0,1]
	v_pk_fma_f32 v[84:85], v[78:79], 0.5, v[84:85] op_sel_hi:[1,0,1]
	s_waitcnt vmcnt(0)
	v_pk_fma_f32 v[90:91], v[76:77], 0.5, v[90:91] op_sel_hi:[1,0,1]
	v_pk_fma_f32 v[88:89], v[74:75], 0.5, v[88:89] op_sel_hi:[1,0,1]
	v_cvt_pk_bf16_f32 v74, v84, v85
	v_cvt_pk_bf16_f32 v75, v86, v87
	v_cvt_pk_bf16_f32 v76, v88, v89
	v_cvt_pk_bf16_f32 v77, v90, v91
	global_store_dwordx4 v94, v[74:77], s[44:45] sc1
	global_load_dwordx4 v[74:77], v[92:93], off offset:512
	s_nop 0
	global_load_dwordx4 v[78:81], v[92:93], off offset:528
	v_mul_f32_e32 v85, v85, v85
	v_mul_f32_e32 v87, v87, v87
	v_mul_f32_e32 v89, v89, v89
	v_fmac_f32_e32 v85, v84, v84
	v_fmac_f32_e32 v87, v86, v86
	v_mul_f32_e32 v91, v91, v91
	v_fmac_f32_e32 v89, v88, v88
	v_add_f32_e32 v84, v85, v87
	v_fmac_f32_e32 v91, v90, v90
	v_add_f32_e32 v84, v89, v84
	v_add_f32_e32 v84, v91, v84
	s_waitcnt vmcnt(1)
	v_pk_fma_f32 v[72:73], v[72:73], 0.5, v[76:77] op_sel_hi:[1,0,1]
	v_pk_fma_f32 v[70:71], v[70:71], 0.5, v[74:75] op_sel_hi:[1,0,1]
	s_waitcnt vmcnt(0)
	v_pk_fma_f32 v[76:77], v[66:67], 0.5, v[78:79] op_sel_hi:[1,0,1]
	v_mul_f32_e32 v66, v71, v71
	v_mul_f32_e32 v67, v73, v73
	v_pk_fma_f32 v[74:75], v[68:69], 0.5, v[80:81] op_sel_hi:[1,0,1]
	v_mul_f32_e32 v68, v77, v77
	v_fmac_f32_e32 v66, v70, v70
	v_fmac_f32_e32 v67, v72, v72
	v_mul_f32_e32 v69, v75, v75
	v_fmac_f32_e32 v68, v76, v76
	v_add_f32_e32 v66, v66, v67
	v_add_f32_e32 v66, v68, v66
	v_fmac_f32_e32 v69, v74, v74
	v_add_f32_e32 v66, v69, v66
	v_add_f32_e32 v66, v84, v66
	ds_bpermute_b32 v67, v123, v66
	v_cvt_pk_bf16_f32 v68, v70, v71
	v_cvt_pk_bf16_f32 v69, v72, v73
	v_cvt_pk_bf16_f32 v70, v76, v77
	v_cvt_pk_bf16_f32 v71, v74, v75
	s_waitcnt lgkmcnt(0)
	v_add_f32_e32 v66, v66, v67
	ds_bpermute_b32 v67, v122, v66
	global_store_dwordx4 v94, v[68:71], s[46:47] sc1
	s_and_saveexec_b64 s[44:45], s[0:1]
	s_cbranch_execz .LBB0_211
	v_lshl_add_u64 v[68:69], v[82:83], 2, s[10:11]
	s_waitcnt lgkmcnt(0)
	v_add_f32_e32 v66, v66, v67
	global_atomic_add_f32 v[68:69], v66, off
; __host__ __device__ __forceinline__ size_t blk(int r, int k, int K) { return (((size_t)((r >> 8) * (K >> 6) + (k >> 6))) << 14) + (size_t)(((r & 255) << 6) + (k & 63)); }
; __device__ __forceinline__ float bflo(unsigned w) { return __uint_as_float(w << 16); }
; __device__ __forceinline__ float bfhi(unsigned w) { return __uint_as_float(w & 0xffff0000u); }
; __device__ __forceinline__ unsigned pk2(float lo, float hi) { f32x2 v = {lo, hi}; bf16x2_t b = __builtin_convertvector(v, bf16x2_t); return __builtin_bit_cast(unsigned, b); }
;     __device__ __forceinline__ void operator()(const f32x4 (&acc)[2][2][4][2], const Unit& u, int wr, int wc, int fr, int fq) const {
;     ...
;             for (int m = 0; m < 4; ++m) { const int row = row0 + ai * HALF + m * 16; const size_t off = (size_t)row * D + col0; float s = 0.f;
; #pragma unroll
;                 for (int bj = 0; bj < 2; ++bj) {
;                     f32x4 v0, v1;
;                     if (MODE == 0) { v0 = *(const f32x4*)(base + off + bj * HALF); v1 = *(const f32x4*)(base + off + bj * HALF + 4); }
;                     else { const u32x4 r = *(const u32x4*)(bb + blk(row, col0 + bj * HALF, D)); v0 = (f32x4){bflo(r.x), bfhi(r.x), bflo(r.y), bfhi(r.y)}; v1 = (f32x4){bflo(r.z), bfhi(r.z), bflo(r.w), bfhi(r.w)}; }
;                     v0 += acc[ai][bj][m][0] * alpha; v1 += acc[ai][bj][m][1] * alpha;
;                     if (MODE == 2) { *(f32x4*)(out + off + bj * HALF) = v0; *(f32x4*)(out + off + bj * HALF + 4) = v1; }
;                     else {
;                         s += (v0[0] * v0[0] + v0[1] * v0[1]) + (v0[2] * v0[2] + v0[3] * v0[3]) + (v1[0] * v1[0] + v1[1] * v1[1]) + (v1[2] * v1[2] + v1[3] * v1[3]);
;                         u32x4 w; w.x = pk2(v0[0], v0[1]); w.y = pk2(v0[2], v0[3]); w.z = pk2(v1[0], v1[1]); w.w = pk2(v1[2], v1[3]); *(u32x4*)(xb + blk(row, col0 + bj * HALF, D)) = w; } }
;                 if (MODE != 2) { s += __shfl_xor(s, 16); s += __shfl_xor(s, 32); if (fq == 0) unsafeAtomicAdd(ssq + row, s); } }
.LBB0_211:
	s_or_b64 exec, exec, s[44:45]
	v_add_u32_e32 v68, 0x80, v150
	v_ashrrev_i32_e32 v69, 31, v68
	s_waitcnt lgkmcnt(0)
	v_lshlrev_b64 v[66:67], 14, v[68:69]
	v_lshl_add_u64 v[66:67], s[8:9], 0, v[66:67]
	v_lshl_add_u64 v[78:79], v[148:149], 2, v[66:67]
	global_load_dwordx4 v[70:73], v[78:79], off
	global_load_dwordx4 v[74:77], v[78:79], off offset:16
	v_ashrrev_i32_e32 v66, 2, v68
	v_lshlrev_b32_e32 v67, 6, v68
	v_and_b32_e32 v82, 0xffffffc0, v66
	v_and_or_b32 v67, v67, s62, v158
	v_add_u32_e32 v66, s50, v82
	v_lshlrev_b32_e32 v138, 1, v67
	v_ashrrev_i32_e32 v67, 31, v66
	v_lshlrev_b64 v[66:67], 15, v[66:67]
	v_lshl_add_u64 v[66:67], s[42:43], 0, v[66:67]
	v_lshl_add_u64 v[80:81], v[66:67], 0, v[138:139]
	s_waitcnt vmcnt(1)
	v_pk_fma_f32 v[72:73], v[64:65], 0.5, v[72:73] op_sel_hi:[1,0,1]
	v_pk_fma_f32 v[70:71], v[62:63], 0.5, v[70:71] op_sel_hi:[1,0,1]
	s_waitcnt vmcnt(0)
	v_pk_fma_f32 v[76:77], v[60:61], 0.5, v[76:77] op_sel_hi:[1,0,1]
	v_pk_fma_f32 v[74:75], v[58:59], 0.5, v[74:75] op_sel_hi:[1,0,1]
	v_cvt_pk_bf16_f32 v58, v70, v71
	v_cvt_pk_bf16_f32 v59, v72, v73
	v_cvt_pk_bf16_f32 v60, v74, v75
	v_cvt_pk_bf16_f32 v61, v76, v77
	global_store_dwordx4 v[80:81], v[58:61], off sc1
	global_load_dwordx4 v[58:61], v[78:79], off offset:512
	s_nop 0
	global_load_dwordx4 v[62:65], v[78:79], off offset:528
	v_mul_f32_e32 v71, v71, v71
	v_mul_f32_e32 v73, v73, v73
	v_mul_f32_e32 v75, v75, v75
	v_fmac_f32_e32 v71, v70, v70
	v_fmac_f32_e32 v73, v72, v72
	v_mul_f32_e32 v77, v77, v77
	v_fmac_f32_e32 v75, v74, v74
	v_add_f32_e32 v70, v71, v73
	v_fmac_f32_e32 v77, v76, v76
	v_add_f32_e32 v70, v75, v70
	v_add_f32_e32 v70, v77, v70
	s_waitcnt vmcnt(1)
	v_pk_fma_f32 v[56:57], v[56:57], 0.5, v[60:61] op_sel_hi:[1,0,1]
	v_pk_fma_f32 v[58:59], v[54:55], 0.5, v[58:59] op_sel_hi:[1,0,1]
	s_waitcnt vmcnt(0)
	v_pk_fma_f32 v[50:51], v[50:51], 0.5, v[62:63] op_sel_hi:[1,0,1]
	v_mul_f32_e32 v55, v59, v59
	v_mul_f32_e32 v60, v57, v57
	v_pk_fma_f32 v[52:53], v[52:53], 0.5, v[64:65] op_sel_hi:[1,0,1]
	v_mul_f32_e32 v61, v51, v51
	v_fmac_f32_e32 v55, v58, v58
	v_fmac_f32_e32 v60, v56, v56
	v_mul_f32_e32 v62, v53, v53
	v_fmac_f32_e32 v61, v50, v50
	v_add_f32_e32 v55, v55, v60
	v_fmac_f32_e32 v62, v52, v52
	v_add_f32_e32 v55, v61, v55
	v_add_f32_e32 v55, v62, v55
	v_cvt_pk_bf16_f32 v54, v58, v59
	v_add_f32_e32 v58, v70, v55
	ds_bpermute_b32 v59, v123, v58
	v_cvt_pk_bf16_f32 v55, v56, v57
	v_cvt_pk_bf16_f32 v57, v52, v53
	v_cvt_pk_bf16_f32 v56, v50, v51
	v_add_u32_e32 v50, s51, v82
	s_waitcnt lgkmcnt(0)
	v_add_f32_e32 v52, v58, v59
	ds_bpermute_b32 v53, v122, v52
	v_ashrrev_i32_e32 v51, 31, v50
	v_lshlrev_b64 v[50:51], 15, v[50:51]
	v_lshl_add_u64 v[50:51], s[42:43], 0, v[50:51]
	v_lshl_add_u64 v[58:59], v[50:51], 0, v[138:139]
	global_store_dwordx4 v[58:59], v[54:57], off sc1
	s_and_saveexec_b64 s[44:45], s[0:1]
	s_cbranch_execz .LBB0_213
	v_lshl_add_u64 v[54:55], v[68:69], 2, s[10:11]
	s_waitcnt lgkmcnt(0)
	v_add_f32_e32 v52, v52, v53
	global_atomic_add_f32 v[54:55], v52, off
.LBB0_213:
	s_or_b64 exec, exec, s[44:45]
	v_add_u32_e32 v52, 0x90, v150
	s_waitcnt lgkmcnt(0)
	v_ashrrev_i32_e32 v53, 31, v52
	v_lshlrev_b64 v[54:55], 14, v[52:53]
	v_lshl_add_u64 v[54:55], s[8:9], 0, v[54:55]
	v_lshl_add_u64 v[62:63], v[148:149], 2, v[54:55]
	global_load_dwordx4 v[54:57], v[62:63], off
	global_load_dwordx4 v[58:61], v[62:63], off offset:16
	v_lshlrev_b32_e32 v64, 6, v52
	v_and_or_b32 v64, v64, s63, v158
	v_lshlrev_b32_e32 v138, 1, v64
	v_lshl_add_u64 v[64:65], v[66:67], 0, v[138:139]
	s_waitcnt vmcnt(1)
	v_pk_fma_f32 v[56:57], v[48:49], 0.5, v[56:57] op_sel_hi:[1,0,1]
	v_pk_fma_f32 v[54:55], v[46:47], 0.5, v[54:55] op_sel_hi:[1,0,1]
	s_waitcnt vmcnt(0)
	v_pk_fma_f32 v[60:61], v[44:45], 0.5, v[60:61] op_sel_hi:[1,0,1]
	v_pk_fma_f32 v[58:59], v[42:43], 0.5, v[58:59] op_sel_hi:[1,0,1]
	v_cvt_pk_bf16_f32 v42, v54, v55
	v_cvt_pk_bf16_f32 v43, v56, v57
	v_cvt_pk_bf16_f32 v44, v58, v59
	v_cvt_pk_bf16_f32 v45, v60, v61
	global_store_dwordx4 v[64:65], v[42:45], off sc1
	global_load_dwordx4 v[42:45], v[62:63], off offset:512
	s_nop 0
	global_load_dwordx4 v[46:49], v[62:63], off offset:528
	v_mul_f32_e32 v55, v55, v55
	v_mul_f32_e32 v57, v57, v57
	v_mul_f32_e32 v59, v59, v59
	v_fmac_f32_e32 v55, v54, v54
	v_fmac_f32_e32 v57, v56, v56
	v_mul_f32_e32 v61, v61, v61
	v_fmac_f32_e32 v59, v58, v58
	v_add_f32_e32 v54, v55, v57
	v_fmac_f32_e32 v61, v60, v60
	v_add_f32_e32 v54, v59, v54
	v_add_f32_e32 v54, v61, v54
	s_waitcnt vmcnt(1)
	v_pk_fma_f32 v[40:41], v[40:41], 0.5, v[44:45] op_sel_hi:[1,0,1]
	v_pk_fma_f32 v[38:39], v[38:39], 0.5, v[42:43] op_sel_hi:[1,0,1]
	s_waitcnt vmcnt(0)
	v_pk_fma_f32 v[44:45], v[34:35], 0.5, v[46:47] op_sel_hi:[1,0,1]
	v_mul_f32_e32 v34, v39, v39
	v_mul_f32_e32 v35, v41, v41
	v_pk_fma_f32 v[42:43], v[36:37], 0.5, v[48:49] op_sel_hi:[1,0,1]
	v_mul_f32_e32 v36, v45, v45
	v_fmac_f32_e32 v34, v38, v38
	v_fmac_f32_e32 v35, v40, v40
	v_mul_f32_e32 v37, v43, v43
	v_fmac_f32_e32 v36, v44, v44
	v_add_f32_e32 v34, v34, v35
	v_add_f32_e32 v34, v36, v34
	v_fmac_f32_e32 v37, v42, v42
	v_add_f32_e32 v34, v37, v34
	v_add_f32_e32 v34, v54, v34
	ds_bpermute_b32 v35, v123, v34
	v_cvt_pk_bf16_f32 v36, v38, v39
	v_cvt_pk_bf16_f32 v37, v40, v41
	v_cvt_pk_bf16_f32 v38, v44, v45
	v_cvt_pk_bf16_f32 v39, v42, v43
	s_waitcnt lgkmcnt(0)
	v_add_f32_e32 v34, v34, v35
	ds_bpermute_b32 v35, v122, v34
	v_lshl_add_u64 v[40:41], v[50:51], 0, v[138:139]
	global_store_dwordx4 v[40:41], v[36:39], off sc1
	s_and_saveexec_b64 s[44:45], s[0:1]
	s_cbranch_execz .LBB0_215
	v_lshl_add_u64 v[36:37], v[52:53], 2, s[10:11]
	s_waitcnt lgkmcnt(0)
	v_add_f32_e32 v34, v34, v35
	global_atomic_add_f32 v[36:37], v34, off
; __host__ __device__ __forceinline__ size_t blk(int r, int k, int K) { return (((size_t)((r >> 8) * (K >> 6) + (k >> 6))) << 14) + (size_t)(((r & 255) << 6) + (k & 63)); }
; __device__ __forceinline__ float bflo(unsigned w) { return __uint_as_float(w << 16); }
; __device__ __forceinline__ float bfhi(unsigned w) { return __uint_as_float(w & 0xffff0000u); }
; __device__ __forceinline__ unsigned pk2(float lo, float hi) { f32x2 v = {lo, hi}; bf16x2_t b = __builtin_convertvector(v, bf16x2_t); return __builtin_bit_cast(unsigned, b); }
;     __device__ __forceinline__ void operator()(const f32x4 (&acc)[2][2][4][2], const Unit& u, int wr, int wc, int fr, int fq) const {
;     ...
;             for (int m = 0; m < 4; ++m) { const int row = row0 + ai * HALF + m * 16; const size_t off = (size_t)row * D + col0; float s = 0.f;
; #pragma unroll
;                 for (int bj = 0; bj < 2; ++bj) {
;                     f32x4 v0, v1;
;                     if (MODE == 0) { v0 = *(const f32x4*)(base + off + bj * HALF); v1 = *(const f32x4*)(base + off + bj * HALF + 4); }
;                     else { const u32x4 r = *(const u32x4*)(bb + blk(row, col0 + bj * HALF, D)); v0 = (f32x4){bflo(r.x), bfhi(r.x), bflo(r.y), bfhi(r.y)}; v1 = (f32x4){bflo(r.z), bfhi(r.z), bflo(r.w), bfhi(r.w)}; }
;                     v0 += acc[ai][bj][m][0] * alpha; v1 += acc[ai][bj][m][1] * alpha;
;                     if (MODE == 2) { *(f32x4*)(out + off + bj * HALF) = v0; *(f32x4*)(out + off + bj * HALF + 4) = v1; }
;                     else {
;                         s += (v0[0] * v0[0] + v0[1] * v0[1]) + (v0[2] * v0[2] + v0[3] * v0[3]) + (v1[0] * v1[0] + v1[1] * v1[1]) + (v1[2] * v1[2] + v1[3] * v1[3]);
;                         u32x4 w; w.x = pk2(v0[0], v0[1]); w.y = pk2(v0[2], v0[3]); w.z = pk2(v1[0], v1[1]); w.w = pk2(v1[2], v1[3]); *(u32x4*)(xb + blk(row, col0 + bj * HALF, D)) = w; } }
;                 if (MODE != 2) { s += __shfl_xor(s, 16); s += __shfl_xor(s, 32); if (fq == 0) unsafeAtomicAdd(ssq + row, s); } }
.LBB0_215:
	s_or_b64 exec, exec, s[44:45]
	v_add_u32_e32 v34, 0xa0, v150
	s_waitcnt lgkmcnt(0)
	v_ashrrev_i32_e32 v35, 31, v34
	v_lshlrev_b64 v[36:37], 14, v[34:35]
	v_lshl_add_u64 v[36:37], s[8:9], 0, v[36:37]
	v_lshl_add_u64 v[44:45], v[148:149], 2, v[36:37]
	global_load_dwordx4 v[36:39], v[44:45], off
	global_load_dwordx4 v[40:43], v[44:45], off offset:16
	v_lshlrev_b32_e32 v46, 6, v34
	v_and_or_b32 v46, v46, s64, v158
	v_lshlrev_b32_e32 v138, 1, v46
	v_lshl_add_u64 v[46:47], v[66:67], 0, v[138:139]
	s_waitcnt vmcnt(1)
	v_pk_fma_f32 v[38:39], v[32:33], 0.5, v[38:39] op_sel_hi:[1,0,1]
	v_pk_fma_f32 v[36:37], v[30:31], 0.5, v[36:37] op_sel_hi:[1,0,1]
	s_waitcnt vmcnt(0)
	v_pk_fma_f32 v[42:43], v[28:29], 0.5, v[42:43] op_sel_hi:[1,0,1]
	v_pk_fma_f32 v[40:41], v[26:27], 0.5, v[40:41] op_sel_hi:[1,0,1]
	v_cvt_pk_bf16_f32 v26, v36, v37
	v_cvt_pk_bf16_f32 v27, v38, v39
	v_cvt_pk_bf16_f32 v28, v40, v41
	v_cvt_pk_bf16_f32 v29, v42, v43
	global_store_dwordx4 v[46:47], v[26:29], off sc1
	global_load_dwordx4 v[26:29], v[44:45], off offset:512
	s_nop 0
	global_load_dwordx4 v[30:33], v[44:45], off offset:528
	v_mul_f32_e32 v37, v37, v37
	v_mul_f32_e32 v39, v39, v39
	v_mul_f32_e32 v41, v41, v41
	v_fmac_f32_e32 v37, v36, v36
	v_fmac_f32_e32 v39, v38, v38
	v_mul_f32_e32 v43, v43, v43
	v_fmac_f32_e32 v41, v40, v40
	v_add_f32_e32 v36, v37, v39
	v_fmac_f32_e32 v43, v42, v42
	v_add_f32_e32 v36, v41, v36
	v_add_f32_e32 v36, v43, v36
	s_waitcnt vmcnt(1)
	v_pk_fma_f32 v[24:25], v[24:25], 0.5, v[28:29] op_sel_hi:[1,0,1]
	v_pk_fma_f32 v[22:23], v[22:23], 0.5, v[26:27] op_sel_hi:[1,0,1]
	s_waitcnt vmcnt(0)
	v_pk_fma_f32 v[28:29], v[18:19], 0.5, v[30:31] op_sel_hi:[1,0,1]
	v_mul_f32_e32 v18, v23, v23
	v_mul_f32_e32 v19, v25, v25
	v_pk_fma_f32 v[26:27], v[20:21], 0.5, v[32:33] op_sel_hi:[1,0,1]
	v_mul_f32_e32 v20, v29, v29
	v_fmac_f32_e32 v18, v22, v22
	v_fmac_f32_e32 v19, v24, v24
	v_mul_f32_e32 v21, v27, v27
	v_fmac_f32_e32 v20, v28, v28
	v_add_f32_e32 v18, v18, v19
	v_add_f32_e32 v18, v20, v18
	v_fmac_f32_e32 v21, v26, v26
	v_add_f32_e32 v18, v21, v18
	v_add_f32_e32 v18, v36, v18
	ds_bpermute_b32 v19, v123, v18
	v_cvt_pk_bf16_f32 v20, v22, v23
	v_cvt_pk_bf16_f32 v21, v24, v25
	v_cvt_pk_bf16_f32 v22, v28, v29
	v_cvt_pk_bf16_f32 v23, v26, v27
	s_waitcnt lgkmcnt(0)
	v_add_f32_e32 v18, v18, v19
	ds_bpermute_b32 v19, v122, v18
	v_lshl_add_u64 v[24:25], v[50:51], 0, v[138:139]
	global_store_dwordx4 v[24:25], v[20:23], off sc1
	s_and_saveexec_b64 s[44:45], s[0:1]
	s_cbranch_execz .LBB0_217
	v_lshl_add_u64 v[20:21], v[34:35], 2, s[10:11]
	s_waitcnt lgkmcnt(0)
	v_add_f32_e32 v18, v18, v19
	global_atomic_add_f32 v[20:21], v18, off
.LBB0_217:
	s_or_b64 exec, exec, s[44:45]
	v_add_u32_e32 v18, 0xb0, v150
	s_waitcnt lgkmcnt(0)
	v_ashrrev_i32_e32 v19, 31, v18
	v_lshlrev_b64 v[20:21], 14, v[18:19]
	v_lshl_add_u64 v[20:21], s[8:9], 0, v[20:21]
	v_lshl_add_u64 v[28:29], v[148:149], 2, v[20:21]
	global_load_dwordx4 v[20:23], v[28:29], off
	global_load_dwordx4 v[24:27], v[28:29], off offset:16
	v_lshlrev_b32_e32 v30, 6, v18
	v_and_or_b32 v30, v30, s65, v158
	v_lshlrev_b32_e32 v138, 1, v30
	v_lshl_add_u64 v[30:31], v[66:67], 0, v[138:139]
	s_waitcnt vmcnt(1)
	v_pk_fma_f32 v[22:23], v[16:17], 0.5, v[22:23] op_sel_hi:[1,0,1]
	v_pk_fma_f32 v[20:21], v[14:15], 0.5, v[20:21] op_sel_hi:[1,0,1]
	s_waitcnt vmcnt(0)
	v_pk_fma_f32 v[26:27], v[12:13], 0.5, v[26:27] op_sel_hi:[1,0,1]
	v_pk_fma_f32 v[24:25], v[10:11], 0.5, v[24:25] op_sel_hi:[1,0,1]
	v_cvt_pk_bf16_f32 v10, v20, v21
	v_cvt_pk_bf16_f32 v11, v22, v23
	v_cvt_pk_bf16_f32 v12, v24, v25
	v_cvt_pk_bf16_f32 v13, v26, v27
	global_store_dwordx4 v[30:31], v[10:13], off sc1
	global_load_dwordx4 v[10:13], v[28:29], off offset:512
	s_nop 0
	global_load_dwordx4 v[14:17], v[28:29], off offset:528
	v_mul_f32_e32 v21, v21, v21
	v_mul_f32_e32 v23, v23, v23
	v_mul_f32_e32 v25, v25, v25
	v_fmac_f32_e32 v21, v20, v20
	v_fmac_f32_e32 v23, v22, v22
	v_mul_f32_e32 v27, v27, v27
	v_fmac_f32_e32 v25, v24, v24
	v_add_f32_e32 v20, v21, v23
	v_fmac_f32_e32 v27, v26, v26
	v_add_f32_e32 v20, v25, v20
	v_add_f32_e32 v20, v27, v20
	s_waitcnt vmcnt(1)
	v_pk_fma_f32 v[8:9], v[8:9], 0.5, v[12:13] op_sel_hi:[1,0,1]
	v_pk_fma_f32 v[6:7], v[6:7], 0.5, v[10:11] op_sel_hi:[1,0,1]
	s_waitcnt vmcnt(0)
	v_pk_fma_f32 v[12:13], v[2:3], 0.5, v[14:15] op_sel_hi:[1,0,1]
	v_mul_f32_e32 v2, v7, v7
	v_mul_f32_e32 v3, v9, v9
	v_pk_fma_f32 v[10:11], v[4:5], 0.5, v[16:17] op_sel_hi:[1,0,1]
	v_mul_f32_e32 v4, v13, v13
	v_fmac_f32_e32 v2, v6, v6
	v_fmac_f32_e32 v3, v8, v8
	v_mul_f32_e32 v5, v11, v11
	v_fmac_f32_e32 v4, v12, v12
	v_add_f32_e32 v2, v2, v3
	v_add_f32_e32 v2, v4, v2
	v_fmac_f32_e32 v5, v10, v10
	v_add_f32_e32 v2, v5, v2
	v_add_f32_e32 v2, v20, v2
	ds_bpermute_b32 v3, v123, v2
	v_cvt_pk_bf16_f32 v4, v6, v7
	v_cvt_pk_bf16_f32 v5, v8, v9
	v_cvt_pk_bf16_f32 v6, v12, v13
	v_cvt_pk_bf16_f32 v7, v10, v11
	s_waitcnt lgkmcnt(0)
	v_add_f32_e32 v2, v2, v3
	ds_bpermute_b32 v3, v122, v2
	v_lshl_add_u64 v[8:9], v[50:51], 0, v[138:139]
	global_store_dwordx4 v[8:9], v[4:7], off sc1
	s_and_saveexec_b64 s[44:45], s[0:1]
	s_cbranch_execz .LBB0_219
	v_lshl_add_u64 v[4:5], v[18:19], 2, s[10:11]
	s_waitcnt lgkmcnt(0)
	v_add_f32_e32 v2, v2, v3
	global_atomic_add_f32 v[4:5], v2, off

; __device__ __forceinline__ unsigned pk2(float lo, float hi) { f32x2 v = {lo, hi}; bf16x2_t b = __builtin_convertvector(v, bf16x2_t); return __builtin_bit_cast(unsigned, b); }
; __device__ __forceinline__ float fsigmoid(float x) { return __builtin_amdgcn_rcpf(1.0f + __expf(-x)); }
;     __device__ __forceinline__ void operator()(const f32x4 (&acc)[2][2][4][2], const Unit& u, int wr, int wc, int fr, int fq) const {
;     ...
;             for (int m = 0; m < 4; ++m) { const int row = row0 + ai * HALF + m * 16; bf16_t* rowp = O + (size_t)row * ldc + col0;
;                 const float rs = 1.0f / sqrtf(ssq[row] * (1.0f / D) + RMS_EPS);
; #pragma unroll
;                 for (int bj = 0; bj < 2; ++bj) { f32x4 v0 = acc[ai][bj][m][0] * rs, v1 = acc[ai][bj][m][1] * rs;
;                     if (mode == 1) {
; #pragma unroll
;                         for (int j = 0; j < 4; ++j) { v0[j] = fsigmoid(v0[j]); v1[j] = fsigmoid(v1[j]); } }
;                     else if (mode == 2) { v0 = v0 * 0.08838834764831845f; v1 = v1 * 0.08838834764831845f; }
;                     u32x4 w; w.x = pk2(v0[0], v0[1]); w.y = pk2(v0[2], v0[3]); w.z = pk2(v1[0], v1[1]); w.w = pk2(v1[2], v1[3]);
;                     *(u32x4*)(rowp + bj * HALF) = w; } }
.LBB0_299:
	v_lshl_or_b32 v122, s50, 8, v161
	v_mov_b64_e32 v[124:125], s[24:25]
	v_ashrrev_i32_e32 v123, 31, v122
	v_mad_i64_i32 v[124:125], s[4:5], v146, s61, v[124:125]
	v_lshl_add_u64 v[124:125], v[122:123], 1, v[124:125]
	v_cvt_pk_bf16_f32 v126, v156, v157
	v_cvt_pk_bf16_f32 v127, v152, v153
	v_cvt_pk_bf16_f32 v128, v158, v159
	v_cvt_pk_bf16_f32 v129, v154, v155
	global_store_dwordx4 v[124:125], v[126:129], off sc1
	v_mov_b32_e32 v151, v150
	v_pk_mul_f32 v[118:119], v[118:119], v[150:151]
	v_mov_b32_e32 v126, v150
	v_mov_b32_e32 v127, v150
	v_pk_mul_f32 v[120:121], v[120:121], v[126:127]
	v_pk_mul_f32 v[116:117], v[116:117], v[126:127]
	v_pk_mul_f32 v[114:115], v[114:115], v[150:151]
	s_cmp_gt_i32 s17, 1
	s_mov_b64 s[4:5], -1
	s_cbranch_scc0 .LBB0_301
	v_pk_mul_f32 v[126:127], v[120:121], s[14:15] op_sel_hi:[1,0]
	v_pk_mul_f32 v[150:151], v[118:119], s[14:15] op_sel_hi:[1,0]
	v_pk_mul_f32 v[128:129], v[116:117], s[14:15] op_sel_hi:[1,0]
	v_pk_mul_f32 v[152:153], v[114:115], s[14:15] op_sel_hi:[1,0]
	s_mov_b64 s[4:5], 0

; __device__ __forceinline__ unsigned pk2(float lo, float hi) { f32x2 v = {lo, hi}; bf16x2_t b = __builtin_convertvector(v, bf16x2_t); return __builtin_bit_cast(unsigned, b); }
; __device__ __forceinline__ float fsigmoid(float x) { return __builtin_amdgcn_rcpf(1.0f + __expf(-x)); }
;     __device__ __forceinline__ void operator()(const f32x4 (&acc)[2][2][4][2], const Unit& u, int wr, int wc, int fr, int fq) const {
;     ...
;             for (int m = 0; m < 4; ++m) { const int row = row0 + ai * HALF + m * 16; bf16_t* rowp = O + (size_t)row * ldc + col0;
;                 const float rs = 1.0f / sqrtf(ssq[row] * (1.0f / D) + RMS_EPS);
; #pragma unroll
;                 for (int bj = 0; bj < 2; ++bj) { f32x4 v0 = acc[ai][bj][m][0] * rs, v1 = acc[ai][bj][m][1] * rs;
;                     if (mode == 1) {
; #pragma unroll
;                         for (int j = 0; j < 4; ++j) { v0[j] = fsigmoid(v0[j]); v1[j] = fsigmoid(v1[j]); } }
;                     else if (mode == 2) { v0 = v0 * 0.08838834764831845f; v1 = v1 * 0.08838834764831845f; }
;                     u32x4 w; w.x = pk2(v0[0], v0[1]); w.y = pk2(v0[2], v0[3]); w.z = pk2(v1[0], v1[1]); w.w = pk2(v1[2], v1[3]);
;                     *(u32x4*)(rowp + bj * HALF) = w; } }
.LBB0_305:
	v_cvt_pk_bf16_f32 v114, v150, v151
	v_cvt_pk_bf16_f32 v115, v126, v127
	v_cvt_pk_bf16_f32 v116, v152, v153
	v_cvt_pk_bf16_f32 v117, v128, v129
	global_store_dwordx4 v[124:125], v[114:117], off offset:256 sc1
	s_cmp_gt_i32 s17, 1
	s_nop 0
	v_or_b32_e32 v114, 16, v146
	v_ashrrev_i32_e32 v115, 31, v114
	v_lshl_add_u64 v[116:117], v[114:115], 2, s[10:11]
	s_nop 0
	v_mov_b32_e32 v115, v168
	v_fmamk_f32 v115, v115, 0x39800000, v165
	v_mul_f32_e32 v116, 0x4f800000, v115
	v_cmp_gt_f32_e32 vcc, s83, v115
	s_nop 1
	v_cndmask_b32_e32 v115, v115, v116, vcc
	v_sqrt_f32_e32 v116, v115
	s_nop 0
	v_add_u32_e32 v117, -1, v116
	v_add_u32_e32 v118, 1, v116
	v_fma_f32 v119, -v117, v116, v115
	v_fma_f32 v120, -v118, v116, v115
	v_cmp_ge_f32_e64 s[4:5], 0, v119
	s_nop 1
	v_cndmask_b32_e64 v116, v116, v117, s[4:5]
	v_cmp_lt_f32_e64 s[4:5], 0, v120
	s_nop 1
	v_cndmask_b32_e64 v116, v116, v118, s[4:5]
	v_mul_f32_e32 v117, 0x37800000, v116
	v_cndmask_b32_e32 v116, v116, v117, vcc
	v_cmp_class_f32_e32 vcc, v115, v166
	s_nop 1
	v_cndmask_b32_e32 v115, v116, v115, vcc
	v_div_scale_f32 v116, s[4:5], v115, v115, 1.0
	v_rcp_f32_e32 v117, v116
	v_div_scale_f32 v118, vcc, 1.0, v115, 1.0
	s_mov_b64 s[4:5], -1
	v_fma_f32 v119, -v116, v117, 1.0
	v_fmac_f32_e32 v117, v119, v117
	v_mul_f32_e32 v119, v118, v117
	v_fma_f32 v120, -v116, v119, v118
	v_fmac_f32_e32 v119, v120, v117
	v_fma_f32 v116, -v116, v119, v118
	v_div_fmas_f32 v116, v116, v117, v119
	v_div_fixup_f32 v116, v116, v115, 1.0
	v_pk_mul_f32 v[112:113], v[112:113], v[116:117] op_sel_hi:[1,0]
	v_pk_mul_f32 v[110:111], v[110:111], v[116:117] op_sel_hi:[1,0]
	v_pk_mul_f32 v[108:109], v[108:109], v[116:117] op_sel_hi:[1,0]
	v_pk_mul_f32 v[106:107], v[106:107], v[116:117] op_sel_hi:[1,0]
	s_cbranch_scc0 .LBB0_307
	v_pk_mul_f32 v[118:119], v[112:113], s[14:15] op_sel_hi:[1,0]
	v_pk_mul_f32 v[124:125], v[110:111], s[14:15] op_sel_hi:[1,0]
	v_pk_mul_f32 v[120:121], v[108:109], s[14:15] op_sel_hi:[1,0]
	v_pk_mul_f32 v[126:127], v[106:107], s[14:15] op_sel_hi:[1,0]
	s_mov_b64 s[4:5], 0

; __device__ __forceinline__ unsigned pk2(float lo, float hi) { f32x2 v = {lo, hi}; bf16x2_t b = __builtin_convertvector(v, bf16x2_t); return __builtin_bit_cast(unsigned, b); }
; __device__ __forceinline__ float fsigmoid(float x) { return __builtin_amdgcn_rcpf(1.0f + __expf(-x)); }
;     __device__ __forceinline__ void operator()(const f32x4 (&acc)[2][2][4][2], const Unit& u, int wr, int wc, int fr, int fq) const {
;     ...
;             for (int m = 0; m < 4; ++m) { const int row = row0 + ai * HALF + m * 16; bf16_t* rowp = O + (size_t)row * ldc + col0;
;                 const float rs = 1.0f / sqrtf(ssq[row] * (1.0f / D) + RMS_EPS);
; #pragma unroll
;                 for (int bj = 0; bj < 2; ++bj) { f32x4 v0 = acc[ai][bj][m][0] * rs, v1 = acc[ai][bj][m][1] * rs;
;                     if (mode == 1) {
; #pragma unroll
;                         for (int j = 0; j < 4; ++j) { v0[j] = fsigmoid(v0[j]); v1[j] = fsigmoid(v1[j]); } }
;                     else if (mode == 2) { v0 = v0 * 0.08838834764831845f; v1 = v1 * 0.08838834764831845f; }
;                     u32x4 w; w.x = pk2(v0[0], v0[1]); w.y = pk2(v0[2], v0[3]); w.z = pk2(v1[0], v1[1]); w.w = pk2(v1[2], v1[3]);
;                     *(u32x4*)(rowp + bj * HALF) = w; } }
.LBB0_311:
	v_mov_b64_e32 v[106:107], s[24:25]
	v_mad_i64_i32 v[106:107], s[4:5], v114, s61, v[106:107]
	v_lshl_add_u64 v[106:107], v[122:123], 1, v[106:107]
	v_cvt_pk_bf16_f32 v108, v124, v125
	v_cvt_pk_bf16_f32 v109, v118, v119
	v_cvt_pk_bf16_f32 v110, v126, v127
	v_cvt_pk_bf16_f32 v111, v120, v121
	global_store_dwordx4 v[106:107], v[108:111], off sc1
	v_mov_b32_e32 v117, v116
	v_pk_mul_f32 v[102:103], v[102:103], v[116:117]
	v_mov_b32_e32 v108, v116
	v_mov_b32_e32 v109, v116
	v_pk_mul_f32 v[104:105], v[104:105], v[108:109]
	v_pk_mul_f32 v[100:101], v[100:101], v[108:109]
	v_pk_mul_f32 v[98:99], v[98:99], v[116:117]
	s_cmp_gt_i32 s17, 1
	s_mov_b64 s[4:5], -1
	s_cbranch_scc0 .LBB0_313
	v_pk_mul_f32 v[108:109], v[104:105], s[14:15] op_sel_hi:[1,0]
	v_pk_mul_f32 v[112:113], v[102:103], s[14:15] op_sel_hi:[1,0]
	v_pk_mul_f32 v[110:111], v[100:101], s[14:15] op_sel_hi:[1,0]
	v_pk_mul_f32 v[114:115], v[98:99], s[14:15] op_sel_hi:[1,0]
	s_mov_b64 s[4:5], 0

; __device__ __forceinline__ unsigned pk2(float lo, float hi) { f32x2 v = {lo, hi}; bf16x2_t b = __builtin_convertvector(v, bf16x2_t); return __builtin_bit_cast(unsigned, b); }
; __device__ __forceinline__ float fsigmoid(float x) { return __builtin_amdgcn_rcpf(1.0f + __expf(-x)); }
;     __device__ __forceinline__ void operator()(const f32x4 (&acc)[2][2][4][2], const Unit& u, int wr, int wc, int fr, int fq) const {
;     ...
;             for (int m = 0; m < 4; ++m) { const int row = row0 + ai * HALF + m * 16; bf16_t* rowp = O + (size_t)row * ldc + col0;
;                 const float rs = 1.0f / sqrtf(ssq[row] * (1.0f / D) + RMS_EPS);
; #pragma unroll
;                 for (int bj = 0; bj < 2; ++bj) { f32x4 v0 = acc[ai][bj][m][0] * rs, v1 = acc[ai][bj][m][1] * rs;
;                     if (mode == 1) {
; #pragma unroll
;                         for (int j = 0; j < 4; ++j) { v0[j] = fsigmoid(v0[j]); v1[j] = fsigmoid(v1[j]); } }
;                     else if (mode == 2) { v0 = v0 * 0.08838834764831845f; v1 = v1 * 0.08838834764831845f; }
;                     u32x4 w; w.x = pk2(v0[0], v0[1]); w.y = pk2(v0[2], v0[3]); w.z = pk2(v1[0], v1[1]); w.w = pk2(v1[2], v1[3]);
;                     *(u32x4*)(rowp + bj * HALF) = w; } }
.LBB0_317:
	v_cvt_pk_bf16_f32 v98, v112, v113
	v_cvt_pk_bf16_f32 v99, v108, v109
	v_cvt_pk_bf16_f32 v100, v114, v115
	v_cvt_pk_bf16_f32 v101, v110, v111
	global_store_dwordx4 v[106:107], v[98:101], off offset:256 sc1
	s_cmp_gt_i32 s17, 1
	s_nop 0
	v_or_b32_e32 v98, 32, v146
	v_ashrrev_i32_e32 v99, 31, v98
	v_lshl_add_u64 v[100:101], v[98:99], 2, s[10:11]
	s_nop 0
	v_mov_b32_e32 v99, v169
	v_fmamk_f32 v99, v99, 0x39800000, v165
	v_mul_f32_e32 v100, 0x4f800000, v99
	v_cmp_gt_f32_e32 vcc, s83, v99
	s_nop 1
	v_cndmask_b32_e32 v99, v99, v100, vcc
	v_sqrt_f32_e32 v100, v99
	s_nop 0
	v_add_u32_e32 v101, -1, v100
	v_add_u32_e32 v102, 1, v100
	v_fma_f32 v103, -v101, v100, v99
	v_fma_f32 v104, -v102, v100, v99
	v_cmp_ge_f32_e64 s[4:5], 0, v103
	s_nop 1
	v_cndmask_b32_e64 v100, v100, v101, s[4:5]
	v_cmp_lt_f32_e64 s[4:5], 0, v104
	s_nop 1
	v_cndmask_b32_e64 v100, v100, v102, s[4:5]
	v_mul_f32_e32 v101, 0x37800000, v100
	v_cndmask_b32_e32 v100, v100, v101, vcc
	v_cmp_class_f32_e32 vcc, v99, v166
	s_nop 1
	v_cndmask_b32_e32 v99, v100, v99, vcc
	v_div_scale_f32 v100, s[4:5], v99, v99, 1.0
	v_rcp_f32_e32 v101, v100
	v_div_scale_f32 v102, vcc, 1.0, v99, 1.0
	s_mov_b64 s[4:5], -1
	v_fma_f32 v103, -v100, v101, 1.0
	v_fmac_f32_e32 v101, v103, v101
	v_mul_f32_e32 v103, v102, v101
	v_fma_f32 v104, -v100, v103, v102
	v_fmac_f32_e32 v103, v104, v101
	v_fma_f32 v100, -v100, v103, v102
	v_div_fmas_f32 v100, v100, v101, v103
	v_div_fixup_f32 v100, v100, v99, 1.0
	v_pk_mul_f32 v[96:97], v[96:97], v[100:101] op_sel_hi:[1,0]
	v_pk_mul_f32 v[94:95], v[94:95], v[100:101] op_sel_hi:[1,0]
	v_pk_mul_f32 v[92:93], v[92:93], v[100:101] op_sel_hi:[1,0]
	v_pk_mul_f32 v[90:91], v[90:91], v[100:101] op_sel_hi:[1,0]
	s_cbranch_scc0 .LBB0_319
	v_pk_mul_f32 v[102:103], v[96:97], s[14:15] op_sel_hi:[1,0]
	v_pk_mul_f32 v[106:107], v[94:95], s[14:15] op_sel_hi:[1,0]
	v_pk_mul_f32 v[104:105], v[92:93], s[14:15] op_sel_hi:[1,0]
	v_pk_mul_f32 v[108:109], v[90:91], s[14:15] op_sel_hi:[1,0]
	s_mov_b64 s[4:5], 0

; __device__ __forceinline__ unsigned pk2(float lo, float hi) { f32x2 v = {lo, hi}; bf16x2_t b = __builtin_convertvector(v, bf16x2_t); return __builtin_bit_cast(unsigned, b); }
; __device__ __forceinline__ float fsigmoid(float x) { return __builtin_amdgcn_rcpf(1.0f + __expf(-x)); }
;     __device__ __forceinline__ void operator()(const f32x4 (&acc)[2][2][4][2], const Unit& u, int wr, int wc, int fr, int fq) const {
;     ...
;             for (int m = 0; m < 4; ++m) { const int row = row0 + ai * HALF + m * 16; bf16_t* rowp = O + (size_t)row * ldc + col0;
;                 const float rs = 1.0f / sqrtf(ssq[row] * (1.0f / D) + RMS_EPS);
; #pragma unroll
;                 for (int bj = 0; bj < 2; ++bj) { f32x4 v0 = acc[ai][bj][m][0] * rs, v1 = acc[ai][bj][m][1] * rs;
;                     if (mode == 1) {
; #pragma unroll
;                         for (int j = 0; j < 4; ++j) { v0[j] = fsigmoid(v0[j]); v1[j] = fsigmoid(v1[j]); } }
;                     else if (mode == 2) { v0 = v0 * 0.08838834764831845f; v1 = v1 * 0.08838834764831845f; }
;                     u32x4 w; w.x = pk2(v0[0], v0[1]); w.y = pk2(v0[2], v0[3]); w.z = pk2(v1[0], v1[1]); w.w = pk2(v1[2], v1[3]);
;                     *(u32x4*)(rowp + bj * HALF) = w; } }
.LBB0_323:
	v_mov_b64_e32 v[90:91], s[24:25]
	v_mad_i64_i32 v[90:91], s[4:5], v98, s61, v[90:91]
	v_lshl_add_u64 v[90:91], v[122:123], 1, v[90:91]
	v_cvt_pk_bf16_f32 v92, v106, v107
	v_cvt_pk_bf16_f32 v93, v102, v103
	v_cvt_pk_bf16_f32 v94, v108, v109
	v_cvt_pk_bf16_f32 v95, v104, v105
	global_store_dwordx4 v[90:91], v[92:95], off sc1
	v_mov_b32_e32 v101, v100
	v_pk_mul_f32 v[86:87], v[86:87], v[100:101]
	v_mov_b32_e32 v92, v100
	v_mov_b32_e32 v93, v100
	v_pk_mul_f32 v[88:89], v[88:89], v[92:93]
	v_pk_mul_f32 v[84:85], v[84:85], v[92:93]
	v_pk_mul_f32 v[82:83], v[82:83], v[100:101]
	s_cmp_gt_i32 s17, 1
	s_mov_b64 s[4:5], -1
	s_cbranch_scc0 .LBB0_325
	v_pk_mul_f32 v[92:93], v[88:89], s[14:15] op_sel_hi:[1,0]
	v_pk_mul_f32 v[96:97], v[86:87], s[14:15] op_sel_hi:[1,0]
	v_pk_mul_f32 v[94:95], v[84:85], s[14:15] op_sel_hi:[1,0]
	v_pk_mul_f32 v[98:99], v[82:83], s[14:15] op_sel_hi:[1,0]
	s_mov_b64 s[4:5], 0

; __device__ __forceinline__ unsigned pk2(float lo, float hi) { f32x2 v = {lo, hi}; bf16x2_t b = __builtin_convertvector(v, bf16x2_t); return __builtin_bit_cast(unsigned, b); }
; __device__ __forceinline__ float fsigmoid(float x) { return __builtin_amdgcn_rcpf(1.0f + __expf(-x)); }
;     __device__ __forceinline__ void operator()(const f32x4 (&acc)[2][2][4][2], const Unit& u, int wr, int wc, int fr, int fq) const {
;     ...
;             for (int m = 0; m < 4; ++m) { const int row = row0 + ai * HALF + m * 16; bf16_t* rowp = O + (size_t)row * ldc + col0;
;                 const float rs = 1.0f / sqrtf(ssq[row] * (1.0f / D) + RMS_EPS);
; #pragma unroll
;                 for (int bj = 0; bj < 2; ++bj) { f32x4 v0 = acc[ai][bj][m][0] * rs, v1 = acc[ai][bj][m][1] * rs;
;                     if (mode == 1) {
; #pragma unroll
;                         for (int j = 0; j < 4; ++j) { v0[j] = fsigmoid(v0[j]); v1[j] = fsigmoid(v1[j]); } }
;                     else if (mode == 2) { v0 = v0 * 0.08838834764831845f; v1 = v1 * 0.08838834764831845f; }
;                     u32x4 w; w.x = pk2(v0[0], v0[1]); w.y = pk2(v0[2], v0[3]); w.z = pk2(v1[0], v1[1]); w.w = pk2(v1[2], v1[3]);
;                     *(u32x4*)(rowp + bj * HALF) = w; } }
.LBB0_329:
	v_cvt_pk_bf16_f32 v82, v96, v97
	v_cvt_pk_bf16_f32 v83, v92, v93
	v_cvt_pk_bf16_f32 v84, v98, v99
	v_cvt_pk_bf16_f32 v85, v94, v95
	global_store_dwordx4 v[90:91], v[82:85], off offset:256 sc1
	s_cmp_gt_i32 s17, 1
	s_nop 0
	v_or_b32_e32 v82, 48, v146
	v_ashrrev_i32_e32 v83, 31, v82
	v_lshl_add_u64 v[84:85], v[82:83], 2, s[10:11]
	s_nop 0
	v_mov_b32_e32 v83, v170
	v_fmamk_f32 v83, v83, 0x39800000, v165
	v_mul_f32_e32 v84, 0x4f800000, v83
	v_cmp_gt_f32_e32 vcc, s83, v83
	s_nop 1
	v_cndmask_b32_e32 v83, v83, v84, vcc
	v_sqrt_f32_e32 v84, v83
	s_nop 0
	v_add_u32_e32 v85, -1, v84
	v_add_u32_e32 v86, 1, v84
	v_fma_f32 v87, -v85, v84, v83
	v_fma_f32 v88, -v86, v84, v83
	v_cmp_ge_f32_e64 s[4:5], 0, v87
	s_nop 1
	v_cndmask_b32_e64 v84, v84, v85, s[4:5]
	v_cmp_lt_f32_e64 s[4:5], 0, v88
	s_nop 1
	v_cndmask_b32_e64 v84, v84, v86, s[4:5]
	v_mul_f32_e32 v85, 0x37800000, v84
	v_cndmask_b32_e32 v84, v84, v85, vcc
	v_cmp_class_f32_e32 vcc, v83, v166
	s_nop 1
	v_cndmask_b32_e32 v83, v84, v83, vcc
	v_div_scale_f32 v84, s[4:5], v83, v83, 1.0
	v_rcp_f32_e32 v85, v84
	v_div_scale_f32 v86, vcc, 1.0, v83, 1.0
	s_mov_b64 s[4:5], -1
	v_fma_f32 v87, -v84, v85, 1.0
	v_fmac_f32_e32 v85, v87, v85
	v_mul_f32_e32 v87, v86, v85
	v_fma_f32 v88, -v84, v87, v86
	v_fmac_f32_e32 v87, v88, v85
	v_fma_f32 v84, -v84, v87, v86
	v_div_fmas_f32 v84, v84, v85, v87
	v_div_fixup_f32 v84, v84, v83, 1.0
	v_pk_mul_f32 v[80:81], v[80:81], v[84:85] op_sel_hi:[1,0]
	v_pk_mul_f32 v[78:79], v[78:79], v[84:85] op_sel_hi:[1,0]
	v_pk_mul_f32 v[76:77], v[76:77], v[84:85] op_sel_hi:[1,0]
	v_pk_mul_f32 v[74:75], v[74:75], v[84:85] op_sel_hi:[1,0]
	s_cbranch_scc0 .LBB0_331
	v_pk_mul_f32 v[86:87], v[80:81], s[14:15] op_sel_hi:[1,0]
	v_pk_mul_f32 v[90:91], v[78:79], s[14:15] op_sel_hi:[1,0]
	v_pk_mul_f32 v[88:89], v[76:77], s[14:15] op_sel_hi:[1,0]
	v_pk_mul_f32 v[92:93], v[74:75], s[14:15] op_sel_hi:[1,0]
	s_mov_b64 s[4:5], 0

; __device__ __forceinline__ unsigned pk2(float lo, float hi) { f32x2 v = {lo, hi}; bf16x2_t b = __builtin_convertvector(v, bf16x2_t); return __builtin_bit_cast(unsigned, b); }
; __device__ __forceinline__ float fsigmoid(float x) { return __builtin_amdgcn_rcpf(1.0f + __expf(-x)); }
;     __device__ __forceinline__ void operator()(const f32x4 (&acc)[2][2][4][2], const Unit& u, int wr, int wc, int fr, int fq) const {
;     ...
;             for (int m = 0; m < 4; ++m) { const int row = row0 + ai * HALF + m * 16; bf16_t* rowp = O + (size_t)row * ldc + col0;
;                 const float rs = 1.0f / sqrtf(ssq[row] * (1.0f / D) + RMS_EPS);
; #pragma unroll
;                 for (int bj = 0; bj < 2; ++bj) { f32x4 v0 = acc[ai][bj][m][0] * rs, v1 = acc[ai][bj][m][1] * rs;
;                     if (mode == 1) {
; #pragma unroll
;                         for (int j = 0; j < 4; ++j) { v0[j] = fsigmoid(v0[j]); v1[j] = fsigmoid(v1[j]); } }
;                     else if (mode == 2) { v0 = v0 * 0.08838834764831845f; v1 = v1 * 0.08838834764831845f; }
;                     u32x4 w; w.x = pk2(v0[0], v0[1]); w.y = pk2(v0[2], v0[3]); w.z = pk2(v1[0], v1[1]); w.w = pk2(v1[2], v1[3]);
;                     *(u32x4*)(rowp + bj * HALF) = w; } }
.LBB0_335:
	v_mov_b64_e32 v[74:75], s[24:25]
	v_mad_i64_i32 v[74:75], s[4:5], v82, s61, v[74:75]
	v_lshl_add_u64 v[74:75], v[122:123], 1, v[74:75]
	v_cvt_pk_bf16_f32 v76, v90, v91
	v_cvt_pk_bf16_f32 v77, v86, v87
	v_cvt_pk_bf16_f32 v78, v92, v93
	v_cvt_pk_bf16_f32 v79, v88, v89
	global_store_dwordx4 v[74:75], v[76:79], off sc1
	v_mov_b32_e32 v85, v84
	v_pk_mul_f32 v[70:71], v[70:71], v[84:85]
	v_mov_b32_e32 v76, v84
	v_mov_b32_e32 v77, v84
	v_pk_mul_f32 v[72:73], v[72:73], v[76:77]
	v_pk_mul_f32 v[68:69], v[68:69], v[76:77]
	v_pk_mul_f32 v[66:67], v[66:67], v[84:85]
	s_cmp_gt_i32 s17, 1
	s_mov_b64 s[4:5], -1
	s_cbranch_scc0 .LBB0_337
	v_pk_mul_f32 v[76:77], v[72:73], s[14:15] op_sel_hi:[1,0]
	v_pk_mul_f32 v[80:81], v[70:71], s[14:15] op_sel_hi:[1,0]
	v_pk_mul_f32 v[78:79], v[68:69], s[14:15] op_sel_hi:[1,0]
	v_pk_mul_f32 v[82:83], v[66:67], s[14:15] op_sel_hi:[1,0]
	s_mov_b64 s[4:5], 0

; __device__ __forceinline__ unsigned pk2(float lo, float hi) { f32x2 v = {lo, hi}; bf16x2_t b = __builtin_convertvector(v, bf16x2_t); return __builtin_bit_cast(unsigned, b); }
; __device__ __forceinline__ float fsigmoid(float x) { return __builtin_amdgcn_rcpf(1.0f + __expf(-x)); }
;     __device__ __forceinline__ void operator()(const f32x4 (&acc)[2][2][4][2], const Unit& u, int wr, int wc, int fr, int fq) const {
;     ...
;             for (int m = 0; m < 4; ++m) { const int row = row0 + ai * HALF + m * 16; bf16_t* rowp = O + (size_t)row * ldc + col0;
;                 const float rs = 1.0f / sqrtf(ssq[row] * (1.0f / D) + RMS_EPS);
; #pragma unroll
;                 for (int bj = 0; bj < 2; ++bj) { f32x4 v0 = acc[ai][bj][m][0] * rs, v1 = acc[ai][bj][m][1] * rs;
;                     if (mode == 1) {
; #pragma unroll
;                         for (int j = 0; j < 4; ++j) { v0[j] = fsigmoid(v0[j]); v1[j] = fsigmoid(v1[j]); } }
;                     else if (mode == 2) { v0 = v0 * 0.08838834764831845f; v1 = v1 * 0.08838834764831845f; }
;                     u32x4 w; w.x = pk2(v0[0], v0[1]); w.y = pk2(v0[2], v0[3]); w.z = pk2(v1[0], v1[1]); w.w = pk2(v1[2], v1[3]);
;                     *(u32x4*)(rowp + bj * HALF) = w; } }
.LBB0_341:
	v_cvt_pk_bf16_f32 v66, v80, v81
	v_cvt_pk_bf16_f32 v67, v76, v77
	v_cvt_pk_bf16_f32 v68, v82, v83
	v_cvt_pk_bf16_f32 v69, v78, v79
	global_store_dwordx4 v[74:75], v[66:69], off offset:256 sc1
	s_nop 0
	s_cmp_gt_i32 s17, 1
	v_mov_b32_e32 v66, v171
	v_fmamk_f32 v66, v66, 0x39800000, v165
	v_mul_f32_e32 v67, 0x4f800000, v66
	v_cmp_gt_f32_e32 vcc, s83, v66
	s_nop 1
	v_cndmask_b32_e32 v66, v66, v67, vcc
	v_sqrt_f32_e32 v67, v66
	s_nop 0
	v_add_u32_e32 v68, -1, v67
	v_add_u32_e32 v69, 1, v67
	v_fma_f32 v70, -v68, v67, v66
	v_fma_f32 v71, -v69, v67, v66
	v_cmp_ge_f32_e64 s[4:5], 0, v70
	s_nop 1
	v_cndmask_b32_e64 v67, v67, v68, s[4:5]
	v_cmp_lt_f32_e64 s[4:5], 0, v71
	s_nop 1
	v_cndmask_b32_e64 v67, v67, v69, s[4:5]
	v_mul_f32_e32 v68, 0x37800000, v67
	v_cndmask_b32_e32 v67, v67, v68, vcc
	v_cmp_class_f32_e32 vcc, v66, v166
	s_nop 1
	v_cndmask_b32_e32 v66, v67, v66, vcc
	v_div_scale_f32 v67, s[4:5], v66, v66, 1.0
	v_rcp_f32_e32 v68, v67
	v_div_scale_f32 v69, vcc, 1.0, v66, 1.0
	s_mov_b64 s[4:5], -1
	v_fma_f32 v70, -v67, v68, 1.0
	v_fmac_f32_e32 v68, v70, v68
	v_mul_f32_e32 v70, v69, v68
	v_fma_f32 v71, -v67, v70, v69
	v_fmac_f32_e32 v70, v71, v68
	v_fma_f32 v67, -v67, v70, v69
	v_div_fmas_f32 v67, v67, v68, v70
	v_div_fixup_f32 v66, v67, v66, 1.0
	v_pk_mul_f32 v[64:65], v[64:65], v[66:67] op_sel_hi:[1,0]
	v_pk_mul_f32 v[62:63], v[62:63], v[66:67] op_sel_hi:[1,0]
	v_pk_mul_f32 v[60:61], v[60:61], v[66:67] op_sel_hi:[1,0]
	v_pk_mul_f32 v[58:59], v[58:59], v[66:67] op_sel_hi:[1,0]
	s_cbranch_scc0 .LBB0_343
	v_pk_mul_f32 v[68:69], v[64:65], s[14:15] op_sel_hi:[1,0]
	v_pk_mul_f32 v[72:73], v[62:63], s[14:15] op_sel_hi:[1,0]
	v_pk_mul_f32 v[70:71], v[60:61], s[14:15] op_sel_hi:[1,0]
	v_pk_mul_f32 v[74:75], v[58:59], s[14:15] op_sel_hi:[1,0]
	s_mov_b64 s[4:5], 0

; __device__ __forceinline__ unsigned pk2(float lo, float hi) { f32x2 v = {lo, hi}; bf16x2_t b = __builtin_convertvector(v, bf16x2_t); return __builtin_bit_cast(unsigned, b); }
; __device__ __forceinline__ float fsigmoid(float x) { return __builtin_amdgcn_rcpf(1.0f + __expf(-x)); }
;     __device__ __forceinline__ void operator()(const f32x4 (&acc)[2][2][4][2], const Unit& u, int wr, int wc, int fr, int fq) const {
;     ...
;             for (int m = 0; m < 4; ++m) { const int row = row0 + ai * HALF + m * 16; bf16_t* rowp = O + (size_t)row * ldc + col0;
;                 const float rs = 1.0f / sqrtf(ssq[row] * (1.0f / D) + RMS_EPS);
; #pragma unroll
;                 for (int bj = 0; bj < 2; ++bj) { f32x4 v0 = acc[ai][bj][m][0] * rs, v1 = acc[ai][bj][m][1] * rs;
;                     if (mode == 1) {
; #pragma unroll
;                         for (int j = 0; j < 4; ++j) { v0[j] = fsigmoid(v0[j]); v1[j] = fsigmoid(v1[j]); } }
;                     else if (mode == 2) { v0 = v0 * 0.08838834764831845f; v1 = v1 * 0.08838834764831845f; }
;                     u32x4 w; w.x = pk2(v0[0], v0[1]); w.y = pk2(v0[2], v0[3]); w.z = pk2(v1[0], v1[1]); w.w = pk2(v1[2], v1[3]);
;                     *(u32x4*)(rowp + bj * HALF) = w; } }
.LBB0_347:
	v_add_u32_e32 v60, 0x80, v146
	v_mov_b64_e32 v[58:59], s[24:25]
	v_mad_i64_i32 v[58:59], s[4:5], v60, s61, v[58:59]
	v_lshl_add_u64 v[58:59], v[122:123], 1, v[58:59]
	v_cvt_pk_bf16_f32 v60, v72, v73
	v_cvt_pk_bf16_f32 v61, v68, v69
	v_cvt_pk_bf16_f32 v62, v74, v75
	v_cvt_pk_bf16_f32 v63, v70, v71
	global_store_dwordx4 v[58:59], v[60:63], off sc1
	v_mov_b32_e32 v67, v66
	v_pk_mul_f32 v[54:55], v[54:55], v[66:67]
	v_mov_b32_e32 v60, v66
	v_mov_b32_e32 v61, v66
	v_pk_mul_f32 v[56:57], v[56:57], v[60:61]
	v_pk_mul_f32 v[52:53], v[52:53], v[60:61]
	v_pk_mul_f32 v[50:51], v[50:51], v[66:67]
	s_cmp_gt_i32 s17, 1
	s_mov_b64 s[4:5], -1
	s_cbranch_scc0 .LBB0_349
	v_pk_mul_f32 v[60:61], v[56:57], s[14:15] op_sel_hi:[1,0]
	v_pk_mul_f32 v[64:65], v[54:55], s[14:15] op_sel_hi:[1,0]
	v_pk_mul_f32 v[62:63], v[52:53], s[14:15] op_sel_hi:[1,0]
	v_pk_mul_f32 v[66:67], v[50:51], s[14:15] op_sel_hi:[1,0]
	s_mov_b64 s[4:5], 0

; __device__ __forceinline__ unsigned pk2(float lo, float hi) { f32x2 v = {lo, hi}; bf16x2_t b = __builtin_convertvector(v, bf16x2_t); return __builtin_bit_cast(unsigned, b); }
; __device__ __forceinline__ float fsigmoid(float x) { return __builtin_amdgcn_rcpf(1.0f + __expf(-x)); }
;     __device__ __forceinline__ void operator()(const f32x4 (&acc)[2][2][4][2], const Unit& u, int wr, int wc, int fr, int fq) const {
;     ...
;             for (int m = 0; m < 4; ++m) { const int row = row0 + ai * HALF + m * 16; bf16_t* rowp = O + (size_t)row * ldc + col0;
;                 const float rs = 1.0f / sqrtf(ssq[row] * (1.0f / D) + RMS_EPS);
; #pragma unroll
;                 for (int bj = 0; bj < 2; ++bj) { f32x4 v0 = acc[ai][bj][m][0] * rs, v1 = acc[ai][bj][m][1] * rs;
;                     if (mode == 1) {
; #pragma unroll
;                         for (int j = 0; j < 4; ++j) { v0[j] = fsigmoid(v0[j]); v1[j] = fsigmoid(v1[j]); } }
;                     else if (mode == 2) { v0 = v0 * 0.08838834764831845f; v1 = v1 * 0.08838834764831845f; }
;                     u32x4 w; w.x = pk2(v0[0], v0[1]); w.y = pk2(v0[2], v0[3]); w.z = pk2(v1[0], v1[1]); w.w = pk2(v1[2], v1[3]);
;                     *(u32x4*)(rowp + bj * HALF) = w; } }
.LBB0_353:
	v_cvt_pk_bf16_f32 v50, v64, v65
	v_cvt_pk_bf16_f32 v51, v60, v61
	v_cvt_pk_bf16_f32 v52, v66, v67
	v_cvt_pk_bf16_f32 v53, v62, v63
	global_store_dwordx4 v[58:59], v[50:53], off offset:256 sc1
	s_nop 0
	s_cmp_gt_i32 s17, 1
	v_mov_b32_e32 v50, v172
	v_fmamk_f32 v50, v50, 0x39800000, v165
	v_mul_f32_e32 v51, 0x4f800000, v50
	v_cmp_gt_f32_e32 vcc, s83, v50
	s_nop 1
	v_cndmask_b32_e32 v50, v50, v51, vcc
	v_sqrt_f32_e32 v51, v50
	s_nop 0
	v_add_u32_e32 v52, -1, v51
	v_add_u32_e32 v53, 1, v51
	v_fma_f32 v54, -v52, v51, v50
	v_fma_f32 v55, -v53, v51, v50
	v_cmp_ge_f32_e64 s[4:5], 0, v54
	s_nop 1
	v_cndmask_b32_e64 v51, v51, v52, s[4:5]
	v_cmp_lt_f32_e64 s[4:5], 0, v55
	s_nop 1
	v_cndmask_b32_e64 v51, v51, v53, s[4:5]
	v_mul_f32_e32 v52, 0x37800000, v51
	v_cndmask_b32_e32 v51, v51, v52, vcc
	v_cmp_class_f32_e32 vcc, v50, v166
	s_nop 1
	v_cndmask_b32_e32 v50, v51, v50, vcc
	v_div_scale_f32 v51, s[4:5], v50, v50, 1.0
	v_rcp_f32_e32 v52, v51
	v_div_scale_f32 v53, vcc, 1.0, v50, 1.0
	s_mov_b64 s[4:5], -1
	v_fma_f32 v54, -v51, v52, 1.0
	v_fmac_f32_e32 v52, v54, v52
	v_mul_f32_e32 v54, v53, v52
	v_fma_f32 v55, -v51, v54, v53
	v_fmac_f32_e32 v54, v55, v52
	v_fma_f32 v51, -v51, v54, v53
	v_div_fmas_f32 v51, v51, v52, v54
	v_div_fixup_f32 v50, v51, v50, 1.0
	v_pk_mul_f32 v[48:49], v[48:49], v[50:51] op_sel_hi:[1,0]
	v_pk_mul_f32 v[46:47], v[46:47], v[50:51] op_sel_hi:[1,0]
	v_pk_mul_f32 v[44:45], v[44:45], v[50:51] op_sel_hi:[1,0]
	v_pk_mul_f32 v[42:43], v[42:43], v[50:51] op_sel_hi:[1,0]
	s_cbranch_scc0 .LBB0_355
	v_pk_mul_f32 v[52:53], v[48:49], s[14:15] op_sel_hi:[1,0]
	v_pk_mul_f32 v[56:57], v[46:47], s[14:15] op_sel_hi:[1,0]
	v_pk_mul_f32 v[54:55], v[44:45], s[14:15] op_sel_hi:[1,0]
	v_pk_mul_f32 v[58:59], v[42:43], s[14:15] op_sel_hi:[1,0]
	s_mov_b64 s[4:5], 0

; __device__ __forceinline__ unsigned pk2(float lo, float hi) { f32x2 v = {lo, hi}; bf16x2_t b = __builtin_convertvector(v, bf16x2_t); return __builtin_bit_cast(unsigned, b); }
; __device__ __forceinline__ float fsigmoid(float x) { return __builtin_amdgcn_rcpf(1.0f + __expf(-x)); }
;     __device__ __forceinline__ void operator()(const f32x4 (&acc)[2][2][4][2], const Unit& u, int wr, int wc, int fr, int fq) const {
;     ...
;             for (int m = 0; m < 4; ++m) { const int row = row0 + ai * HALF + m * 16; bf16_t* rowp = O + (size_t)row * ldc + col0;
;                 const float rs = 1.0f / sqrtf(ssq[row] * (1.0f / D) + RMS_EPS);
; #pragma unroll
;                 for (int bj = 0; bj < 2; ++bj) { f32x4 v0 = acc[ai][bj][m][0] * rs, v1 = acc[ai][bj][m][1] * rs;
;                     if (mode == 1) {
; #pragma unroll
;                         for (int j = 0; j < 4; ++j) { v0[j] = fsigmoid(v0[j]); v1[j] = fsigmoid(v1[j]); } }
;                     else if (mode == 2) { v0 = v0 * 0.08838834764831845f; v1 = v1 * 0.08838834764831845f; }
;                     u32x4 w; w.x = pk2(v0[0], v0[1]); w.y = pk2(v0[2], v0[3]); w.z = pk2(v1[0], v1[1]); w.w = pk2(v1[2], v1[3]);
;                     *(u32x4*)(rowp + bj * HALF) = w; } }
.LBB0_359:
	v_add_u32_e32 v44, 0x90, v146
	v_mov_b64_e32 v[42:43], s[24:25]
	v_mad_i64_i32 v[42:43], s[4:5], v44, s61, v[42:43]
	v_lshl_add_u64 v[42:43], v[122:123], 1, v[42:43]
	v_cvt_pk_bf16_f32 v44, v56, v57
	v_cvt_pk_bf16_f32 v45, v52, v53
	v_cvt_pk_bf16_f32 v46, v58, v59
	v_cvt_pk_bf16_f32 v47, v54, v55
	global_store_dwordx4 v[42:43], v[44:47], off sc1
	v_mov_b32_e32 v51, v50
	v_pk_mul_f32 v[38:39], v[38:39], v[50:51]
	v_mov_b32_e32 v44, v50
	v_mov_b32_e32 v45, v50
	v_pk_mul_f32 v[40:41], v[40:41], v[44:45]
	v_pk_mul_f32 v[36:37], v[36:37], v[44:45]
	v_pk_mul_f32 v[34:35], v[34:35], v[50:51]
	s_cmp_gt_i32 s17, 1
	s_mov_b64 s[4:5], -1
	s_cbranch_scc0 .LBB0_361
	v_pk_mul_f32 v[44:45], v[40:41], s[14:15] op_sel_hi:[1,0]
	v_pk_mul_f32 v[48:49], v[38:39], s[14:15] op_sel_hi:[1,0]
	v_pk_mul_f32 v[46:47], v[36:37], s[14:15] op_sel_hi:[1,0]
	v_pk_mul_f32 v[50:51], v[34:35], s[14:15] op_sel_hi:[1,0]
	s_mov_b64 s[4:5], 0

; __device__ __forceinline__ unsigned pk2(float lo, float hi) { f32x2 v = {lo, hi}; bf16x2_t b = __builtin_convertvector(v, bf16x2_t); return __builtin_bit_cast(unsigned, b); }
; __device__ __forceinline__ float fsigmoid(float x) { return __builtin_amdgcn_rcpf(1.0f + __expf(-x)); }
;     __device__ __forceinline__ void operator()(const f32x4 (&acc)[2][2][4][2], const Unit& u, int wr, int wc, int fr, int fq) const {
;     ...
;             for (int m = 0; m < 4; ++m) { const int row = row0 + ai * HALF + m * 16; bf16_t* rowp = O + (size_t)row * ldc + col0;
;                 const float rs = 1.0f / sqrtf(ssq[row] * (1.0f / D) + RMS_EPS);
; #pragma unroll
;                 for (int bj = 0; bj < 2; ++bj) { f32x4 v0 = acc[ai][bj][m][0] * rs, v1 = acc[ai][bj][m][1] * rs;
;                     if (mode == 1) {
; #pragma unroll
;                         for (int j = 0; j < 4; ++j) { v0[j] = fsigmoid(v0[j]); v1[j] = fsigmoid(v1[j]); } }
;                     else if (mode == 2) { v0 = v0 * 0.08838834764831845f; v1 = v1 * 0.08838834764831845f; }
;                     u32x4 w; w.x = pk2(v0[0], v0[1]); w.y = pk2(v0[2], v0[3]); w.z = pk2(v1[0], v1[1]); w.w = pk2(v1[2], v1[3]);
;                     *(u32x4*)(rowp + bj * HALF) = w; } }
.LBB0_365:
	v_cvt_pk_bf16_f32 v34, v48, v49
	v_cvt_pk_bf16_f32 v35, v44, v45
	v_cvt_pk_bf16_f32 v36, v50, v51
	v_cvt_pk_bf16_f32 v37, v46, v47
	global_store_dwordx4 v[42:43], v[34:37], off offset:256 sc1
	s_nop 0
	s_cmp_gt_i32 s17, 1
	v_mov_b32_e32 v34, v173
	v_fmamk_f32 v34, v34, 0x39800000, v165
	v_mul_f32_e32 v35, 0x4f800000, v34
	v_cmp_gt_f32_e32 vcc, s83, v34
	s_nop 1
	v_cndmask_b32_e32 v34, v34, v35, vcc
	v_sqrt_f32_e32 v35, v34
	s_nop 0
	v_add_u32_e32 v36, -1, v35
	v_add_u32_e32 v37, 1, v35
	v_fma_f32 v38, -v36, v35, v34
	v_fma_f32 v39, -v37, v35, v34
	v_cmp_ge_f32_e64 s[4:5], 0, v38
	s_nop 1
	v_cndmask_b32_e64 v35, v35, v36, s[4:5]
	v_cmp_lt_f32_e64 s[4:5], 0, v39
	s_nop 1
	v_cndmask_b32_e64 v35, v35, v37, s[4:5]
	v_mul_f32_e32 v36, 0x37800000, v35
	v_cndmask_b32_e32 v35, v35, v36, vcc
	v_cmp_class_f32_e32 vcc, v34, v166
	s_nop 1
	v_cndmask_b32_e32 v34, v35, v34, vcc
	v_div_scale_f32 v35, s[4:5], v34, v34, 1.0
	v_rcp_f32_e32 v36, v35
	v_div_scale_f32 v37, vcc, 1.0, v34, 1.0
	s_mov_b64 s[4:5], -1
	v_fma_f32 v38, -v35, v36, 1.0
	v_fmac_f32_e32 v36, v38, v36
	v_mul_f32_e32 v38, v37, v36
	v_fma_f32 v39, -v35, v38, v37
	v_fmac_f32_e32 v38, v39, v36
	v_fma_f32 v35, -v35, v38, v37
	v_div_fmas_f32 v35, v35, v36, v38
	v_div_fixup_f32 v34, v35, v34, 1.0
	v_pk_mul_f32 v[32:33], v[32:33], v[34:35] op_sel_hi:[1,0]
	v_pk_mul_f32 v[30:31], v[30:31], v[34:35] op_sel_hi:[1,0]
	v_pk_mul_f32 v[28:29], v[28:29], v[34:35] op_sel_hi:[1,0]
	v_pk_mul_f32 v[26:27], v[26:27], v[34:35] op_sel_hi:[1,0]
	s_cbranch_scc0 .LBB0_367
	v_pk_mul_f32 v[36:37], v[32:33], s[14:15] op_sel_hi:[1,0]
	v_pk_mul_f32 v[40:41], v[30:31], s[14:15] op_sel_hi:[1,0]
	v_pk_mul_f32 v[38:39], v[28:29], s[14:15] op_sel_hi:[1,0]
	v_pk_mul_f32 v[42:43], v[26:27], s[14:15] op_sel_hi:[1,0]
	s_mov_b64 s[4:5], 0

; __device__ __forceinline__ unsigned pk2(float lo, float hi) { f32x2 v = {lo, hi}; bf16x2_t b = __builtin_convertvector(v, bf16x2_t); return __builtin_bit_cast(unsigned, b); }
; __device__ __forceinline__ float fsigmoid(float x) { return __builtin_amdgcn_rcpf(1.0f + __expf(-x)); }
;     __device__ __forceinline__ void operator()(const f32x4 (&acc)[2][2][4][2], const Unit& u, int wr, int wc, int fr, int fq) const {
;     ...
;             for (int m = 0; m < 4; ++m) { const int row = row0 + ai * HALF + m * 16; bf16_t* rowp = O + (size_t)row * ldc + col0;
;                 const float rs = 1.0f / sqrtf(ssq[row] * (1.0f / D) + RMS_EPS);
; #pragma unroll
;                 for (int bj = 0; bj < 2; ++bj) { f32x4 v0 = acc[ai][bj][m][0] * rs, v1 = acc[ai][bj][m][1] * rs;
;                     if (mode == 1) {
; #pragma unroll
;                         for (int j = 0; j < 4; ++j) { v0[j] = fsigmoid(v0[j]); v1[j] = fsigmoid(v1[j]); } }
;                     else if (mode == 2) { v0 = v0 * 0.08838834764831845f; v1 = v1 * 0.08838834764831845f; }
;                     u32x4 w; w.x = pk2(v0[0], v0[1]); w.y = pk2(v0[2], v0[3]); w.z = pk2(v1[0], v1[1]); w.w = pk2(v1[2], v1[3]);
;                     *(u32x4*)(rowp + bj * HALF) = w; } }
.LBB0_371:
	v_add_u32_e32 v28, 0xa0, v146
	v_mov_b64_e32 v[26:27], s[24:25]
	v_mad_i64_i32 v[26:27], s[4:5], v28, s61, v[26:27]
	v_lshl_add_u64 v[26:27], v[122:123], 1, v[26:27]
	v_cvt_pk_bf16_f32 v28, v40, v41
	v_cvt_pk_bf16_f32 v29, v36, v37
	v_cvt_pk_bf16_f32 v30, v42, v43
	v_cvt_pk_bf16_f32 v31, v38, v39
	global_store_dwordx4 v[26:27], v[28:31], off sc1
	v_mov_b32_e32 v35, v34
	v_pk_mul_f32 v[22:23], v[22:23], v[34:35]
	v_mov_b32_e32 v28, v34
	v_mov_b32_e32 v29, v34
	v_pk_mul_f32 v[24:25], v[24:25], v[28:29]
	v_pk_mul_f32 v[20:21], v[20:21], v[28:29]
	v_pk_mul_f32 v[18:19], v[18:19], v[34:35]
	s_cmp_gt_i32 s17, 1
	s_mov_b64 s[4:5], -1
	s_cbranch_scc0 .LBB0_373
	v_pk_mul_f32 v[28:29], v[24:25], s[14:15] op_sel_hi:[1,0]
	v_pk_mul_f32 v[32:33], v[22:23], s[14:15] op_sel_hi:[1,0]
	v_pk_mul_f32 v[30:31], v[20:21], s[14:15] op_sel_hi:[1,0]
	v_pk_mul_f32 v[34:35], v[18:19], s[14:15] op_sel_hi:[1,0]
	s_mov_b64 s[4:5], 0

; __device__ __forceinline__ unsigned pk2(float lo, float hi) { f32x2 v = {lo, hi}; bf16x2_t b = __builtin_convertvector(v, bf16x2_t); return __builtin_bit_cast(unsigned, b); }
; __device__ __forceinline__ float fsigmoid(float x) { return __builtin_amdgcn_rcpf(1.0f + __expf(-x)); }
;     __device__ __forceinline__ void operator()(const f32x4 (&acc)[2][2][4][2], const Unit& u, int wr, int wc, int fr, int fq) const {
;     ...
;             for (int m = 0; m < 4; ++m) { const int row = row0 + ai * HALF + m * 16; bf16_t* rowp = O + (size_t)row * ldc + col0;
;                 const float rs = 1.0f / sqrtf(ssq[row] * (1.0f / D) + RMS_EPS);
; #pragma unroll
;                 for (int bj = 0; bj < 2; ++bj) { f32x4 v0 = acc[ai][bj][m][0] * rs, v1 = acc[ai][bj][m][1] * rs;
;                     if (mode == 1) {
; #pragma unroll
;                         for (int j = 0; j < 4; ++j) { v0[j] = fsigmoid(v0[j]); v1[j] = fsigmoid(v1[j]); } }
;                     else if (mode == 2) { v0 = v0 * 0.08838834764831845f; v1 = v1 * 0.08838834764831845f; }
;                     u32x4 w; w.x = pk2(v0[0], v0[1]); w.y = pk2(v0[2], v0[3]); w.z = pk2(v1[0], v1[1]); w.w = pk2(v1[2], v1[3]);
;                     *(u32x4*)(rowp + bj * HALF) = w; } }
.LBB0_377:
	v_cvt_pk_bf16_f32 v18, v32, v33
	v_cvt_pk_bf16_f32 v19, v28, v29
	v_cvt_pk_bf16_f32 v20, v34, v35
	v_cvt_pk_bf16_f32 v21, v30, v31
	global_store_dwordx4 v[26:27], v[18:21], off offset:256 sc1
	s_nop 0
	s_cmp_gt_i32 s17, 1
	v_mov_b32_e32 v18, v174
	v_fmamk_f32 v18, v18, 0x39800000, v165
	v_mul_f32_e32 v19, 0x4f800000, v18
	v_cmp_gt_f32_e32 vcc, s83, v18
	s_nop 1
	v_cndmask_b32_e32 v18, v18, v19, vcc
	v_sqrt_f32_e32 v19, v18
	s_nop 0
	v_add_u32_e32 v20, -1, v19
	v_add_u32_e32 v21, 1, v19
	v_fma_f32 v22, -v20, v19, v18
	v_fma_f32 v23, -v21, v19, v18
	v_cmp_ge_f32_e64 s[4:5], 0, v22
	s_nop 1
	v_cndmask_b32_e64 v19, v19, v20, s[4:5]
	v_cmp_lt_f32_e64 s[4:5], 0, v23
	s_nop 1
	v_cndmask_b32_e64 v19, v19, v21, s[4:5]
	v_mul_f32_e32 v20, 0x37800000, v19
	v_cndmask_b32_e32 v19, v19, v20, vcc
	v_cmp_class_f32_e32 vcc, v18, v166
	s_nop 1
	v_cndmask_b32_e32 v18, v19, v18, vcc
	v_div_scale_f32 v19, s[4:5], v18, v18, 1.0
	v_rcp_f32_e32 v20, v19
	v_div_scale_f32 v21, vcc, 1.0, v18, 1.0
	s_mov_b64 s[4:5], -1
	v_fma_f32 v22, -v19, v20, 1.0
	v_fmac_f32_e32 v20, v22, v20
	v_mul_f32_e32 v22, v21, v20
	v_fma_f32 v23, -v19, v22, v21
	v_fmac_f32_e32 v22, v23, v20
	v_fma_f32 v19, -v19, v22, v21
	v_div_fmas_f32 v19, v19, v20, v22
	v_div_fixup_f32 v18, v19, v18, 1.0
	v_pk_mul_f32 v[16:17], v[16:17], v[18:19] op_sel_hi:[1,0]
	v_pk_mul_f32 v[14:15], v[14:15], v[18:19] op_sel_hi:[1,0]
	v_pk_mul_f32 v[12:13], v[12:13], v[18:19] op_sel_hi:[1,0]
	v_pk_mul_f32 v[10:11], v[10:11], v[18:19] op_sel_hi:[1,0]
	s_cbranch_scc0 .LBB0_379
	v_pk_mul_f32 v[20:21], v[16:17], s[14:15] op_sel_hi:[1,0]
	v_pk_mul_f32 v[24:25], v[14:15], s[14:15] op_sel_hi:[1,0]
	v_pk_mul_f32 v[22:23], v[12:13], s[14:15] op_sel_hi:[1,0]
	v_pk_mul_f32 v[26:27], v[10:11], s[14:15] op_sel_hi:[1,0]
	s_mov_b64 s[4:5], 0

; __device__ __forceinline__ unsigned pk2(float lo, float hi) { f32x2 v = {lo, hi}; bf16x2_t b = __builtin_convertvector(v, bf16x2_t); return __builtin_bit_cast(unsigned, b); }
; __device__ __forceinline__ float fsigmoid(float x) { return __builtin_amdgcn_rcpf(1.0f + __expf(-x)); }
;     __device__ __forceinline__ void operator()(const f32x4 (&acc)[2][2][4][2], const Unit& u, int wr, int wc, int fr, int fq) const {
;     ...
;             for (int m = 0; m < 4; ++m) { const int row = row0 + ai * HALF + m * 16; bf16_t* rowp = O + (size_t)row * ldc + col0;
;                 const float rs = 1.0f / sqrtf(ssq[row] * (1.0f / D) + RMS_EPS);
; #pragma unroll
;                 for (int bj = 0; bj < 2; ++bj) { f32x4 v0 = acc[ai][bj][m][0] * rs, v1 = acc[ai][bj][m][1] * rs;
;                     if (mode == 1) {
; #pragma unroll
;                         for (int j = 0; j < 4; ++j) { v0[j] = fsigmoid(v0[j]); v1[j] = fsigmoid(v1[j]); } }
;                     else if (mode == 2) { v0 = v0 * 0.08838834764831845f; v1 = v1 * 0.08838834764831845f; }
;                     u32x4 w; w.x = pk2(v0[0], v0[1]); w.y = pk2(v0[2], v0[3]); w.z = pk2(v1[0], v1[1]); w.w = pk2(v1[2], v1[3]);
;                     *(u32x4*)(rowp + bj * HALF) = w; } }
.LBB0_383:
	v_add_u32_e32 v12, 0xb0, v146
	v_mov_b64_e32 v[10:11], s[24:25]
	v_mad_i64_i32 v[10:11], s[4:5], v12, s61, v[10:11]
	v_lshl_add_u64 v[10:11], v[122:123], 1, v[10:11]
	v_cvt_pk_bf16_f32 v12, v24, v25
	v_cvt_pk_bf16_f32 v13, v20, v21
	v_cvt_pk_bf16_f32 v14, v26, v27
	v_cvt_pk_bf16_f32 v15, v22, v23
	global_store_dwordx4 v[10:11], v[12:15], off sc1
	v_mov_b32_e32 v19, v18
	v_pk_mul_f32 v[6:7], v[6:7], v[18:19]
	v_mov_b32_e32 v12, v18
	v_mov_b32_e32 v13, v18
	v_pk_mul_f32 v[8:9], v[8:9], v[12:13]
	v_pk_mul_f32 v[4:5], v[4:5], v[12:13]
	v_pk_mul_f32 v[2:3], v[2:3], v[18:19]
	s_cmp_gt_i32 s17, 1
	s_mov_b64 s[4:5], -1
	s_cbranch_scc0 .LBB0_385
	v_pk_mul_f32 v[12:13], v[8:9], s[14:15] op_sel_hi:[1,0]
	v_pk_mul_f32 v[16:17], v[6:7], s[14:15] op_sel_hi:[1,0]
	v_pk_mul_f32 v[14:15], v[4:5], s[14:15] op_sel_hi:[1,0]
	v_pk_mul_f32 v[18:19], v[2:3], s[14:15] op_sel_hi:[1,0]
	s_mov_b64 s[4:5], 0

; __device__ __forceinline__ unsigned pk2(float lo, float hi) { f32x2 v = {lo, hi}; bf16x2_t b = __builtin_convertvector(v, bf16x2_t); return __builtin_bit_cast(unsigned, b); }
; __device__ __forceinline__ float fsigmoid(float x) { return __builtin_amdgcn_rcpf(1.0f + __expf(-x)); }
;     __device__ __forceinline__ void operator()(const f32x4 (&acc)[2][2][4][2], const Unit& u, int wr, int wc, int fr, int fq) const {
;     ...
;             for (int m = 0; m < 4; ++m) { const int row = row0 + ai * HALF + m * 16; bf16_t* rowp = O + (size_t)row * ldc + col0;
;                 const float rs = 1.0f / sqrtf(ssq[row] * (1.0f / D) + RMS_EPS);
; #pragma unroll
;                 for (int bj = 0; bj < 2; ++bj) { f32x4 v0 = acc[ai][bj][m][0] * rs, v1 = acc[ai][bj][m][1] * rs;
;                     if (mode == 1) {
; #pragma unroll
;                         for (int j = 0; j < 4; ++j) { v0[j] = fsigmoid(v0[j]); v1[j] = fsigmoid(v1[j]); } }
;                     else if (mode == 2) { v0 = v0 * 0.08838834764831845f; v1 = v1 * 0.08838834764831845f; }
;                     u32x4 w; w.x = pk2(v0[0], v0[1]); w.y = pk2(v0[2], v0[3]); w.z = pk2(v1[0], v1[1]); w.w = pk2(v1[2], v1[3]);
;                     *(u32x4*)(rowp + bj * HALF) = w; } }
.LBB0_389:
	v_cvt_pk_bf16_f32 v2, v16, v17
	v_cvt_pk_bf16_f32 v3, v12, v13
	v_cvt_pk_bf16_f32 v4, v18, v19
	v_cvt_pk_bf16_f32 v5, v14, v15
	s_andn2_b64 vcc, exec, s[0:1]
	s_mov_b64 s[0:1], -1
	global_store_dwordx4 v[10:11], v[2:5], off offset:256 sc1
	s_cbranch_vccnz .LBB0_286
	s_andn2_b64 vcc, exec, s[8:9]
	s_cbranch_vccnz .LBB0_285
	s_barrier
	s_branch .LBB0_285

; __host__ __device__ __forceinline__ size_t blk(int r, int k, int K) { return (((size_t)((r >> 8) * (K >> 6) + (k >> 6))) << 14) + (size_t)(((r & 255) << 6) + (k & 63)); }
; __device__ __forceinline__ float bflo(unsigned w) { return __uint_as_float(w << 16); }
; __device__ __forceinline__ float bfhi(unsigned w) { return __uint_as_float(w & 0xffff0000u); }
; __device__ __forceinline__ unsigned pk2(float lo, float hi) { f32x2 v = {lo, hi}; bf16x2_t b = __builtin_convertvector(v, bf16x2_t); return __builtin_bit_cast(unsigned, b); }
;     __device__ __forceinline__ void operator()(const f32x4 (&acc)[2][2][4][2], const Unit& u, int wr, int wc, int fr, int fq) const {
;     ...
;             for (int m = 0; m < 4; ++m) { const int row = row0 + ai * HALF + m * 16;
; #pragma unroll
;                 for (int bj = 0; bj < 2; ++bj) { const int c = col0 + bj * HALF; const u32x4 b = *(const u32x4*)(P + (size_t)row * NP + PC_GB + c);
;                     const f32x4 b0 = {bflo(b.x), bfhi(b.x), bflo(b.y), bfhi(b.y)}, b1 = {bflo(b.z), bfhi(b.z), bflo(b.w), bfhi(b.w)};
;                     const f32x4 v0 = acc[ai][bj][m][0] * b0, v1 = acc[ai][bj][m][1] * b1;
;                     u32x4 w; w.x = pk2(v0[0], v0[1]); w.y = pk2(v0[2], v0[3]); w.z = pk2(v1[0], v1[1]); w.w = pk2(v1[2], v1[3]);
;                     *(u32x4*)(MG + blk(row, c, D)) = w; } }
.LBB0_687:
	s_or_b32 s33, s39, s74
	v_or_b32_e32 v130, s33, v1
	v_mov_b64_e32 v[132:133], s[24:25]
	v_ashrrev_i32_e32 v131, 31, v130
	v_mad_i64_i32 v[156:157], s[26:27], v166, s78, v[132:133]
	v_lshl_add_u64 v[172:173], v[156:157], 0, s[8:9]
	v_lshlrev_b64 v[156:157], 1, v[130:131]
	v_lshl_add_u64 v[158:159], v[172:173], 0, v[156:157]
	global_load_dwordx4 v[168:171], v[158:159], off
	v_ashrrev_i32_e32 v131, 2, v166
	s_ashr_i32 s26, s33, 6
	v_and_b32_e32 v159, 0xffffffc0, v131
	v_add_u32_e32 v176, s26, v159
	v_bitop3_b32 v158, s33, 56, v1 bitop3:0xc8
	v_lshlrev_b32_e32 v142, 6, v166
	v_ashrrev_i32_e32 v177, 31, v176
	v_and_or_b32 v131, v142, s82, v158
	v_or_b32_e32 v174, 0x80, v130
	v_lshlrev_b64 v[176:177], 15, v[176:177]
	v_lshlrev_b32_e32 v142, 1, v131
	v_ashrrev_i32_e32 v175, 31, v174
	v_lshl_add_u64 v[176:177], s[66:67], 0, v[176:177]
	v_lshlrev_b64 v[130:131], 1, v[174:175]
	v_lshl_add_u64 v[176:177], v[176:177], 0, v[142:143]
	v_lshl_add_u64 v[172:173], v[172:173], 0, v[130:131]
	s_andn2_b64 vcc, exec, s[0:1]
	s_mov_b64 s[0:1], -1
	s_waitcnt vmcnt(0)
	v_lshlrev_b32_e32 v180, 16, v168
	v_and_b32_e32 v181, 0xffff0000, v168
	v_lshlrev_b32_e32 v168, 16, v169
	v_and_b32_e32 v169, 0xffff0000, v169
	v_lshlrev_b32_e32 v182, 16, v170
	v_and_b32_e32 v183, 0xffff0000, v170
	v_lshlrev_b32_e32 v170, 16, v171
	v_and_b32_e32 v171, 0xffff0000, v171
	v_pk_mul_f32 v[16:17], v[16:17], v[168:169]
	v_pk_mul_f32 v[14:15], v[14:15], v[180:181]
	v_pk_mul_f32 v[168:169], v[12:13], v[170:171]
	v_pk_mul_f32 v[12:13], v[10:11], v[182:183]
	v_cvt_pk_bf16_f32 v10, v14, v15
	v_cvt_pk_bf16_f32 v11, v16, v17
	v_cvt_pk_bf16_f32 v12, v12, v13
	v_cvt_pk_bf16_f32 v13, v168, v169
	global_store_dwordx4 v[176:177], v[10:13], off sc1
	global_load_dwordx4 v[12:15], v[172:173], off
	s_waitcnt vmcnt(0)
	v_lshlrev_b32_e32 v172, 16, v12
	v_ashrrev_i32_e32 v10, 6, v174
	v_add_u32_e32 v168, v159, v10
	v_ashrrev_i32_e32 v169, 31, v168
	v_add_u32_e32 v11, 16, v166
	v_lshlrev_b64 v[168:169], 15, v[168:169]
	v_and_b32_e32 v173, 0xffff0000, v12
	v_lshlrev_b32_e32 v12, 16, v13
	v_and_b32_e32 v13, 0xffff0000, v13
	v_lshlrev_b32_e32 v174, 16, v14
	v_and_b32_e32 v175, 0xffff0000, v14
	v_lshlrev_b32_e32 v14, 16, v15
	v_and_b32_e32 v15, 0xffff0000, v15
	v_mad_i64_i32 v[16:17], s[48:49], v11, s78, v[132:133]
	v_lshl_add_u64 v[168:169], s[66:67], 0, v[168:169]
	v_pk_mul_f32 v[32:33], v[32:33], v[12:13]
	v_pk_mul_f32 v[12:13], v[30:31], v[172:173]
	v_pk_mul_f32 v[28:29], v[28:29], v[14:15]
	v_pk_mul_f32 v[14:15], v[26:27], v[174:175]
	v_lshl_add_u64 v[16:17], v[16:17], 0, s[8:9]
	v_lshl_add_u64 v[168:169], v[168:169], 0, v[142:143]
	v_cvt_pk_bf16_f32 v12, v12, v13
	v_cvt_pk_bf16_f32 v13, v32, v33
	v_cvt_pk_bf16_f32 v14, v14, v15
	v_cvt_pk_bf16_f32 v15, v28, v29
	v_lshl_add_u64 v[170:171], v[16:17], 0, v[156:157]
	global_store_dwordx4 v[168:169], v[12:15], off sc1
	global_load_dwordx4 v[12:15], v[170:171], off
	v_ashrrev_i32_e32 v26, 2, v11
	v_and_b32_e32 v159, 0xffffffc0, v26
	v_add_u32_e32 v26, s26, v159
	v_lshlrev_b32_e32 v11, 6, v11
	v_ashrrev_i32_e32 v27, 31, v26
	v_and_or_b32 v11, v11, s82, v158
	v_lshlrev_b64 v[26:27], 15, v[26:27]
	v_lshl_add_u64 v[26:27], s[66:67], 0, v[26:27]
	v_lshlrev_b32_e32 v142, 1, v11
	v_lshl_add_u64 v[26:27], v[26:27], 0, v[142:143]
	v_lshl_add_u64 v[16:17], v[16:17], 0, v[130:131]
	v_add_u32_e32 v11, 32, v166
	s_waitcnt vmcnt(0)
	v_lshlrev_b32_e32 v28, 16, v12
	v_and_b32_e32 v29, 0xffff0000, v12
	v_lshlrev_b32_e32 v12, 16, v13
	v_and_b32_e32 v13, 0xffff0000, v13
	v_lshlrev_b32_e32 v30, 16, v14
	v_and_b32_e32 v31, 0xffff0000, v14
	v_lshlrev_b32_e32 v14, 16, v15
	v_and_b32_e32 v15, 0xffff0000, v15
	v_pk_mul_f32 v[32:33], v[40:41], v[12:13]
	v_pk_mul_f32 v[12:13], v[38:39], v[28:29]
	v_pk_mul_f32 v[28:29], v[36:37], v[14:15]
	v_pk_mul_f32 v[14:15], v[34:35], v[30:31]
	v_cvt_pk_bf16_f32 v12, v12, v13
	v_cvt_pk_bf16_f32 v13, v32, v33
	v_cvt_pk_bf16_f32 v14, v14, v15
	v_cvt_pk_bf16_f32 v15, v28, v29
	global_store_dwordx4 v[26:27], v[12:15], off sc1
	global_load_dwordx4 v[12:15], v[16:17], off
	v_add_u32_e32 v26, v159, v10
	v_ashrrev_i32_e32 v27, 31, v26
	v_lshlrev_b64 v[26:27], 15, v[26:27]
	v_mad_i64_i32 v[16:17], s[48:49], v11, s78, v[132:133]
	v_lshl_add_u64 v[26:27], s[66:67], 0, v[26:27]
	v_lshl_add_u64 v[16:17], v[16:17], 0, s[8:9]
	v_lshl_add_u64 v[26:27], v[26:27], 0, v[142:143]
	v_lshl_add_u64 v[28:29], v[16:17], 0, v[156:157]
	v_lshl_add_u64 v[16:17], v[16:17], 0, v[130:131]
	s_waitcnt vmcnt(0)
	v_lshlrev_b32_e32 v30, 16, v12
	v_and_b32_e32 v31, 0xffff0000, v12
	v_lshlrev_b32_e32 v12, 16, v13
	v_and_b32_e32 v13, 0xffff0000, v13
	v_lshlrev_b32_e32 v32, 16, v14
	v_and_b32_e32 v33, 0xffff0000, v14
	v_lshlrev_b32_e32 v14, 16, v15
	v_and_b32_e32 v15, 0xffff0000, v15
	v_pk_mul_f32 v[34:35], v[56:57], v[12:13]
	v_pk_mul_f32 v[12:13], v[54:55], v[30:31]
	v_pk_mul_f32 v[30:31], v[52:53], v[14:15]
	v_pk_mul_f32 v[14:15], v[50:51], v[32:33]
	v_cvt_pk_bf16_f32 v12, v12, v13
	v_cvt_pk_bf16_f32 v13, v34, v35
	v_cvt_pk_bf16_f32 v14, v14, v15
	v_cvt_pk_bf16_f32 v15, v30, v31
	global_store_dwordx4 v[26:27], v[12:15], off sc1
	global_load_dwordx4 v[12:15], v[28:29], off
	v_ashrrev_i32_e32 v26, 2, v11
	v_and_b32_e32 v34, 0xffffffc0, v26
	v_add_u32_e32 v26, s26, v34
	v_lshlrev_b32_e32 v11, 6, v11
	v_ashrrev_i32_e32 v27, 31, v26
	v_and_or_b32 v11, v11, s82, v158
	v_lshlrev_b64 v[26:27], 15, v[26:27]
	v_lshl_add_u64 v[26:27], s[66:67], 0, v[26:27]
	v_lshlrev_b32_e32 v142, 1, v11
	v_lshl_add_u64 v[26:27], v[26:27], 0, v[142:143]
	v_add_u32_e32 v11, 48, v166
	s_waitcnt vmcnt(0)
; __host__ __device__ __forceinline__ size_t blk(int r, int k, int K) { return (((size_t)((r >> 8) * (K >> 6) + (k >> 6))) << 14) + (size_t)(((r & 255) << 6) + (k & 63)); }
; __device__ __forceinline__ float bflo(unsigned w) { return __uint_as_float(w << 16); }
; __device__ __forceinline__ float bfhi(unsigned w) { return __uint_as_float(w & 0xffff0000u); }
; __device__ __forceinline__ unsigned pk2(float lo, float hi) { f32x2 v = {lo, hi}; bf16x2_t b = __builtin_convertvector(v, bf16x2_t); return __builtin_bit_cast(unsigned, b); }
;     __device__ __forceinline__ void operator()(const f32x4 (&acc)[2][2][4][2], const Unit& u, int wr, int wc, int fr, int fq) const {
;     ...
;             for (int m = 0; m < 4; ++m) { const int row = row0 + ai * HALF + m * 16;
; #pragma unroll
;                 for (int bj = 0; bj < 2; ++bj) { const int c = col0 + bj * HALF; const u32x4 b = *(const u32x4*)(P + (size_t)row * NP + PC_GB + c);
;                     const f32x4 b0 = {bflo(b.x), bfhi(b.x), bflo(b.y), bfhi(b.y)}, b1 = {bflo(b.z), bfhi(b.z), bflo(b.w), bfhi(b.w)};
;                     const f32x4 v0 = acc[ai][bj][m][0] * b0, v1 = acc[ai][bj][m][1] * b1;
;                     u32x4 w; w.x = pk2(v0[0], v0[1]); w.y = pk2(v0[2], v0[3]); w.z = pk2(v1[0], v1[1]); w.w = pk2(v1[2], v1[3]);
;                     *(u32x4*)(MG + blk(row, c, D)) = w; } }
	v_lshlrev_b32_e32 v28, 16, v12
	v_and_b32_e32 v29, 0xffff0000, v12
	v_lshlrev_b32_e32 v12, 16, v13
	v_and_b32_e32 v13, 0xffff0000, v13
	v_lshlrev_b32_e32 v30, 16, v14
	v_and_b32_e32 v31, 0xffff0000, v14
	v_lshlrev_b32_e32 v14, 16, v15
	v_and_b32_e32 v15, 0xffff0000, v15
	v_pk_mul_f32 v[32:33], v[72:73], v[12:13]
	v_pk_mul_f32 v[12:13], v[70:71], v[28:29]
	v_pk_mul_f32 v[28:29], v[68:69], v[14:15]
	v_pk_mul_f32 v[14:15], v[66:67], v[30:31]
	v_cvt_pk_bf16_f32 v12, v12, v13
	v_cvt_pk_bf16_f32 v13, v32, v33
	v_cvt_pk_bf16_f32 v14, v14, v15
	v_cvt_pk_bf16_f32 v15, v28, v29
	global_store_dwordx4 v[26:27], v[12:15], off sc1
	global_load_dwordx4 v[12:15], v[16:17], off
	v_add_u32_e32 v26, v34, v10
	v_ashrrev_i32_e32 v27, 31, v26
	v_lshlrev_b64 v[26:27], 15, v[26:27]
	v_mad_i64_i32 v[16:17], s[48:49], v11, s78, v[132:133]
	v_lshl_add_u64 v[26:27], s[66:67], 0, v[26:27]
	v_lshl_add_u64 v[16:17], v[16:17], 0, s[8:9]
	v_lshl_add_u64 v[26:27], v[26:27], 0, v[142:143]
	v_lshl_add_u64 v[28:29], v[16:17], 0, v[156:157]
	v_lshl_add_u64 v[16:17], v[16:17], 0, v[130:131]
	s_waitcnt vmcnt(0)
	v_lshlrev_b32_e32 v30, 16, v12
	v_and_b32_e32 v31, 0xffff0000, v12
	v_lshlrev_b32_e32 v12, 16, v13
	v_and_b32_e32 v13, 0xffff0000, v13
	v_lshlrev_b32_e32 v32, 16, v14
	v_and_b32_e32 v33, 0xffff0000, v14
	v_lshlrev_b32_e32 v14, 16, v15
	v_and_b32_e32 v15, 0xffff0000, v15
	v_pk_mul_f32 v[34:35], v[88:89], v[12:13]
	v_pk_mul_f32 v[12:13], v[86:87], v[30:31]
	v_pk_mul_f32 v[30:31], v[84:85], v[14:15]
	v_pk_mul_f32 v[14:15], v[82:83], v[32:33]
	v_cvt_pk_bf16_f32 v12, v12, v13
	v_cvt_pk_bf16_f32 v13, v34, v35
	v_cvt_pk_bf16_f32 v14, v14, v15
	v_cvt_pk_bf16_f32 v15, v30, v31
	global_store_dwordx4 v[26:27], v[12:15], off sc1
	global_load_dwordx4 v[12:15], v[28:29], off
	v_ashrrev_i32_e32 v26, 2, v11
	v_and_b32_e32 v34, 0xffffffc0, v26
	v_add_u32_e32 v26, s26, v34
	v_lshlrev_b32_e32 v11, 6, v11
	v_ashrrev_i32_e32 v27, 31, v26
	v_and_or_b32 v11, v11, s82, v158
	v_lshlrev_b64 v[26:27], 15, v[26:27]
	v_lshl_add_u64 v[26:27], s[66:67], 0, v[26:27]
	v_lshlrev_b32_e32 v142, 1, v11
	v_lshl_add_u64 v[26:27], v[26:27], 0, v[142:143]
	v_add_u32_e32 v11, 0x80, v166
	s_waitcnt vmcnt(0)
	v_lshlrev_b32_e32 v28, 16, v12
	v_and_b32_e32 v29, 0xffff0000, v12
	v_lshlrev_b32_e32 v12, 16, v13
	v_and_b32_e32 v13, 0xffff0000, v13
	v_lshlrev_b32_e32 v30, 16, v14
	v_and_b32_e32 v31, 0xffff0000, v14
	v_lshlrev_b32_e32 v14, 16, v15
	v_and_b32_e32 v15, 0xffff0000, v15
	v_pk_mul_f32 v[32:33], v[96:97], v[12:13]
	v_pk_mul_f32 v[12:13], v[94:95], v[28:29]
	v_pk_mul_f32 v[28:29], v[92:93], v[14:15]
	v_pk_mul_f32 v[14:15], v[90:91], v[30:31]
	v_cvt_pk_bf16_f32 v12, v12, v13
	v_cvt_pk_bf16_f32 v13, v32, v33
	v_cvt_pk_bf16_f32 v14, v14, v15
	v_cvt_pk_bf16_f32 v15, v28, v29
	global_store_dwordx4 v[26:27], v[12:15], off sc1
	global_load_dwordx4 v[12:15], v[16:17], off
	v_add_u32_e32 v26, v34, v10
	v_ashrrev_i32_e32 v27, 31, v26
	v_lshlrev_b64 v[26:27], 15, v[26:27]
	v_mad_i64_i32 v[16:17], s[48:49], v11, s78, v[132:133]
	v_lshl_add_u64 v[26:27], s[66:67], 0, v[26:27]
	v_lshl_add_u64 v[16:17], v[16:17], 0, s[8:9]
	v_lshl_add_u64 v[26:27], v[26:27], 0, v[142:143]
	v_lshl_add_u64 v[28:29], v[16:17], 0, v[156:157]
	v_lshl_add_u64 v[16:17], v[16:17], 0, v[130:131]
	s_waitcnt vmcnt(0)
	v_lshlrev_b32_e32 v30, 16, v12
	v_and_b32_e32 v31, 0xffff0000, v12
	v_lshlrev_b32_e32 v12, 16, v13
	v_and_b32_e32 v13, 0xffff0000, v13
	v_lshlrev_b32_e32 v32, 16, v14
	v_and_b32_e32 v33, 0xffff0000, v14
	v_lshlrev_b32_e32 v14, 16, v15
	v_and_b32_e32 v15, 0xffff0000, v15
	v_pk_mul_f32 v[34:35], v[112:113], v[12:13]
	v_pk_mul_f32 v[12:13], v[110:111], v[30:31]
	v_pk_mul_f32 v[30:31], v[108:109], v[14:15]
	v_pk_mul_f32 v[14:15], v[106:107], v[32:33]
	v_cvt_pk_bf16_f32 v12, v12, v13
	v_cvt_pk_bf16_f32 v13, v34, v35
	v_cvt_pk_bf16_f32 v14, v14, v15
	v_cvt_pk_bf16_f32 v15, v30, v31
	global_store_dwordx4 v[26:27], v[12:15], off sc1
	global_load_dwordx4 v[12:15], v[28:29], off
	v_ashrrev_i32_e32 v26, 2, v11
	v_and_b32_e32 v34, 0xffffffc0, v26
	v_add_u32_e32 v26, s26, v34
	v_lshlrev_b32_e32 v11, 6, v11
	v_ashrrev_i32_e32 v27, 31, v26
	v_and_or_b32 v11, v11, s82, v158
	v_lshlrev_b64 v[26:27], 15, v[26:27]
	v_lshl_add_u64 v[26:27], s[66:67], 0, v[26:27]
	v_lshlrev_b32_e32 v142, 1, v11
	v_lshl_add_u64 v[26:27], v[26:27], 0, v[142:143]
	v_add_u32_e32 v11, 0x90, v166
	s_waitcnt vmcnt(0)
	v_lshlrev_b32_e32 v28, 16, v12
	v_and_b32_e32 v29, 0xffff0000, v12
	v_lshlrev_b32_e32 v12, 16, v13
	v_and_b32_e32 v13, 0xffff0000, v13
	v_lshlrev_b32_e32 v30, 16, v14
	v_and_b32_e32 v31, 0xffff0000, v14
	v_lshlrev_b32_e32 v14, 16, v15
	v_and_b32_e32 v15, 0xffff0000, v15
	v_pk_mul_f32 v[32:33], v[128:129], v[12:13]
	v_pk_mul_f32 v[12:13], v[126:127], v[28:29]
	v_pk_mul_f32 v[28:29], v[124:125], v[14:15]
	v_pk_mul_f32 v[14:15], v[122:123], v[30:31]
	v_cvt_pk_bf16_f32 v12, v12, v13
	v_cvt_pk_bf16_f32 v13, v32, v33
	v_cvt_pk_bf16_f32 v14, v14, v15
	v_cvt_pk_bf16_f32 v15, v28, v29
	global_store_dwordx4 v[26:27], v[12:15], off sc1
	global_load_dwordx4 v[12:15], v[16:17], off
	v_add_u32_e32 v26, v34, v10
	v_ashrrev_i32_e32 v27, 31, v26
	v_lshlrev_b64 v[26:27], 15, v[26:27]
	v_mad_i64_i32 v[16:17], s[48:49], v11, s78, v[132:133]
	v_lshl_add_u64 v[26:27], s[66:67], 0, v[26:27]
	v_lshl_add_u64 v[16:17], v[16:17], 0, s[8:9]
	v_lshl_add_u64 v[26:27], v[26:27], 0, v[142:143]
	v_lshl_add_u64 v[28:29], v[16:17], 0, v[156:157]
	v_lshl_add_u64 v[16:17], v[16:17], 0, v[130:131]
	s_waitcnt vmcnt(0)
; __host__ __device__ __forceinline__ size_t blk(int r, int k, int K) { return (((size_t)((r >> 8) * (K >> 6) + (k >> 6))) << 14) + (size_t)(((r & 255) << 6) + (k & 63)); }
; __device__ __forceinline__ float bflo(unsigned w) { return __uint_as_float(w << 16); }
; __device__ __forceinline__ float bfhi(unsigned w) { return __uint_as_float(w & 0xffff0000u); }
; __device__ __forceinline__ unsigned pk2(float lo, float hi) { f32x2 v = {lo, hi}; bf16x2_t b = __builtin_convertvector(v, bf16x2_t); return __builtin_bit_cast(unsigned, b); }
;     __device__ __forceinline__ void operator()(const f32x4 (&acc)[2][2][4][2], const Unit& u, int wr, int wc, int fr, int fq) const {
;     ...
;             for (int m = 0; m < 4; ++m) { const int row = row0 + ai * HALF + m * 16;
; #pragma unroll
;                 for (int bj = 0; bj < 2; ++bj) { const int c = col0 + bj * HALF; const u32x4 b = *(const u32x4*)(P + (size_t)row * NP + PC_GB + c);
;                     const f32x4 b0 = {bflo(b.x), bfhi(b.x), bflo(b.y), bfhi(b.y)}, b1 = {bflo(b.z), bfhi(b.z), bflo(b.w), bfhi(b.w)};
;                     const f32x4 v0 = acc[ai][bj][m][0] * b0, v1 = acc[ai][bj][m][1] * b1;
;                     u32x4 w; w.x = pk2(v0[0], v0[1]); w.y = pk2(v0[2], v0[3]); w.z = pk2(v1[0], v1[1]); w.w = pk2(v1[2], v1[3]);
;                     *(u32x4*)(MG + blk(row, c, D)) = w; } }
	v_lshlrev_b32_e32 v30, 16, v12
	v_and_b32_e32 v31, 0xffff0000, v12
	v_lshlrev_b32_e32 v12, 16, v13
	v_and_b32_e32 v13, 0xffff0000, v13
	v_lshlrev_b32_e32 v32, 16, v14
	v_and_b32_e32 v33, 0xffff0000, v14
	v_lshlrev_b32_e32 v14, 16, v15
	v_and_b32_e32 v15, 0xffff0000, v15
	v_pk_mul_f32 v[34:35], v[120:121], v[12:13]
	v_pk_mul_f32 v[12:13], v[118:119], v[30:31]
	v_pk_mul_f32 v[30:31], v[116:117], v[14:15]
	v_pk_mul_f32 v[14:15], v[114:115], v[32:33]
	v_cvt_pk_bf16_f32 v12, v12, v13
	v_cvt_pk_bf16_f32 v13, v34, v35
	v_cvt_pk_bf16_f32 v14, v14, v15
	v_cvt_pk_bf16_f32 v15, v30, v31
	global_store_dwordx4 v[26:27], v[12:15], off sc1
	global_load_dwordx4 v[12:15], v[28:29], off
	v_ashrrev_i32_e32 v26, 2, v11
	v_and_b32_e32 v34, 0xffffffc0, v26
	v_add_u32_e32 v26, s26, v34
	v_lshlrev_b32_e32 v11, 6, v11
	v_ashrrev_i32_e32 v27, 31, v26
	v_and_or_b32 v11, v11, s82, v158
	v_lshlrev_b64 v[26:27], 15, v[26:27]
	v_lshl_add_u64 v[26:27], s[66:67], 0, v[26:27]
	v_lshlrev_b32_e32 v142, 1, v11
	v_lshl_add_u64 v[26:27], v[26:27], 0, v[142:143]
	v_add_u32_e32 v11, 0xa0, v166
	s_waitcnt vmcnt(0)
	v_lshlrev_b32_e32 v28, 16, v12
	v_and_b32_e32 v29, 0xffff0000, v12
	v_lshlrev_b32_e32 v12, 16, v13
	v_and_b32_e32 v13, 0xffff0000, v13
	v_lshlrev_b32_e32 v30, 16, v14
	v_and_b32_e32 v31, 0xffff0000, v14
	v_lshlrev_b32_e32 v14, 16, v15
	v_and_b32_e32 v15, 0xffff0000, v15
	v_pk_mul_f32 v[32:33], v[104:105], v[12:13]
	v_pk_mul_f32 v[12:13], v[102:103], v[28:29]
	v_pk_mul_f32 v[28:29], v[100:101], v[14:15]
	v_pk_mul_f32 v[14:15], v[98:99], v[30:31]
	v_cvt_pk_bf16_f32 v12, v12, v13
	v_cvt_pk_bf16_f32 v13, v32, v33
	v_cvt_pk_bf16_f32 v14, v14, v15
	v_cvt_pk_bf16_f32 v15, v28, v29
	global_store_dwordx4 v[26:27], v[12:15], off sc1
	global_load_dwordx4 v[12:15], v[16:17], off
	v_add_u32_e32 v26, v34, v10
	v_ashrrev_i32_e32 v27, 31, v26
	v_lshlrev_b64 v[26:27], 15, v[26:27]
	v_mad_i64_i32 v[16:17], s[48:49], v11, s78, v[132:133]
	v_lshl_add_u64 v[26:27], s[66:67], 0, v[26:27]
	v_lshl_add_u64 v[16:17], v[16:17], 0, s[8:9]
	v_lshl_add_u64 v[26:27], v[26:27], 0, v[142:143]
	v_lshl_add_u64 v[28:29], v[16:17], 0, v[156:157]
	v_lshl_add_u64 v[16:17], v[16:17], 0, v[130:131]
	s_waitcnt vmcnt(0)
	v_lshlrev_b32_e32 v30, 16, v12
	v_and_b32_e32 v31, 0xffff0000, v12
	v_lshlrev_b32_e32 v12, 16, v13
	v_and_b32_e32 v13, 0xffff0000, v13
	v_lshlrev_b32_e32 v32, 16, v14
	v_and_b32_e32 v33, 0xffff0000, v14
	v_lshlrev_b32_e32 v14, 16, v15
	v_and_b32_e32 v15, 0xffff0000, v15
	v_pk_mul_f32 v[34:35], v[80:81], v[12:13]
	v_pk_mul_f32 v[12:13], v[78:79], v[30:31]
	v_pk_mul_f32 v[30:31], v[76:77], v[14:15]
	v_pk_mul_f32 v[14:15], v[74:75], v[32:33]
	v_cvt_pk_bf16_f32 v12, v12, v13
	v_cvt_pk_bf16_f32 v13, v34, v35
	v_cvt_pk_bf16_f32 v14, v14, v15
	v_cvt_pk_bf16_f32 v15, v30, v31
	global_store_dwordx4 v[26:27], v[12:15], off sc1
	global_load_dwordx4 v[12:15], v[28:29], off
	v_ashrrev_i32_e32 v26, 2, v11
	v_and_b32_e32 v34, 0xffffffc0, v26
	v_add_u32_e32 v26, s26, v34
	v_lshlrev_b32_e32 v11, 6, v11
	v_ashrrev_i32_e32 v27, 31, v26
	v_and_or_b32 v11, v11, s82, v158
	v_lshlrev_b64 v[26:27], 15, v[26:27]
	v_lshl_add_u64 v[26:27], s[66:67], 0, v[26:27]
	v_lshlrev_b32_e32 v142, 1, v11
	v_lshl_add_u64 v[26:27], v[26:27], 0, v[142:143]
	v_add_u32_e32 v11, 0xb0, v166
	s_waitcnt vmcnt(0)
	v_lshlrev_b32_e32 v28, 16, v12
	v_and_b32_e32 v29, 0xffff0000, v12
	v_lshlrev_b32_e32 v12, 16, v13
	v_and_b32_e32 v13, 0xffff0000, v13
	v_lshlrev_b32_e32 v30, 16, v14
	v_and_b32_e32 v31, 0xffff0000, v14
	v_lshlrev_b32_e32 v14, 16, v15
	v_and_b32_e32 v15, 0xffff0000, v15
	v_pk_mul_f32 v[32:33], v[64:65], v[12:13]
	v_pk_mul_f32 v[12:13], v[62:63], v[28:29]
	v_pk_mul_f32 v[28:29], v[60:61], v[14:15]
	v_pk_mul_f32 v[14:15], v[58:59], v[30:31]
	v_cvt_pk_bf16_f32 v12, v12, v13
	v_cvt_pk_bf16_f32 v13, v32, v33
	v_cvt_pk_bf16_f32 v14, v14, v15
	v_cvt_pk_bf16_f32 v15, v28, v29
	global_store_dwordx4 v[26:27], v[12:15], off sc1
	global_load_dwordx4 v[12:15], v[16:17], off
	v_add_u32_e32 v26, v34, v10
	v_ashrrev_i32_e32 v27, 31, v26
	v_lshlrev_b64 v[26:27], 15, v[26:27]
	v_mad_i64_i32 v[16:17], s[48:49], v11, s78, v[132:133]
	v_lshl_add_u64 v[26:27], s[66:67], 0, v[26:27]
	v_lshl_add_u64 v[16:17], v[16:17], 0, s[8:9]
	v_lshl_add_u64 v[26:27], v[26:27], 0, v[142:143]
	v_lshl_add_u64 v[28:29], v[16:17], 0, v[156:157]
	v_lshl_add_u64 v[16:17], v[16:17], 0, v[130:131]
	s_waitcnt vmcnt(0)
	v_lshlrev_b32_e32 v30, 16, v12
	v_and_b32_e32 v31, 0xffff0000, v12
	v_lshlrev_b32_e32 v12, 16, v13
	v_and_b32_e32 v13, 0xffff0000, v13
	v_lshlrev_b32_e32 v32, 16, v14
	v_and_b32_e32 v33, 0xffff0000, v14
	v_lshlrev_b32_e32 v14, 16, v15
	v_and_b32_e32 v15, 0xffff0000, v15
	v_pk_mul_f32 v[34:35], v[48:49], v[12:13]
	v_pk_mul_f32 v[12:13], v[46:47], v[30:31]
	v_pk_mul_f32 v[30:31], v[44:45], v[14:15]
	v_pk_mul_f32 v[14:15], v[42:43], v[32:33]
	v_cvt_pk_bf16_f32 v12, v12, v13
	v_cvt_pk_bf16_f32 v13, v34, v35
	v_cvt_pk_bf16_f32 v14, v14, v15
	v_cvt_pk_bf16_f32 v15, v30, v31
	global_store_dwordx4 v[26:27], v[12:15], off sc1
	global_load_dwordx4 v[12:15], v[28:29], off
	v_ashrrev_i32_e32 v26, 2, v11
	v_and_b32_e32 v32, 0xffffffc0, v26
	v_add_u32_e32 v26, s26, v32
	v_lshlrev_b32_e32 v11, 6, v11
	v_ashrrev_i32_e32 v27, 31, v26
	v_and_or_b32 v11, v11, s82, v158
	v_lshlrev_b64 v[26:27], 15, v[26:27]
	v_lshl_add_u64 v[26:27], s[66:67], 0, v[26:27]
	v_lshlrev_b32_e32 v142, 1, v11
	v_lshl_add_u64 v[26:27], v[26:27], 0, v[142:143]
	v_add_u32_e32 v10, v32, v10
	v_ashrrev_i32_e32 v11, 31, v10
	v_lshlrev_b64 v[10:11], 15, v[10:11]
	v_lshl_add_u64 v[10:11], s[66:67], 0, v[10:11]
	v_lshl_add_u64 v[10:11], v[10:11], 0, v[142:143]
	s_waitcnt vmcnt(0)
	v_lshlrev_b32_e32 v28, 16, v12
	v_and_b32_e32 v29, 0xffff0000, v12
	v_lshlrev_b32_e32 v12, 16, v13
	v_and_b32_e32 v13, 0xffff0000, v13
	v_lshlrev_b32_e32 v30, 16, v14
	v_and_b32_e32 v31, 0xffff0000, v14
	v_lshlrev_b32_e32 v14, 16, v15
	v_and_b32_e32 v15, 0xffff0000, v15
	v_pk_mul_f32 v[24:25], v[24:25], v[12:13]
	v_pk_mul_f32 v[12:13], v[22:23], v[28:29]
	v_pk_mul_f32 v[20:21], v[20:21], v[14:15]
	v_pk_mul_f32 v[14:15], v[18:19], v[30:31]
	v_cvt_pk_bf16_f32 v12, v12, v13
	v_cvt_pk_bf16_f32 v13, v24, v25
	v_cvt_pk_bf16_f32 v14, v14, v15
	v_cvt_pk_bf16_f32 v15, v20, v21
	global_store_dwordx4 v[26:27], v[12:15], off sc1
	global_load_dwordx4 v[12:15], v[16:17], off
	s_waitcnt vmcnt(0)
	v_lshlrev_b32_e32 v16, 16, v12
	v_and_b32_e32 v17, 0xffff0000, v12
	v_lshlrev_b32_e32 v12, 16, v13
	v_and_b32_e32 v13, 0xffff0000, v13
	v_lshlrev_b32_e32 v18, 16, v14
	v_and_b32_e32 v19, 0xffff0000, v14
	v_lshlrev_b32_e32 v14, 16, v15
	v_and_b32_e32 v15, 0xffff0000, v15
	v_pk_mul_f32 v[8:9], v[8:9], v[12:13]
	v_pk_mul_f32 v[6:7], v[6:7], v[16:17]
	v_pk_mul_f32 v[12:13], v[4:5], v[14:15]
	v_pk_mul_f32 v[4:5], v[2:3], v[18:19]
	v_cvt_pk_bf16_f32 v2, v6, v7
	v_cvt_pk_bf16_f32 v3, v8, v9
	v_cvt_pk_bf16_f32 v4, v4, v5
	v_cvt_pk_bf16_f32 v5, v12, v13
	global_store_dwordx4 v[10:11], v[2:5], off sc1
	s_cbranch_vccnz .LBB0_674
	s_andn2_b64 vcc, exec, s[6:7]
	s_cbranch_vccnz .LBB0_673
	s_barrier
	s_branch .LBB0_673

; __host__ __device__ __forceinline__ size_t blk(int r, int k, int K) { return (((size_t)((r >> 8) * (K >> 6) + (k >> 6))) << 14) + (size_t)(((r & 255) << 6) + (k & 63)); }
; __device__ __forceinline__ float bflo(unsigned w) { return __uint_as_float(w << 16); }
; __device__ __forceinline__ float bfhi(unsigned w) { return __uint_as_float(w & 0xffff0000u); }
; __device__ __forceinline__ unsigned pk2(float lo, float hi) { f32x2 v = {lo, hi}; bf16x2_t b = __builtin_convertvector(v, bf16x2_t); return __builtin_bit_cast(unsigned, b); }
;     __device__ __forceinline__ void operator()(const f32x4 (&acc)[2][2][4][2], const Unit& u, int wr, int wc, int fr, int fq) const {
;     ...
;             for (int m = 0; m < 4; ++m) { const int row = row0 + ai * HALF + m * 16; const size_t off = (size_t)row * D + col0; float s = 0.f;
; #pragma unroll
;                 for (int bj = 0; bj < 2; ++bj) {
;                     f32x4 v0, v1;
;                     if (MODE == 0) { v0 = *(const f32x4*)(base + off + bj * HALF); v1 = *(const f32x4*)(base + off + bj * HALF + 4); }
;                     else { const u32x4 r = *(const u32x4*)(bb + blk(row, col0 + bj * HALF, D)); v0 = (f32x4){bflo(r.x), bfhi(r.x), bflo(r.y), bfhi(r.y)}; v1 = (f32x4){bflo(r.z), bfhi(r.z), bflo(r.w), bfhi(r.w)}; }
;                     v0 += acc[ai][bj][m][0] * alpha; v1 += acc[ai][bj][m][1] * alpha;
;                     if (MODE == 2) { *(f32x4*)(out + off + bj * HALF) = v0; *(f32x4*)(out + off + bj * HALF + 4) = v1; }
;                     else {
;                         s += (v0[0] * v0[0] + v0[1] * v0[1]) + (v0[2] * v0[2] + v0[3] * v0[3]) + (v1[0] * v1[0] + v1[1] * v1[1]) + (v1[2] * v1[2] + v1[3] * v1[3]);
;                         u32x4 w; w.x = pk2(v0[0], v0[1]); w.y = pk2(v0[2], v0[3]); w.z = pk2(v1[0], v1[1]); w.w = pk2(v1[2], v1[3]); *(u32x4*)(xb + blk(row, col0 + bj * HALF, D)) = w; } }
;                 if (MODE != 2) { s += __shfl_xor(s, 16); s += __shfl_xor(s, 32); if (fq == 0) unsafeAtomicAdd(ssq + row, s); } }
.LBB0_760:
	s_lshl_b32 s15, s40, 8
	s_add_i32 s15, s15, s35
	s_lshl_b32 s17, s38, 8
	v_or_b32_e32 v146, s15, v195
	s_or_b32 s17, s17, s56
	s_ashr_i32 s15, s15, 2
	s_and_b32 s40, s15, 0xffffffc0
	s_ashr_i32 s15, s17, 6
	s_add_i32 s38, s40, s15
	v_lshlrev_b32_e32 v147, 6, v146
	s_ashr_i32 s39, s38, 31
	v_and_or_b32 v147, v147, s62, v148
	s_lshl_b64 s[38:39], s[38:39], 14
	v_or_b32_e32 v154, s38, v147
	v_mov_b32_e32 v155, s39
	v_lshlrev_b64 v[158:159], 1, v[154:155]
	v_lshl_add_u64 v[154:155], s[42:43], 0, v[158:159]
	v_lshl_add_u64 v[176:177], s[42:43], 0, v[158:159]
	global_load_dwordx4 v[154:157], v[154:155], off
	s_mov_b32 s98, 0x1000
	s_mov_b32 s99, 0
	s_mov_b32 s100, 0x10000
	s_mov_b32 s101, 0
	v_lshl_add_u64 v[222:223], v[176:177], 0, s[100:101]
	s_mov_b32 s100, 0x3000
	global_load_dwordx4 v[168:171], v[222:223], off
	global_load_dwordx4 v[172:175], v[176:177], off offset:2048
	global_load_dwordx4 v[180:183], v[222:223], off offset:2048
	v_lshl_add_u64 v[176:177], v[176:177], 0, s[98:99]
	v_lshl_add_u64 v[222:223], v[222:223], 0, s[98:99]
	global_load_dwordx4 v[184:187], v[176:177], off
	global_load_dwordx4 v[188:191], v[222:223], off
	global_load_dwordx4 v[198:201], v[176:177], off offset:2048
	global_load_dwordx4 v[202:205], v[222:223], off offset:2048
	v_lshl_add_u64 v[176:177], v[176:177], 0, s[100:101]
	v_lshl_add_u64 v[222:223], v[222:223], 0, s[100:101]
	global_load_dwordx4 v[206:209], v[176:177], off
	global_load_dwordx4 v[210:213], v[222:223], off
	global_load_dwordx4 v[214:217], v[176:177], off offset:2048
	global_load_dwordx4 v[218:221], v[222:223], off offset:2048
	s_or_b32 s17, s15, 2
	s_add_i32 s40, s40, s17
	s_ashr_i32 s41, s40, 31
	s_lshl_b64 s[40:41], s[40:41], 14
	v_or_b32_e32 v160, s40, v147
	v_mov_b32_e32 v161, s41
	v_lshlrev_b64 v[160:161], 1, v[160:161]
	v_lshl_add_u64 v[158:159], s[18:19], 0, v[158:159]
	v_lshl_add_u64 v[162:163], s[42:43], 0, v[160:161]
	v_xor_b32_e32 v147, 32, v152
	s_waitcnt vmcnt(0)
	v_lshlrev_b32_e32 v164, 16, v154
	v_and_b32_e32 v165, 0xffff0000, v154
	v_lshlrev_b32_e32 v154, 16, v155
	v_and_b32_e32 v155, 0xffff0000, v155
	v_lshlrev_b32_e32 v166, 16, v156
	v_and_b32_e32 v167, 0xffff0000, v156
	v_lshlrev_b32_e32 v156, 16, v157
	v_and_b32_e32 v157, 0xffff0000, v157
	v_pk_add_f32 v[128:129], v[128:129], v[154:155]
	v_pk_add_f32 v[154:155], v[126:127], v[164:165]
	v_pk_add_f32 v[156:157], v[124:125], v[156:157]
	v_pk_add_f32 v[164:165], v[122:123], v[166:167]
	v_cvt_pk_bf16_f32 v122, v154, v155
	v_cvt_pk_bf16_f32 v123, v128, v129
	v_cvt_pk_bf16_f32 v124, v164, v165
	v_cvt_pk_bf16_f32 v125, v156, v157
	global_store_dwordx4 v[158:159], v[122:125], off sc1
	s_nop 0
	v_mul_f32_e32 v153, v155, v155
	v_mul_f32_e32 v129, v129, v129
	v_mul_f32_e32 v155, v165, v165
	v_fmac_f32_e32 v153, v154, v154
	v_fmac_f32_e32 v129, v128, v128
	v_mul_f32_e32 v157, v157, v157
	v_fmac_f32_e32 v155, v164, v164
	v_add_f32_e32 v128, v153, v129
	v_fmac_f32_e32 v157, v156, v156
	v_add_f32_e32 v128, v155, v128
	v_add_f32_e32 v153, v157, v128
	v_and_b32_e32 v123, 64, v152
	v_xor_b32_e32 v122, 16, v152
	v_add_u32_e32 v123, 64, v123
	v_cmp_lt_i32_e32 vcc, v122, v123
	v_mov_b32_e32 v124, v168
	v_mov_b32_e32 v125, v169
	v_mov_b32_e32 v126, v170
	v_mov_b32_e32 v127, v171
	v_lshlrev_b32_e32 v128, 16, v124
	v_and_b32_e32 v129, 0xffff0000, v124
	v_lshlrev_b32_e32 v124, 16, v125
	v_and_b32_e32 v125, 0xffff0000, v125
	v_lshlrev_b32_e32 v154, 16, v126
	v_and_b32_e32 v155, 0xffff0000, v126
	v_lshlrev_b32_e32 v126, 16, v127
	v_and_b32_e32 v127, 0xffff0000, v127
	v_pk_add_f32 v[120:121], v[120:121], v[124:125]
	v_pk_add_f32 v[118:119], v[118:119], v[128:129]
	v_pk_add_f32 v[124:125], v[116:117], v[126:127]
	v_pk_add_f32 v[126:127], v[114:115], v[154:155]
	v_mul_f32_e32 v114, v119, v119
	v_mul_f32_e32 v115, v121, v121
	v_mul_f32_e32 v116, v127, v127
	v_fmac_f32_e32 v114, v118, v118
	v_fmac_f32_e32 v115, v120, v120
	v_mul_f32_e32 v117, v125, v125
	v_fmac_f32_e32 v116, v126, v126
	v_add_f32_e32 v114, v114, v115
	v_fmac_f32_e32 v117, v124, v124
	v_add_f32_e32 v114, v116, v114
	v_cndmask_b32_e32 v122, v152, v122, vcc
	v_add_f32_e32 v114, v117, v114
	v_lshlrev_b32_e32 v122, 2, v122
	v_add_f32_e32 v114, v153, v114
	ds_bpermute_b32 v115, v122, v114
	v_cmp_lt_i32_e32 vcc, v147, v123
	v_cvt_pk_bf16_f32 v118, v118, v119
	v_cvt_pk_bf16_f32 v119, v120, v121
	v_cndmask_b32_e32 v116, v152, v147, vcc
	v_lshlrev_b32_e32 v116, 2, v116
	s_waitcnt lgkmcnt(0)
	v_add_f32_e32 v114, v114, v115
	ds_bpermute_b32 v115, v116, v114
	v_cvt_pk_bf16_f32 v120, v126, v127
	v_cvt_pk_bf16_f32 v121, v124, v125
	v_lshl_add_u64 v[124:125], s[18:19], 0, v[160:161]
	global_store_dwordx4 v[124:125], v[118:121], off sc1
	s_and_saveexec_b64 s[44:45], s[0:1]
	s_cbranch_execz .LBB0_762
	v_ashrrev_i32_e32 v147, 31, v146
	v_lshl_add_u64 v[118:119], v[146:147], 2, s[10:11]
	s_waitcnt lgkmcnt(0)
	v_add_f32_e32 v114, v114, v115
	global_atomic_add_f32 v[118:119], v114, off
; __host__ __device__ __forceinline__ size_t blk(int r, int k, int K) { return (((size_t)((r >> 8) * (K >> 6) + (k >> 6))) << 14) + (size_t)(((r & 255) << 6) + (k & 63)); }
; __device__ __forceinline__ float bflo(unsigned w) { return __uint_as_float(w << 16); }
; __device__ __forceinline__ float bfhi(unsigned w) { return __uint_as_float(w & 0xffff0000u); }
; __device__ __forceinline__ unsigned pk2(float lo, float hi) { f32x2 v = {lo, hi}; bf16x2_t b = __builtin_convertvector(v, bf16x2_t); return __builtin_bit_cast(unsigned, b); }
;     __device__ __forceinline__ void operator()(const f32x4 (&acc)[2][2][4][2], const Unit& u, int wr, int wc, int fr, int fq) const {
;     ...
;             for (int m = 0; m < 4; ++m) { const int row = row0 + ai * HALF + m * 16; const size_t off = (size_t)row * D + col0; float s = 0.f;
; #pragma unroll
;                 for (int bj = 0; bj < 2; ++bj) {
;                     f32x4 v0, v1;
;                     if (MODE == 0) { v0 = *(const f32x4*)(base + off + bj * HALF); v1 = *(const f32x4*)(base + off + bj * HALF + 4); }
;                     else { const u32x4 r = *(const u32x4*)(bb + blk(row, col0 + bj * HALF, D)); v0 = (f32x4){bflo(r.x), bfhi(r.x), bflo(r.y), bfhi(r.y)}; v1 = (f32x4){bflo(r.z), bfhi(r.z), bflo(r.w), bfhi(r.w)}; }
;                     v0 += acc[ai][bj][m][0] * alpha; v1 += acc[ai][bj][m][1] * alpha;
;                     if (MODE == 2) { *(f32x4*)(out + off + bj * HALF) = v0; *(f32x4*)(out + off + bj * HALF + 4) = v1; }
;                     else {
;                         s += (v0[0] * v0[0] + v0[1] * v0[1]) + (v0[2] * v0[2] + v0[3] * v0[3]) + (v1[0] * v1[0] + v1[1] * v1[1]) + (v1[2] * v1[2] + v1[3] * v1[3]);
;                         u32x4 w; w.x = pk2(v0[0], v0[1]); w.y = pk2(v0[2], v0[3]); w.z = pk2(v1[0], v1[1]); w.w = pk2(v1[2], v1[3]); *(u32x4*)(xb + blk(row, col0 + bj * HALF, D)) = w; } }
;                 if (MODE != 2) { s += __shfl_xor(s, 16); s += __shfl_xor(s, 32); if (fq == 0) unsafeAtomicAdd(ssq + row, s); } }
.LBB0_762:
	s_or_b64 exec, exec, s[44:45]
	v_or_b32_e32 v114, 16, v146
	s_waitcnt lgkmcnt(0)
	v_lshlrev_b32_e32 v115, 6, v114
	v_and_or_b32 v115, v115, s63, v148
	v_or_b32_e32 v118, s38, v115
	v_mov_b32_e32 v119, s39
	v_lshlrev_b64 v[124:125], 1, v[118:119]
	v_lshl_add_u64 v[118:119], s[42:43], 0, v[124:125]
	s_nop 0
	v_mov_b32_e32 v127, s41
	v_or_b32_e32 v126, s40, v115
	v_lshlrev_b64 v[126:127], 1, v[126:127]
	v_lshl_add_u64 v[124:125], s[18:19], 0, v[124:125]
	v_lshl_add_u64 v[128:129], s[42:43], 0, v[126:127]
	v_mov_b32_e32 v118, v172
	v_mov_b32_e32 v119, v173
	v_mov_b32_e32 v120, v174
	v_mov_b32_e32 v121, v175
	v_lshlrev_b32_e32 v154, 16, v118
	v_and_b32_e32 v155, 0xffff0000, v118
	v_lshlrev_b32_e32 v118, 16, v119
	v_and_b32_e32 v119, 0xffff0000, v119
	v_lshlrev_b32_e32 v156, 16, v120
	v_and_b32_e32 v157, 0xffff0000, v120
	v_lshlrev_b32_e32 v120, 16, v121
	v_and_b32_e32 v121, 0xffff0000, v121
	v_pk_add_f32 v[112:113], v[112:113], v[118:119]
	v_pk_add_f32 v[110:111], v[110:111], v[154:155]
	v_pk_add_f32 v[118:119], v[108:109], v[120:121]
	v_pk_add_f32 v[120:121], v[106:107], v[156:157]
	v_cvt_pk_bf16_f32 v106, v110, v111
	v_cvt_pk_bf16_f32 v107, v112, v113
	v_cvt_pk_bf16_f32 v108, v120, v121
	v_cvt_pk_bf16_f32 v109, v118, v119
	global_store_dwordx4 v[124:125], v[106:109], off sc1
	s_nop 0
	v_mul_f32_e32 v111, v111, v111
	v_mul_f32_e32 v113, v113, v113
	v_mul_f32_e32 v115, v121, v121
	v_fmac_f32_e32 v111, v110, v110
	v_fmac_f32_e32 v113, v112, v112
	v_mul_f32_e32 v117, v119, v119
	v_fmac_f32_e32 v115, v120, v120
	v_add_f32_e32 v110, v111, v113
	v_fmac_f32_e32 v117, v118, v118
	v_add_f32_e32 v110, v115, v110
	v_add_f32_e32 v115, v117, v110
	v_mov_b32_e32 v106, v180
	v_mov_b32_e32 v107, v181
	v_mov_b32_e32 v108, v182
	v_mov_b32_e32 v109, v183
	v_lshlrev_b32_e32 v110, 16, v106
	v_and_b32_e32 v111, 0xffff0000, v106
	v_lshlrev_b32_e32 v106, 16, v107
	v_and_b32_e32 v107, 0xffff0000, v107
	v_lshlrev_b32_e32 v112, 16, v108
	v_and_b32_e32 v113, 0xffff0000, v108
	v_lshlrev_b32_e32 v108, 16, v109
	v_and_b32_e32 v109, 0xffff0000, v109
	v_pk_add_f32 v[104:105], v[104:105], v[106:107]
	v_pk_add_f32 v[102:103], v[102:103], v[110:111]
	v_pk_add_f32 v[106:107], v[100:101], v[108:109]
	v_pk_add_f32 v[108:109], v[98:99], v[112:113]
	v_mul_f32_e32 v98, v103, v103
	v_mul_f32_e32 v99, v105, v105
	v_mul_f32_e32 v100, v109, v109
	v_fmac_f32_e32 v98, v102, v102
	v_fmac_f32_e32 v99, v104, v104
	v_mul_f32_e32 v101, v107, v107
	v_fmac_f32_e32 v100, v108, v108
	v_add_f32_e32 v98, v98, v99
	v_add_f32_e32 v98, v100, v98
	v_fmac_f32_e32 v101, v106, v106
	v_add_f32_e32 v98, v101, v98
	v_add_f32_e32 v98, v115, v98
	ds_bpermute_b32 v99, v122, v98
	v_cvt_pk_bf16_f32 v100, v102, v103
	v_cvt_pk_bf16_f32 v101, v104, v105
	v_cvt_pk_bf16_f32 v102, v108, v109
	v_cvt_pk_bf16_f32 v103, v106, v107
	s_waitcnt lgkmcnt(0)
	v_add_f32_e32 v98, v98, v99
	ds_bpermute_b32 v99, v116, v98
	v_lshl_add_u64 v[104:105], s[18:19], 0, v[126:127]
	global_store_dwordx4 v[104:105], v[100:103], off sc1
	s_and_saveexec_b64 s[44:45], s[0:1]
	s_cbranch_execz .LBB0_764
	v_ashrrev_i32_e32 v115, 31, v114
	v_lshl_add_u64 v[100:101], v[114:115], 2, s[10:11]
	s_waitcnt lgkmcnt(0)
	v_add_f32_e32 v98, v98, v99
	global_atomic_add_f32 v[100:101], v98, off
.LBB0_764:
	s_or_b64 exec, exec, s[44:45]
	v_or_b32_e32 v98, 32, v146
	s_waitcnt lgkmcnt(0)
	v_lshlrev_b32_e32 v99, 6, v98
	v_and_or_b32 v99, v99, s64, v148
	v_or_b32_e32 v100, s38, v99
	v_mov_b32_e32 v101, s39
	v_lshlrev_b64 v[104:105], 1, v[100:101]
	v_lshl_add_u64 v[100:101], s[42:43], 0, v[104:105]
	s_nop 0
	v_mov_b32_e32 v107, s41
	v_or_b32_e32 v106, s40, v99
	v_lshlrev_b64 v[106:107], 1, v[106:107]
	v_lshl_add_u64 v[104:105], s[18:19], 0, v[104:105]
	v_lshl_add_u64 v[108:109], s[42:43], 0, v[106:107]
	v_mov_b32_e32 v100, v184
	v_mov_b32_e32 v101, v185
	v_mov_b32_e32 v102, v186
	v_mov_b32_e32 v103, v187
	v_lshlrev_b32_e32 v110, 16, v100
	v_and_b32_e32 v111, 0xffff0000, v100
	v_lshlrev_b32_e32 v100, 16, v101
	v_and_b32_e32 v101, 0xffff0000, v101
	v_lshlrev_b32_e32 v112, 16, v102
	v_and_b32_e32 v113, 0xffff0000, v102
	v_lshlrev_b32_e32 v102, 16, v103
	v_and_b32_e32 v103, 0xffff0000, v103
	v_pk_add_f32 v[96:97], v[96:97], v[100:101]
	v_pk_add_f32 v[94:95], v[94:95], v[110:111]
	v_pk_add_f32 v[100:101], v[92:93], v[102:103]
	v_pk_add_f32 v[102:103], v[90:91], v[112:113]
	v_cvt_pk_bf16_f32 v90, v94, v95
	v_cvt_pk_bf16_f32 v91, v96, v97
	v_cvt_pk_bf16_f32 v92, v102, v103
	v_cvt_pk_bf16_f32 v93, v100, v101
	global_store_dwordx4 v[104:105], v[90:93], off sc1
	s_nop 0
	v_mul_f32_e32 v95, v95, v95
	v_mul_f32_e32 v97, v97, v97
	v_mul_f32_e32 v99, v103, v103
	v_fmac_f32_e32 v95, v94, v94
	v_fmac_f32_e32 v97, v96, v96
	v_mul_f32_e32 v101, v101, v101
	v_fmac_f32_e32 v99, v102, v102
	v_add_f32_e32 v94, v95, v97
	v_fmac_f32_e32 v101, v100, v100
	v_add_f32_e32 v94, v99, v94
	v_add_f32_e32 v99, v101, v94
	v_mov_b32_e32 v90, v188
	v_mov_b32_e32 v91, v189
	v_mov_b32_e32 v92, v190
	v_mov_b32_e32 v93, v191
	v_lshl_add_u64 v[176:177], v[176:177], 0, s[98:99]
	v_lshl_add_u64 v[222:223], v[222:223], 0, s[98:99]
	global_load_dwordx4 v[168:171], v[176:177], off
	global_load_dwordx4 v[172:175], v[222:223], off
	global_load_dwordx4 v[180:183], v[176:177], off offset:2048
	global_load_dwordx4 v[184:187], v[222:223], off offset:2048
	v_lshlrev_b32_e32 v94, 16, v90
	v_and_b32_e32 v95, 0xffff0000, v90
	v_lshlrev_b32_e32 v90, 16, v91
	v_and_b32_e32 v91, 0xffff0000, v91
	v_lshlrev_b32_e32 v96, 16, v92
	v_and_b32_e32 v97, 0xffff0000, v92
	v_lshlrev_b32_e32 v92, 16, v93
	v_and_b32_e32 v93, 0xffff0000, v93
	v_pk_add_f32 v[88:89], v[88:89], v[90:91]
	v_pk_add_f32 v[86:87], v[86:87], v[94:95]
	v_pk_add_f32 v[90:91], v[84:85], v[92:93]
	v_pk_add_f32 v[92:93], v[82:83], v[96:97]
	v_mul_f32_e32 v82, v87, v87
	v_mul_f32_e32 v83, v89, v89
	v_mul_f32_e32 v84, v93, v93
	v_fmac_f32_e32 v82, v86, v86
	v_fmac_f32_e32 v83, v88, v88
	v_mul_f32_e32 v85, v91, v91
	v_fmac_f32_e32 v84, v92, v92
	v_add_f32_e32 v82, v82, v83
	v_add_f32_e32 v82, v84, v82
	v_fmac_f32_e32 v85, v90, v90
	v_add_f32_e32 v82, v85, v82
	v_add_f32_e32 v82, v99, v82
	ds_bpermute_b32 v83, v122, v82
	v_cvt_pk_bf16_f32 v84, v86, v87
	v_cvt_pk_bf16_f32 v85, v88, v89
	v_cvt_pk_bf16_f32 v86, v92, v93
	v_cvt_pk_bf16_f32 v87, v90, v91
	s_waitcnt lgkmcnt(0)
	v_add_f32_e32 v82, v82, v83
	ds_bpermute_b32 v83, v116, v82
	v_lshl_add_u64 v[88:89], s[18:19], 0, v[106:107]
	global_store_dwordx4 v[88:89], v[84:87], off sc1
	s_and_saveexec_b64 s[44:45], s[0:1]
	s_cbranch_execz .LBB0_766
	v_ashrrev_i32_e32 v99, 31, v98
	v_lshl_add_u64 v[84:85], v[98:99], 2, s[10:11]
	s_waitcnt lgkmcnt(0)
	v_add_f32_e32 v82, v82, v83
	global_atomic_add_f32 v[84:85], v82, off
; __host__ __device__ __forceinline__ size_t blk(int r, int k, int K) { return (((size_t)((r >> 8) * (K >> 6) + (k >> 6))) << 14) + (size_t)(((r & 255) << 6) + (k & 63)); }
; __device__ __forceinline__ float bflo(unsigned w) { return __uint_as_float(w << 16); }
; __device__ __forceinline__ float bfhi(unsigned w) { return __uint_as_float(w & 0xffff0000u); }
; __device__ __forceinline__ unsigned pk2(float lo, float hi) { f32x2 v = {lo, hi}; bf16x2_t b = __builtin_convertvector(v, bf16x2_t); return __builtin_bit_cast(unsigned, b); }
;     __device__ __forceinline__ void operator()(const f32x4 (&acc)[2][2][4][2], const Unit& u, int wr, int wc, int fr, int fq) const {
;     ...
;             for (int m = 0; m < 4; ++m) { const int row = row0 + ai * HALF + m * 16; const size_t off = (size_t)row * D + col0; float s = 0.f;
; #pragma unroll
;                 for (int bj = 0; bj < 2; ++bj) {
;                     f32x4 v0, v1;
;                     if (MODE == 0) { v0 = *(const f32x4*)(base + off + bj * HALF); v1 = *(const f32x4*)(base + off + bj * HALF + 4); }
;                     else { const u32x4 r = *(const u32x4*)(bb + blk(row, col0 + bj * HALF, D)); v0 = (f32x4){bflo(r.x), bfhi(r.x), bflo(r.y), bfhi(r.y)}; v1 = (f32x4){bflo(r.z), bfhi(r.z), bflo(r.w), bfhi(r.w)}; }
;                     v0 += acc[ai][bj][m][0] * alpha; v1 += acc[ai][bj][m][1] * alpha;
;                     if (MODE == 2) { *(f32x4*)(out + off + bj * HALF) = v0; *(f32x4*)(out + off + bj * HALF + 4) = v1; }
;                     else {
;                         s += (v0[0] * v0[0] + v0[1] * v0[1]) + (v0[2] * v0[2] + v0[3] * v0[3]) + (v1[0] * v1[0] + v1[1] * v1[1]) + (v1[2] * v1[2] + v1[3] * v1[3]);
;                         u32x4 w; w.x = pk2(v0[0], v0[1]); w.y = pk2(v0[2], v0[3]); w.z = pk2(v1[0], v1[1]); w.w = pk2(v1[2], v1[3]); *(u32x4*)(xb + blk(row, col0 + bj * HALF, D)) = w; } }
;                 if (MODE != 2) { s += __shfl_xor(s, 16); s += __shfl_xor(s, 32); if (fq == 0) unsafeAtomicAdd(ssq + row, s); } }
.LBB0_766:
	s_or_b64 exec, exec, s[44:45]
	v_or_b32_e32 v82, 48, v146
	s_waitcnt lgkmcnt(0)
	v_lshlrev_b32_e32 v83, 6, v82
	v_and_or_b32 v83, v83, s65, v148
	v_or_b32_e32 v84, s38, v83
	v_mov_b32_e32 v85, s39
	v_lshlrev_b64 v[88:89], 1, v[84:85]
	v_lshl_add_u64 v[84:85], s[42:43], 0, v[88:89]
	s_nop 0
	v_mov_b32_e32 v91, s41
	v_or_b32_e32 v90, s40, v83
	v_lshlrev_b64 v[90:91], 1, v[90:91]
	v_lshl_add_u64 v[88:89], s[18:19], 0, v[88:89]
	v_lshl_add_u64 v[92:93], s[42:43], 0, v[90:91]
	v_mov_b32_e32 v84, v198
	v_mov_b32_e32 v85, v199
	v_mov_b32_e32 v86, v200
	v_mov_b32_e32 v87, v201
	v_lshlrev_b32_e32 v94, 16, v84
	v_and_b32_e32 v95, 0xffff0000, v84
	v_lshlrev_b32_e32 v84, 16, v85
	v_and_b32_e32 v85, 0xffff0000, v85
	v_lshlrev_b32_e32 v96, 16, v86
	v_and_b32_e32 v97, 0xffff0000, v86
	v_lshlrev_b32_e32 v86, 16, v87
	v_and_b32_e32 v87, 0xffff0000, v87
	v_pk_add_f32 v[80:81], v[80:81], v[84:85]
	v_pk_add_f32 v[78:79], v[78:79], v[94:95]
	v_pk_add_f32 v[84:85], v[76:77], v[86:87]
	v_pk_add_f32 v[86:87], v[74:75], v[96:97]
	v_cvt_pk_bf16_f32 v74, v78, v79
	v_cvt_pk_bf16_f32 v75, v80, v81
	v_cvt_pk_bf16_f32 v76, v86, v87
	v_cvt_pk_bf16_f32 v77, v84, v85
	global_store_dwordx4 v[88:89], v[74:77], off sc1
	s_nop 0
	v_mul_f32_e32 v79, v79, v79
	v_mul_f32_e32 v81, v81, v81
	v_mul_f32_e32 v83, v87, v87
	v_fmac_f32_e32 v79, v78, v78
	v_fmac_f32_e32 v81, v80, v80
	v_mul_f32_e32 v85, v85, v85
	v_fmac_f32_e32 v83, v86, v86
	v_add_f32_e32 v78, v79, v81
	v_fmac_f32_e32 v85, v84, v84
	v_add_f32_e32 v78, v83, v78
	v_add_f32_e32 v83, v85, v78
	v_mov_b32_e32 v74, v202
	v_mov_b32_e32 v75, v203
	v_mov_b32_e32 v76, v204
	v_mov_b32_e32 v77, v205
	v_lshlrev_b32_e32 v78, 16, v74
	v_and_b32_e32 v79, 0xffff0000, v74
	v_lshlrev_b32_e32 v74, 16, v75
	v_and_b32_e32 v75, 0xffff0000, v75
	v_lshlrev_b32_e32 v80, 16, v76
	v_and_b32_e32 v81, 0xffff0000, v76
	v_lshlrev_b32_e32 v76, 16, v77
	v_and_b32_e32 v77, 0xffff0000, v77
	v_pk_add_f32 v[72:73], v[72:73], v[74:75]
	v_pk_add_f32 v[70:71], v[70:71], v[78:79]
	v_pk_add_f32 v[74:75], v[68:69], v[76:77]
	v_pk_add_f32 v[76:77], v[66:67], v[80:81]
	v_mul_f32_e32 v66, v71, v71
	v_mul_f32_e32 v67, v73, v73
	v_mul_f32_e32 v68, v77, v77
	v_fmac_f32_e32 v66, v70, v70
	v_fmac_f32_e32 v67, v72, v72
	v_mul_f32_e32 v69, v75, v75
	v_fmac_f32_e32 v68, v76, v76
	v_add_f32_e32 v66, v66, v67
	v_add_f32_e32 v66, v68, v66
	v_fmac_f32_e32 v69, v74, v74
	v_add_f32_e32 v66, v69, v66
	v_add_f32_e32 v66, v83, v66
	ds_bpermute_b32 v67, v122, v66
	v_cvt_pk_bf16_f32 v68, v70, v71
	v_cvt_pk_bf16_f32 v69, v72, v73
	v_cvt_pk_bf16_f32 v70, v76, v77
	v_cvt_pk_bf16_f32 v71, v74, v75
	s_waitcnt lgkmcnt(0)
	v_add_f32_e32 v66, v66, v67
	ds_bpermute_b32 v67, v116, v66
	v_lshl_add_u64 v[72:73], s[18:19], 0, v[90:91]
	global_store_dwordx4 v[72:73], v[68:71], off sc1
	s_and_saveexec_b64 s[38:39], s[0:1]
	s_cbranch_execz .LBB0_768
	v_ashrrev_i32_e32 v83, 31, v82
	v_lshl_add_u64 v[68:69], v[82:83], 2, s[10:11]
	s_waitcnt lgkmcnt(0)
	v_add_f32_e32 v66, v66, v67
	global_atomic_add_f32 v[68:69], v66, off
.LBB0_768:
	s_or_b64 exec, exec, s[38:39]
	v_add_u32_e32 v70, 0x80, v146
	v_ashrrev_i32_e32 v66, 2, v70
	v_and_b32_e32 v71, 0xffffffc0, v66
	v_lshlrev_b32_e32 v66, 6, v70
	v_and_or_b32 v78, v66, s62, v148
	v_add_u32_e32 v66, s15, v71
	s_waitcnt lgkmcnt(0)
	v_ashrrev_i32_e32 v67, 31, v66
	v_lshlrev_b64 v[66:67], 14, v[66:67]
	v_or_b32_e32 v68, v66, v78
	v_mov_b32_e32 v69, v67
	v_lshlrev_b64 v[76:77], 1, v[68:69]
	v_lshl_add_u64 v[68:69], s[42:43], 0, v[76:77]
	s_nop 0
	v_add_u32_e32 v68, s17, v71
	v_ashrrev_i32_e32 v69, 31, v68
	v_lshlrev_b64 v[68:69], 14, v[68:69]
	v_or_b32_e32 v78, v68, v78
	v_mov_b32_e32 v79, v69
	v_lshlrev_b64 v[78:79], 1, v[78:79]
	v_lshl_add_u64 v[76:77], s[18:19], 0, v[76:77]
	v_lshl_add_u64 v[80:81], s[42:43], 0, v[78:79]
	v_mov_b32_e32 v72, v206
	v_mov_b32_e32 v73, v207
	v_mov_b32_e32 v74, v208
	v_mov_b32_e32 v75, v209
	v_lshlrev_b32_e32 v82, 16, v72
	v_and_b32_e32 v83, 0xffff0000, v72
	v_lshlrev_b32_e32 v72, 16, v73
	v_and_b32_e32 v73, 0xffff0000, v73
	v_lshlrev_b32_e32 v84, 16, v74
	v_and_b32_e32 v85, 0xffff0000, v74
	v_lshlrev_b32_e32 v74, 16, v75
	v_and_b32_e32 v75, 0xffff0000, v75
	v_pk_add_f32 v[64:65], v[64:65], v[72:73]
	v_pk_add_f32 v[62:63], v[62:63], v[82:83]
	v_pk_add_f32 v[72:73], v[60:61], v[74:75]
	v_pk_add_f32 v[74:75], v[58:59], v[84:85]
	v_cvt_pk_bf16_f32 v58, v62, v63
	v_cvt_pk_bf16_f32 v59, v64, v65
	v_cvt_pk_bf16_f32 v60, v74, v75
	v_cvt_pk_bf16_f32 v61, v72, v73
	global_store_dwordx4 v[76:77], v[58:61], off sc1
	s_nop 0
	v_mul_f32_e32 v63, v63, v63
	v_mul_f32_e32 v65, v65, v65
	v_mul_f32_e32 v71, v75, v75
	v_fmac_f32_e32 v63, v62, v62
	v_fmac_f32_e32 v65, v64, v64
	v_mul_f32_e32 v73, v73, v73
	v_fmac_f32_e32 v71, v74, v74
	v_add_f32_e32 v62, v63, v65
	v_fmac_f32_e32 v73, v72, v72
	v_add_f32_e32 v62, v71, v62
	v_add_f32_e32 v71, v73, v62
	v_mov_b32_e32 v58, v210
	v_mov_b32_e32 v59, v211
	v_mov_b32_e32 v60, v212
	v_mov_b32_e32 v61, v213
	v_lshlrev_b32_e32 v62, 16, v58
	v_and_b32_e32 v63, 0xffff0000, v58
	v_lshlrev_b32_e32 v58, 16, v59
	v_and_b32_e32 v59, 0xffff0000, v59
	v_lshlrev_b32_e32 v64, 16, v60
	v_and_b32_e32 v65, 0xffff0000, v60
	v_lshlrev_b32_e32 v60, 16, v61
	v_and_b32_e32 v61, 0xffff0000, v61
	v_pk_add_f32 v[56:57], v[56:57], v[58:59]
	v_pk_add_f32 v[54:55], v[54:55], v[62:63]
	v_pk_add_f32 v[58:59], v[52:53], v[60:61]
	v_pk_add_f32 v[60:61], v[50:51], v[64:65]
	v_mul_f32_e32 v50, v55, v55
	v_mul_f32_e32 v51, v57, v57
	v_mul_f32_e32 v52, v61, v61
	v_fmac_f32_e32 v50, v54, v54
	v_fmac_f32_e32 v51, v56, v56
	v_mul_f32_e32 v53, v59, v59
	v_fmac_f32_e32 v52, v60, v60
	v_add_f32_e32 v50, v50, v51
	v_add_f32_e32 v50, v52, v50
	v_fmac_f32_e32 v53, v58, v58
	v_add_f32_e32 v50, v53, v50
	v_add_f32_e32 v50, v71, v50
	ds_bpermute_b32 v51, v122, v50
	v_cvt_pk_bf16_f32 v52, v54, v55
	v_cvt_pk_bf16_f32 v53, v56, v57
	v_cvt_pk_bf16_f32 v54, v60, v61
	v_cvt_pk_bf16_f32 v55, v58, v59
	s_waitcnt lgkmcnt(0)
	v_add_f32_e32 v50, v50, v51
	ds_bpermute_b32 v51, v116, v50
	v_lshl_add_u64 v[56:57], s[18:19], 0, v[78:79]
	global_store_dwordx4 v[56:57], v[52:55], off sc1
	s_and_saveexec_b64 s[38:39], s[0:1]
	s_cbranch_execz .LBB0_770
	v_ashrrev_i32_e32 v71, 31, v70
	v_lshl_add_u64 v[52:53], v[70:71], 2, s[10:11]
	s_waitcnt lgkmcnt(0)
	v_add_f32_e32 v50, v50, v51
	global_atomic_add_f32 v[52:53], v50, off
; __host__ __device__ __forceinline__ size_t blk(int r, int k, int K) { return (((size_t)((r >> 8) * (K >> 6) + (k >> 6))) << 14) + (size_t)(((r & 255) << 6) + (k & 63)); }
; __device__ __forceinline__ float bflo(unsigned w) { return __uint_as_float(w << 16); }
; __device__ __forceinline__ float bfhi(unsigned w) { return __uint_as_float(w & 0xffff0000u); }
; __device__ __forceinline__ unsigned pk2(float lo, float hi) { f32x2 v = {lo, hi}; bf16x2_t b = __builtin_convertvector(v, bf16x2_t); return __builtin_bit_cast(unsigned, b); }
;     __device__ __forceinline__ void operator()(const f32x4 (&acc)[2][2][4][2], const Unit& u, int wr, int wc, int fr, int fq) const {
;     ...
;             for (int m = 0; m < 4; ++m) { const int row = row0 + ai * HALF + m * 16; const size_t off = (size_t)row * D + col0; float s = 0.f;
; #pragma unroll
;                 for (int bj = 0; bj < 2; ++bj) {
;                     f32x4 v0, v1;
;                     if (MODE == 0) { v0 = *(const f32x4*)(base + off + bj * HALF); v1 = *(const f32x4*)(base + off + bj * HALF + 4); }
;                     else { const u32x4 r = *(const u32x4*)(bb + blk(row, col0 + bj * HALF, D)); v0 = (f32x4){bflo(r.x), bfhi(r.x), bflo(r.y), bfhi(r.y)}; v1 = (f32x4){bflo(r.z), bfhi(r.z), bflo(r.w), bfhi(r.w)}; }
;                     v0 += acc[ai][bj][m][0] * alpha; v1 += acc[ai][bj][m][1] * alpha;
;                     if (MODE == 2) { *(f32x4*)(out + off + bj * HALF) = v0; *(f32x4*)(out + off + bj * HALF + 4) = v1; }
;                     else {
;                         s += (v0[0] * v0[0] + v0[1] * v0[1]) + (v0[2] * v0[2] + v0[3] * v0[3]) + (v1[0] * v1[0] + v1[1] * v1[1]) + (v1[2] * v1[2] + v1[3] * v1[3]);
;                         u32x4 w; w.x = pk2(v0[0], v0[1]); w.y = pk2(v0[2], v0[3]); w.z = pk2(v1[0], v1[1]); w.w = pk2(v1[2], v1[3]); *(u32x4*)(xb + blk(row, col0 + bj * HALF, D)) = w; } }
;                 if (MODE != 2) { s += __shfl_xor(s, 16); s += __shfl_xor(s, 32); if (fq == 0) unsafeAtomicAdd(ssq + row, s); } }
.LBB0_770:
	s_or_b64 exec, exec, s[38:39]
	v_add_u32_e32 v50, 0x90, v146
	s_waitcnt lgkmcnt(0)
	v_lshlrev_b32_e32 v51, 6, v50
	v_and_or_b32 v51, v51, s63, v148
	v_or_b32_e32 v52, v66, v51
	v_mov_b32_e32 v53, v67
	v_lshlrev_b64 v[56:57], 1, v[52:53]
	v_lshl_add_u64 v[52:53], s[42:43], 0, v[56:57]
	s_nop 0
	v_mov_b32_e32 v59, v69
	v_or_b32_e32 v58, v68, v51
	v_lshlrev_b64 v[58:59], 1, v[58:59]
	v_lshl_add_u64 v[56:57], s[18:19], 0, v[56:57]
	v_lshl_add_u64 v[60:61], s[42:43], 0, v[58:59]
	v_mov_b32_e32 v52, v214
	v_mov_b32_e32 v53, v215
	v_mov_b32_e32 v54, v216
	v_mov_b32_e32 v55, v217
	v_lshlrev_b32_e32 v62, 16, v52
	v_and_b32_e32 v63, 0xffff0000, v52
	v_lshlrev_b32_e32 v52, 16, v53
	v_and_b32_e32 v53, 0xffff0000, v53
	v_lshlrev_b32_e32 v64, 16, v54
	v_and_b32_e32 v65, 0xffff0000, v54
	v_lshlrev_b32_e32 v54, 16, v55
	v_and_b32_e32 v55, 0xffff0000, v55
	v_pk_add_f32 v[48:49], v[48:49], v[52:53]
	v_pk_add_f32 v[46:47], v[46:47], v[62:63]
	v_pk_add_f32 v[52:53], v[44:45], v[54:55]
	v_pk_add_f32 v[54:55], v[42:43], v[64:65]
	v_cvt_pk_bf16_f32 v42, v46, v47
	v_cvt_pk_bf16_f32 v43, v48, v49
	v_cvt_pk_bf16_f32 v44, v54, v55
	v_cvt_pk_bf16_f32 v45, v52, v53
	global_store_dwordx4 v[56:57], v[42:45], off sc1
	s_nop 0
	v_mul_f32_e32 v47, v47, v47
	v_mul_f32_e32 v49, v49, v49
	v_mul_f32_e32 v51, v55, v55
	v_fmac_f32_e32 v47, v46, v46
	v_fmac_f32_e32 v49, v48, v48
	v_mul_f32_e32 v53, v53, v53
	v_fmac_f32_e32 v51, v54, v54
	v_add_f32_e32 v46, v47, v49
	v_fmac_f32_e32 v53, v52, v52
	v_add_f32_e32 v46, v51, v46
	v_add_f32_e32 v51, v53, v46
	v_mov_b32_e32 v42, v218
	v_mov_b32_e32 v43, v219
	v_mov_b32_e32 v44, v220
	v_mov_b32_e32 v45, v221
	v_lshlrev_b32_e32 v46, 16, v42
	v_and_b32_e32 v47, 0xffff0000, v42
	v_lshlrev_b32_e32 v42, 16, v43
	v_and_b32_e32 v43, 0xffff0000, v43
	v_lshlrev_b32_e32 v48, 16, v44
	v_and_b32_e32 v49, 0xffff0000, v44
	v_lshlrev_b32_e32 v44, 16, v45
	v_and_b32_e32 v45, 0xffff0000, v45
	v_pk_add_f32 v[40:41], v[40:41], v[42:43]
	v_pk_add_f32 v[38:39], v[38:39], v[46:47]
	v_pk_add_f32 v[42:43], v[36:37], v[44:45]
	v_pk_add_f32 v[44:45], v[34:35], v[48:49]
	v_mul_f32_e32 v34, v39, v39
	v_mul_f32_e32 v35, v41, v41
	v_mul_f32_e32 v36, v45, v45
	v_fmac_f32_e32 v34, v38, v38
	v_fmac_f32_e32 v35, v40, v40
	v_mul_f32_e32 v37, v43, v43
	v_fmac_f32_e32 v36, v44, v44
	v_add_f32_e32 v34, v34, v35
	v_add_f32_e32 v34, v36, v34
	v_fmac_f32_e32 v37, v42, v42
	v_add_f32_e32 v34, v37, v34
	v_add_f32_e32 v34, v51, v34
	ds_bpermute_b32 v35, v122, v34
	v_cvt_pk_bf16_f32 v36, v38, v39
	v_cvt_pk_bf16_f32 v37, v40, v41
	v_cvt_pk_bf16_f32 v38, v44, v45
	v_cvt_pk_bf16_f32 v39, v42, v43
	s_waitcnt lgkmcnt(0)
	v_add_f32_e32 v34, v34, v35
	ds_bpermute_b32 v35, v116, v34
	v_lshl_add_u64 v[40:41], s[18:19], 0, v[58:59]
	global_store_dwordx4 v[40:41], v[36:39], off sc1
	s_and_saveexec_b64 s[38:39], s[0:1]
	s_cbranch_execz .LBB0_772
	v_ashrrev_i32_e32 v51, 31, v50
	v_lshl_add_u64 v[36:37], v[50:51], 2, s[10:11]
	s_waitcnt lgkmcnt(0)
	v_add_f32_e32 v34, v34, v35
	global_atomic_add_f32 v[36:37], v34, off
; __host__ __device__ __forceinline__ size_t blk(int r, int k, int K) { return (((size_t)((r >> 8) * (K >> 6) + (k >> 6))) << 14) + (size_t)(((r & 255) << 6) + (k & 63)); }
; __device__ __forceinline__ float bflo(unsigned w) { return __uint_as_float(w << 16); }
; __device__ __forceinline__ float bfhi(unsigned w) { return __uint_as_float(w & 0xffff0000u); }
; __device__ __forceinline__ unsigned pk2(float lo, float hi) { f32x2 v = {lo, hi}; bf16x2_t b = __builtin_convertvector(v, bf16x2_t); return __builtin_bit_cast(unsigned, b); }
;     __device__ __forceinline__ void operator()(const f32x4 (&acc)[2][2][4][2], const Unit& u, int wr, int wc, int fr, int fq) const {
;     ...
;             for (int m = 0; m < 4; ++m) { const int row = row0 + ai * HALF + m * 16; const size_t off = (size_t)row * D + col0; float s = 0.f;
; #pragma unroll
;                 for (int bj = 0; bj < 2; ++bj) {
;                     f32x4 v0, v1;
;                     if (MODE == 0) { v0 = *(const f32x4*)(base + off + bj * HALF); v1 = *(const f32x4*)(base + off + bj * HALF + 4); }
;                     else { const u32x4 r = *(const u32x4*)(bb + blk(row, col0 + bj * HALF, D)); v0 = (f32x4){bflo(r.x), bfhi(r.x), bflo(r.y), bfhi(r.y)}; v1 = (f32x4){bflo(r.z), bfhi(r.z), bflo(r.w), bfhi(r.w)}; }
;                     v0 += acc[ai][bj][m][0] * alpha; v1 += acc[ai][bj][m][1] * alpha;
;                     if (MODE == 2) { *(f32x4*)(out + off + bj * HALF) = v0; *(f32x4*)(out + off + bj * HALF + 4) = v1; }
;                     else {
;                         s += (v0[0] * v0[0] + v0[1] * v0[1]) + (v0[2] * v0[2] + v0[3] * v0[3]) + (v1[0] * v1[0] + v1[1] * v1[1]) + (v1[2] * v1[2] + v1[3] * v1[3]);
;                         u32x4 w; w.x = pk2(v0[0], v0[1]); w.y = pk2(v0[2], v0[3]); w.z = pk2(v1[0], v1[1]); w.w = pk2(v1[2], v1[3]); *(u32x4*)(xb + blk(row, col0 + bj * HALF, D)) = w; } }
;                 if (MODE != 2) { s += __shfl_xor(s, 16); s += __shfl_xor(s, 32); if (fq == 0) unsafeAtomicAdd(ssq + row, s); } }
.LBB0_772:
	s_or_b64 exec, exec, s[38:39]
	v_add_u32_e32 v34, 0xa0, v146
	s_waitcnt lgkmcnt(0)
	v_lshlrev_b32_e32 v35, 6, v34
	v_and_or_b32 v35, v35, s64, v148
	v_or_b32_e32 v36, v66, v35
	v_mov_b32_e32 v37, v67
	v_lshlrev_b64 v[40:41], 1, v[36:37]
	v_lshl_add_u64 v[36:37], s[42:43], 0, v[40:41]
	s_nop 0
	v_mov_b32_e32 v43, v69
	v_or_b32_e32 v42, v68, v35
	v_lshlrev_b64 v[42:43], 1, v[42:43]
	v_lshl_add_u64 v[40:41], s[18:19], 0, v[40:41]
	v_lshl_add_u64 v[44:45], s[42:43], 0, v[42:43]
	s_waitcnt vmcnt(10)
	v_mov_b32_e32 v36, v168
	v_mov_b32_e32 v37, v169
	v_mov_b32_e32 v38, v170
	v_mov_b32_e32 v39, v171
	v_lshlrev_b32_e32 v46, 16, v36
	v_and_b32_e32 v47, 0xffff0000, v36
	v_lshlrev_b32_e32 v36, 16, v37
	v_and_b32_e32 v37, 0xffff0000, v37
	v_lshlrev_b32_e32 v48, 16, v38
	v_and_b32_e32 v49, 0xffff0000, v38
	v_lshlrev_b32_e32 v38, 16, v39
	v_and_b32_e32 v39, 0xffff0000, v39
	v_pk_add_f32 v[32:33], v[32:33], v[36:37]
	v_pk_add_f32 v[30:31], v[30:31], v[46:47]
	v_pk_add_f32 v[36:37], v[28:29], v[38:39]
	v_pk_add_f32 v[38:39], v[26:27], v[48:49]
	v_cvt_pk_bf16_f32 v26, v30, v31
	v_cvt_pk_bf16_f32 v27, v32, v33
	v_cvt_pk_bf16_f32 v28, v38, v39
	v_cvt_pk_bf16_f32 v29, v36, v37
	global_store_dwordx4 v[40:41], v[26:29], off sc1
	s_nop 0
	v_mul_f32_e32 v31, v31, v31
	v_mul_f32_e32 v33, v33, v33
	v_mul_f32_e32 v35, v39, v39
	v_fmac_f32_e32 v31, v30, v30
	v_fmac_f32_e32 v33, v32, v32
	v_mul_f32_e32 v37, v37, v37
	v_fmac_f32_e32 v35, v38, v38
	v_add_f32_e32 v30, v31, v33
	v_fmac_f32_e32 v37, v36, v36
	v_add_f32_e32 v30, v35, v30
	v_add_f32_e32 v35, v37, v30
	v_mov_b32_e32 v26, v172
	v_mov_b32_e32 v27, v173
	v_mov_b32_e32 v28, v174
	v_mov_b32_e32 v29, v175
	v_lshlrev_b32_e32 v30, 16, v26
	v_and_b32_e32 v31, 0xffff0000, v26
	v_lshlrev_b32_e32 v26, 16, v27
	v_and_b32_e32 v27, 0xffff0000, v27
	v_lshlrev_b32_e32 v32, 16, v28
	v_and_b32_e32 v33, 0xffff0000, v28
	v_lshlrev_b32_e32 v28, 16, v29
	v_and_b32_e32 v29, 0xffff0000, v29
	v_pk_add_f32 v[24:25], v[24:25], v[26:27]
	v_pk_add_f32 v[22:23], v[22:23], v[30:31]
	v_pk_add_f32 v[26:27], v[20:21], v[28:29]
	v_pk_add_f32 v[28:29], v[18:19], v[32:33]
	v_mul_f32_e32 v18, v23, v23
	v_mul_f32_e32 v19, v25, v25
	v_mul_f32_e32 v20, v29, v29
	v_fmac_f32_e32 v18, v22, v22
	v_fmac_f32_e32 v19, v24, v24
	v_mul_f32_e32 v21, v27, v27
	v_fmac_f32_e32 v20, v28, v28
	v_add_f32_e32 v18, v18, v19
	v_add_f32_e32 v18, v20, v18
	v_fmac_f32_e32 v21, v26, v26
	v_add_f32_e32 v18, v21, v18
	v_add_f32_e32 v18, v35, v18
	ds_bpermute_b32 v19, v122, v18
	v_cvt_pk_bf16_f32 v20, v22, v23
	v_cvt_pk_bf16_f32 v21, v24, v25
	v_cvt_pk_bf16_f32 v22, v28, v29
	v_cvt_pk_bf16_f32 v23, v26, v27
	s_waitcnt lgkmcnt(0)
	v_add_f32_e32 v18, v18, v19
	ds_bpermute_b32 v19, v116, v18
	v_lshl_add_u64 v[24:25], s[18:19], 0, v[42:43]
	global_store_dwordx4 v[24:25], v[20:23], off sc1
	s_and_saveexec_b64 s[38:39], s[0:1]
	s_cbranch_execz .LBB0_774
	v_ashrrev_i32_e32 v35, 31, v34
	v_lshl_add_u64 v[20:21], v[34:35], 2, s[10:11]
	s_waitcnt lgkmcnt(0)
	v_add_f32_e32 v18, v18, v19
	global_atomic_add_f32 v[20:21], v18, off
.LBB0_774:
	s_or_b64 exec, exec, s[38:39]
	v_add_u32_e32 v18, 0xb0, v146
	s_waitcnt lgkmcnt(0)
	v_lshlrev_b32_e32 v19, 6, v18
	v_and_or_b32 v19, v19, s65, v148
	v_or_b32_e32 v66, v66, v19
	v_lshlrev_b64 v[24:25], 1, v[66:67]
	v_lshl_add_u64 v[20:21], s[42:43], 0, v[24:25]
	s_nop 0
	v_or_b32_e32 v68, v68, v19
	v_lshlrev_b64 v[26:27], 1, v[68:69]
	v_lshl_add_u64 v[24:25], s[18:19], 0, v[24:25]
	v_lshl_add_u64 v[28:29], s[42:43], 0, v[26:27]
	v_mov_b32_e32 v20, v180
	v_mov_b32_e32 v21, v181
	v_mov_b32_e32 v22, v182
	v_mov_b32_e32 v23, v183
	v_lshlrev_b32_e32 v30, 16, v20
	v_and_b32_e32 v31, 0xffff0000, v20
	v_lshlrev_b32_e32 v20, 16, v21
	v_and_b32_e32 v21, 0xffff0000, v21
	v_lshlrev_b32_e32 v32, 16, v22
	v_and_b32_e32 v33, 0xffff0000, v22
	v_lshlrev_b32_e32 v22, 16, v23
	v_and_b32_e32 v23, 0xffff0000, v23
	v_pk_add_f32 v[16:17], v[16:17], v[20:21]
	v_pk_add_f32 v[14:15], v[14:15], v[30:31]
	v_pk_add_f32 v[20:21], v[12:13], v[22:23]
	v_pk_add_f32 v[22:23], v[10:11], v[32:33]
	v_cvt_pk_bf16_f32 v10, v14, v15
	v_cvt_pk_bf16_f32 v11, v16, v17
	v_cvt_pk_bf16_f32 v12, v22, v23
	v_cvt_pk_bf16_f32 v13, v20, v21
	global_store_dwordx4 v[24:25], v[10:13], off sc1
	s_nop 0
	v_mul_f32_e32 v15, v15, v15
	v_mul_f32_e32 v17, v17, v17
	v_mul_f32_e32 v19, v23, v23
	v_fmac_f32_e32 v15, v14, v14
	v_fmac_f32_e32 v17, v16, v16
	v_mul_f32_e32 v21, v21, v21
	v_fmac_f32_e32 v19, v22, v22
	v_add_f32_e32 v14, v15, v17
	v_fmac_f32_e32 v21, v20, v20
	v_add_f32_e32 v14, v19, v14
	v_add_f32_e32 v19, v21, v14
	v_mov_b32_e32 v10, v184
	v_mov_b32_e32 v11, v185
	v_mov_b32_e32 v12, v186
	v_mov_b32_e32 v13, v187
	v_lshlrev_b32_e32 v14, 16, v10
	v_and_b32_e32 v15, 0xffff0000, v10
	v_lshlrev_b32_e32 v10, 16, v11
	v_and_b32_e32 v11, 0xffff0000, v11
	v_lshlrev_b32_e32 v16, 16, v12
	v_and_b32_e32 v17, 0xffff0000, v12
	v_lshlrev_b32_e32 v12, 16, v13
	v_and_b32_e32 v13, 0xffff0000, v13
	v_pk_add_f32 v[8:9], v[8:9], v[10:11]
	v_pk_add_f32 v[6:7], v[6:7], v[14:15]
	v_pk_add_f32 v[10:11], v[4:5], v[12:13]
	v_pk_add_f32 v[12:13], v[2:3], v[16:17]
	v_mul_f32_e32 v2, v7, v7
	v_mul_f32_e32 v3, v9, v9
	v_mul_f32_e32 v4, v13, v13
	v_fmac_f32_e32 v2, v6, v6
	v_fmac_f32_e32 v3, v8, v8
	v_mul_f32_e32 v5, v11, v11
	v_fmac_f32_e32 v4, v12, v12
	v_add_f32_e32 v2, v2, v3
	v_add_f32_e32 v2, v4, v2
	v_fmac_f32_e32 v5, v10, v10
	v_add_f32_e32 v2, v5, v2
	v_add_f32_e32 v2, v19, v2
	ds_bpermute_b32 v3, v122, v2
	v_cvt_pk_bf16_f32 v4, v6, v7
	v_cvt_pk_bf16_f32 v5, v8, v9
	v_cvt_pk_bf16_f32 v6, v12, v13
	v_cvt_pk_bf16_f32 v7, v10, v11
	s_waitcnt lgkmcnt(0)
	v_add_f32_e32 v2, v2, v3
	ds_bpermute_b32 v3, v116, v2
	v_lshl_add_u64 v[8:9], s[18:19], 0, v[26:27]
	global_store_dwordx4 v[8:9], v[4:7], off sc1
	s_and_saveexec_b64 s[38:39], s[0:1]
	s_cbranch_execz .LBB0_776
	v_ashrrev_i32_e32 v19, 31, v18
	v_lshl_add_u64 v[4:5], v[18:19], 2, s[10:11]
	s_waitcnt lgkmcnt(0)
	v_add_f32_e32 v2, v2, v3
	global_atomic_add_f32 v[4:5], v2, off

; __host__ __device__ __forceinline__ size_t blk(int r, int k, int K) { return (((size_t)((r >> 8) * (K >> 6) + (k >> 6))) << 14) + (size_t)(((r & 255) << 6) + (k & 63)); }
; __device__ __forceinline__ unsigned pk2(float lo, float hi) { f32x2 v = {lo, hi}; bf16x2_t b = __builtin_convertvector(v, bf16x2_t); return __builtin_bit_cast(unsigned, b); }
; __device__ __forceinline__ float fsilu(float x) { return x * fsigmoid(x); }
;     __device__ __forceinline__ void operator()(const f32x4 (&acc)[2][2][4][2], const Unit& u, int wr, int wc, int fr, int fq) const {
;     ...
;             for (int m = 0; m < 4; ++m) { const int row = row0 + ai * HALF + m * 16; bf16_t* rowp = O + blk(row, col0, ldc);
;                 const float rs = ssq ? 1.0f / sqrtf(ssq[row] * (1.0f / D) + RMS_EPS) : 1.0f;
;                 const f32x4 a0 = acc[ai][0][m][0] * rs, a1 = acc[ai][0][m][1] * rs, b0 = acc[ai][1][m][0] * rs, b1 = acc[ai][1][m][1] * rs;
;                 u32x4 w; w.x = pk2(fsilu(a0[0]) * b0[0], fsilu(a0[1]) * b0[1]); w.y = pk2(fsilu(a0[2]) * b0[2], fsilu(a0[3]) * b0[3]);
;                 w.z = pk2(fsilu(a1[0]) * b1[0], fsilu(a1[1]) * b1[1]); w.w = pk2(fsilu(a1[2]) * b1[2], fsilu(a1[3]) * b1[3]);
;                 *(u32x4*)rowp = w; }
.LBB0_843:
	s_lshl_b32 s4, s4, 8
	s_add_i32 s4, s4, s48
	v_or_b32_e32 v150, s4, v195
	v_ashrrev_i32_e32 v151, 31, v150
	v_lshl_add_u64 v[148:149], v[150:151], 2, s[12:13]
	global_load_dword v138, v[148:149], off
	global_load_dword v175, v[148:149], off offset:64
	global_load_dword v176, v[148:149], off offset:128
	global_load_dword v177, v[148:149], off offset:192
	global_load_dword v180, v[148:149], off offset:512
	global_load_dword v181, v[148:149], off offset:576
	global_load_dword v182, v[148:149], off offset:640
	global_load_dword v183, v[148:149], off offset:704
	v_lshlrev_b32_e32 v151, 6, v150
	v_and_or_b32 v160, v151, s59, v152
	v_lshlrev_b32_e32 v170, 1, v160
	s_lshl_b32 s5, s5, 7
	s_or_b32 s5, s5, s49
	s_ashr_i32 s4, s4, 8
	v_or_b32_e32 v158, 16, v150
	s_ashr_i32 s17, s5, 6
	s_mulk_i32 s4, 0xac
	v_ashrrev_i32_e32 v159, 31, v158
	s_add_i32 s4, s4, s17
	s_ashr_i32 s5, s4, 31
	s_lshl_b64 s[40:41], s[4:5], 15
	s_add_u32 s40, s20, s40
	s_addc_u32 s41, s21, s41
	s_waitcnt vmcnt(0)
	v_fmamk_f32 v138, v138, 0x39800000, v156
	v_mul_f32_e32 v160, 0x4f800000, v138
	v_cmp_gt_f32_e32 vcc, s61, v138
	s_nop 1
	v_cndmask_b32_e32 v138, v138, v160, vcc
	v_sqrt_f32_e32 v162, v138
	v_lshl_add_u64 v[160:161], v[158:159], 2, s[12:13]
	v_add_u32_e32 v159, -1, v162
	v_add_u32_e32 v163, 1, v162
	v_fma_f32 v164, -v159, v162, v138
	v_fma_f32 v165, -v163, v162, v138
	v_cmp_ge_f32_e64 s[4:5], 0, v164
	s_nop 1
	v_cndmask_b32_e64 v159, v162, v159, s[4:5]
	v_cmp_lt_f32_e64 s[4:5], 0, v165
	s_nop 1
	v_cndmask_b32_e64 v159, v159, v163, s[4:5]
	v_mul_f32_e32 v162, 0x37800000, v159
	v_cndmask_b32_e32 v159, v159, v162, vcc
	v_cmp_class_f32_e32 vcc, v138, v157
	s_nop 1
	v_cndmask_b32_e32 v138, v159, v138, vcc
	v_div_scale_f32 v159, s[4:5], v138, v138, 1.0
	v_rcp_f32_e32 v162, v159
	v_div_scale_f32 v163, vcc, 1.0, v138, 1.0
	v_fma_f32 v164, -v159, v162, 1.0
	v_fmac_f32_e32 v162, v164, v162
	v_mul_f32_e32 v164, v163, v162
	v_fma_f32 v165, -v159, v164, v163
	v_fmac_f32_e32 v164, v165, v162
	v_fma_f32 v159, -v159, v164, v163
	v_div_fmas_f32 v159, v159, v162, v164
	v_div_fixup_f32 v138, v159, v138, 1.0
	v_pk_mul_f32 v[128:129], v[128:129], v[138:139] op_sel_hi:[1,0]
	v_pk_mul_f32 v[126:127], v[126:127], v[138:139] op_sel_hi:[1,0]
	v_pk_mul_f32 v[124:125], v[124:125], v[138:139] op_sel_hi:[1,0]
	v_pk_mul_f32 v[122:123], v[122:123], v[138:139] op_sel_hi:[1,0]
	v_pk_mul_f32 v[120:121], v[120:121], v[138:139] op_sel_hi:[1,0]
	v_pk_mul_f32 v[118:119], v[118:119], v[138:139] op_sel_hi:[1,0]
	v_pk_mul_f32 v[116:117], v[116:117], v[138:139] op_sel_hi:[1,0]
	v_pk_mul_f32 v[114:115], v[114:115], v[138:139] op_sel_hi:[1,0]
	v_mul_f32_e32 v138, 0xbfb8aa3b, v126
	v_mul_f32_e32 v159, 0xbfb8aa3b, v127
	v_mul_f32_e32 v162, 0xbfb8aa3b, v128
	v_mul_f32_e32 v163, 0xbfb8aa3b, v129
	v_mul_f32_e32 v164, 0xbfb8aa3b, v122
	v_mul_f32_e32 v165, 0xbfb8aa3b, v123
	v_mul_f32_e32 v166, 0xbfb8aa3b, v124
	v_mul_f32_e32 v167, 0xbfb8aa3b, v125
	v_exp_f32_e32 v138, v138
	v_exp_f32_e32 v159, v159
	v_exp_f32_e32 v162, v162
	v_exp_f32_e32 v163, v163
	v_exp_f32_e32 v164, v164
	v_exp_f32_e32 v165, v165
	v_exp_f32_e32 v166, v166
	v_exp_f32_e32 v167, v167
	v_add_f32_e32 v138, 1.0, v138
	v_add_f32_e32 v159, 1.0, v159
	v_add_f32_e32 v168, 1.0, v162
	v_add_f32_e32 v169, 1.0, v163
	v_add_f32_e32 v171, 1.0, v164
	v_add_f32_e32 v172, 1.0, v165
	v_add_f32_e32 v173, 1.0, v166
	v_add_f32_e32 v174, 1.0, v167
	v_rcp_f32_e32 v162, v138
	v_rcp_f32_e32 v163, v159
	v_rcp_f32_e32 v164, v168
	v_rcp_f32_e32 v165, v169
	v_rcp_f32_e32 v166, v171
	v_rcp_f32_e32 v167, v172
	v_rcp_f32_e32 v168, v173
	v_rcp_f32_e32 v169, v174
	v_pk_mul_f32 v[126:127], v[126:127], v[162:163]
	v_pk_mul_f32 v[128:129], v[128:129], v[164:165]
	v_pk_mul_f32 v[122:123], v[122:123], v[166:167]
	v_pk_mul_f32 v[124:125], v[124:125], v[168:169]
	v_pk_mul_f32 v[118:119], v[118:119], v[126:127]
	v_pk_mul_f32 v[120:121], v[120:121], v[128:129]
	v_pk_mul_f32 v[122:123], v[114:115], v[122:123]
	v_pk_mul_f32 v[124:125], v[116:117], v[124:125]
	v_cvt_pk_bf16_f32 v114, v118, v119
	v_cvt_pk_bf16_f32 v115, v120, v121
	v_cvt_pk_bf16_f32 v116, v122, v123
	v_cvt_pk_bf16_f32 v117, v124, v125
	global_store_dwordx4 v170, v[114:117], s[40:41] sc1
	s_nop 0
	s_nop 0
	v_or_b32_e32 v114, 32, v150
	v_lshlrev_b32_e32 v116, 6, v158
	v_and_or_b32 v120, v116, s62, v152
	v_lshlrev_b32_e32 v126, 1, v120
	v_mov_b32_e32 v115, v175
	v_fmamk_f32 v115, v115, 0x39800000, v156
	v_mul_f32_e32 v117, 0x4f800000, v115
	v_cmp_gt_f32_e32 vcc, s61, v115
	s_nop 1
	v_cndmask_b32_e32 v118, v115, v117, vcc
	v_sqrt_f32_e32 v119, v118
	v_ashrrev_i32_e32 v115, 31, v114
	v_lshl_add_u64 v[116:117], v[114:115], 2, s[12:13]
	v_add_u32_e32 v115, -1, v119
	v_add_u32_e32 v121, 1, v119
	v_fma_f32 v122, -v115, v119, v118
	v_fma_f32 v123, -v121, v119, v118
	v_cmp_ge_f32_e64 s[4:5], 0, v122
	s_nop 1
	v_cndmask_b32_e64 v115, v119, v115, s[4:5]
	v_cmp_lt_f32_e64 s[4:5], 0, v123
	s_nop 1
	v_cndmask_b32_e64 v115, v115, v121, s[4:5]
	v_mul_f32_e32 v119, 0x37800000, v115
	v_cndmask_b32_e32 v115, v115, v119, vcc
	v_cmp_class_f32_e32 vcc, v118, v157
	s_nop 1
	v_cndmask_b32_e32 v115, v115, v118, vcc
	v_div_scale_f32 v118, s[4:5], v115, v115, 1.0
	v_rcp_f32_e32 v119, v118
	v_div_scale_f32 v120, vcc, 1.0, v115, 1.0
	v_fma_f32 v121, -v118, v119, 1.0
	v_fmac_f32_e32 v119, v121, v119
	v_mul_f32_e32 v121, v120, v119
	v_fma_f32 v122, -v118, v121, v120
	v_fmac_f32_e32 v121, v122, v119
	v_fma_f32 v118, -v118, v121, v120
	v_div_fmas_f32 v118, v118, v119, v121
	v_div_fixup_f32 v118, v118, v115, 1.0
	v_pk_mul_f32 v[112:113], v[112:113], v[118:119] op_sel_hi:[1,0]
	v_pk_mul_f32 v[110:111], v[110:111], v[118:119] op_sel_hi:[1,0]
; __host__ __device__ __forceinline__ size_t blk(int r, int k, int K) { return (((size_t)((r >> 8) * (K >> 6) + (k >> 6))) << 14) + (size_t)(((r & 255) << 6) + (k & 63)); }
; __device__ __forceinline__ unsigned pk2(float lo, float hi) { f32x2 v = {lo, hi}; bf16x2_t b = __builtin_convertvector(v, bf16x2_t); return __builtin_bit_cast(unsigned, b); }
; __device__ __forceinline__ float fsilu(float x) { return x * fsigmoid(x); }
;     __device__ __forceinline__ void operator()(const f32x4 (&acc)[2][2][4][2], const Unit& u, int wr, int wc, int fr, int fq) const {
;     ...
;             for (int m = 0; m < 4; ++m) { const int row = row0 + ai * HALF + m * 16; bf16_t* rowp = O + blk(row, col0, ldc);
;                 const float rs = ssq ? 1.0f / sqrtf(ssq[row] * (1.0f / D) + RMS_EPS) : 1.0f;
;                 const f32x4 a0 = acc[ai][0][m][0] * rs, a1 = acc[ai][0][m][1] * rs, b0 = acc[ai][1][m][0] * rs, b1 = acc[ai][1][m][1] * rs;
;                 u32x4 w; w.x = pk2(fsilu(a0[0]) * b0[0], fsilu(a0[1]) * b0[1]); w.y = pk2(fsilu(a0[2]) * b0[2], fsilu(a0[3]) * b0[3]);
;                 w.z = pk2(fsilu(a1[0]) * b1[0], fsilu(a1[1]) * b1[1]); w.w = pk2(fsilu(a1[2]) * b1[2], fsilu(a1[3]) * b1[3]);
;                 *(u32x4*)rowp = w; }
	v_pk_mul_f32 v[108:109], v[108:109], v[118:119] op_sel_hi:[1,0]
	v_pk_mul_f32 v[106:107], v[106:107], v[118:119] op_sel_hi:[1,0]
	v_pk_mul_f32 v[104:105], v[104:105], v[118:119] op_sel_hi:[1,0]
	v_pk_mul_f32 v[102:103], v[102:103], v[118:119] op_sel_hi:[1,0]
	v_pk_mul_f32 v[100:101], v[100:101], v[118:119] op_sel_hi:[1,0]
	v_pk_mul_f32 v[98:99], v[98:99], v[118:119] op_sel_hi:[1,0]
	v_mul_f32_e32 v115, 0xbfb8aa3b, v110
	v_mul_f32_e32 v118, 0xbfb8aa3b, v111
	v_mul_f32_e32 v119, 0xbfb8aa3b, v112
	v_mul_f32_e32 v120, 0xbfb8aa3b, v113
	v_mul_f32_e32 v121, 0xbfb8aa3b, v106
	v_mul_f32_e32 v122, 0xbfb8aa3b, v107
	v_mul_f32_e32 v123, 0xbfb8aa3b, v108
	v_mul_f32_e32 v124, 0xbfb8aa3b, v109
	v_exp_f32_e32 v115, v115
	v_exp_f32_e32 v118, v118
	v_exp_f32_e32 v119, v119
	v_exp_f32_e32 v120, v120
	v_exp_f32_e32 v121, v121
	v_exp_f32_e32 v122, v122
	v_exp_f32_e32 v123, v123
	v_exp_f32_e32 v124, v124
	v_add_f32_e32 v115, 1.0, v115
	v_add_f32_e32 v125, 1.0, v118
	v_add_f32_e32 v127, 1.0, v119
	v_add_f32_e32 v128, 1.0, v120
	v_add_f32_e32 v129, 1.0, v121
	v_add_f32_e32 v138, 1.0, v122
	v_add_f32_e32 v158, 1.0, v123
	v_add_f32_e32 v159, 1.0, v124
	v_rcp_f32_e32 v118, v115
	v_rcp_f32_e32 v119, v125
	v_rcp_f32_e32 v120, v127
	v_rcp_f32_e32 v121, v128
	v_rcp_f32_e32 v122, v129
	v_rcp_f32_e32 v123, v138
	v_rcp_f32_e32 v124, v158
	v_rcp_f32_e32 v125, v159
	v_pk_mul_f32 v[110:111], v[110:111], v[118:119]
	v_pk_mul_f32 v[112:113], v[112:113], v[120:121]
	v_pk_mul_f32 v[106:107], v[106:107], v[122:123]
	v_pk_mul_f32 v[108:109], v[108:109], v[124:125]
	v_pk_mul_f32 v[102:103], v[102:103], v[110:111]
	v_pk_mul_f32 v[104:105], v[104:105], v[112:113]
	v_pk_mul_f32 v[106:107], v[98:99], v[106:107]
	v_pk_mul_f32 v[108:109], v[100:101], v[108:109]
	v_cvt_pk_bf16_f32 v98, v102, v103
	v_cvt_pk_bf16_f32 v99, v104, v105
	v_cvt_pk_bf16_f32 v100, v106, v107
	v_cvt_pk_bf16_f32 v101, v108, v109
	global_store_dwordx4 v126, v[98:101], s[40:41] sc1
	s_nop 0
	s_nop 0
	v_or_b32_e32 v98, 48, v150
	v_lshlrev_b32_e32 v100, 6, v114
	v_and_or_b32 v104, v100, s63, v152
	v_lshlrev_b32_e32 v110, 1, v104
	v_mov_b32_e32 v99, v176
	v_fmamk_f32 v99, v99, 0x39800000, v156
	v_mul_f32_e32 v101, 0x4f800000, v99
	v_cmp_gt_f32_e32 vcc, s61, v99
	s_nop 1
	v_cndmask_b32_e32 v102, v99, v101, vcc
	v_sqrt_f32_e32 v103, v102
	v_ashrrev_i32_e32 v99, 31, v98
	v_lshl_add_u64 v[100:101], v[98:99], 2, s[12:13]
	v_add_u32_e32 v99, -1, v103
	v_add_u32_e32 v105, 1, v103
	v_fma_f32 v106, -v99, v103, v102
	v_fma_f32 v107, -v105, v103, v102
	v_cmp_ge_f32_e64 s[4:5], 0, v106
	s_nop 1
	v_cndmask_b32_e64 v99, v103, v99, s[4:5]
	v_cmp_lt_f32_e64 s[4:5], 0, v107
	s_nop 1
	v_cndmask_b32_e64 v99, v99, v105, s[4:5]
	v_mul_f32_e32 v103, 0x37800000, v99
	v_cndmask_b32_e32 v99, v99, v103, vcc
	v_cmp_class_f32_e32 vcc, v102, v157
	s_nop 1
	v_cndmask_b32_e32 v99, v99, v102, vcc
	v_div_scale_f32 v102, s[4:5], v99, v99, 1.0
	v_rcp_f32_e32 v103, v102
	v_div_scale_f32 v104, vcc, 1.0, v99, 1.0
	v_fma_f32 v105, -v102, v103, 1.0
	v_fmac_f32_e32 v103, v105, v103
	v_mul_f32_e32 v105, v104, v103
	v_fma_f32 v106, -v102, v105, v104
	v_fmac_f32_e32 v105, v106, v103
	v_fma_f32 v102, -v102, v105, v104
	v_div_fmas_f32 v102, v102, v103, v105
	v_div_fixup_f32 v102, v102, v99, 1.0
	v_pk_mul_f32 v[96:97], v[96:97], v[102:103] op_sel_hi:[1,0]
	v_pk_mul_f32 v[94:95], v[94:95], v[102:103] op_sel_hi:[1,0]
	v_pk_mul_f32 v[92:93], v[92:93], v[102:103] op_sel_hi:[1,0]
	v_pk_mul_f32 v[90:91], v[90:91], v[102:103] op_sel_hi:[1,0]
	v_pk_mul_f32 v[88:89], v[88:89], v[102:103] op_sel_hi:[1,0]
	v_pk_mul_f32 v[86:87], v[86:87], v[102:103] op_sel_hi:[1,0]
	v_pk_mul_f32 v[84:85], v[84:85], v[102:103] op_sel_hi:[1,0]
	v_pk_mul_f32 v[82:83], v[82:83], v[102:103] op_sel_hi:[1,0]
	v_mul_f32_e32 v99, 0xbfb8aa3b, v94
	v_mul_f32_e32 v102, 0xbfb8aa3b, v95
	v_mul_f32_e32 v103, 0xbfb8aa3b, v96
	v_mul_f32_e32 v104, 0xbfb8aa3b, v97
	v_mul_f32_e32 v105, 0xbfb8aa3b, v90
	v_mul_f32_e32 v106, 0xbfb8aa3b, v91
	v_mul_f32_e32 v107, 0xbfb8aa3b, v92
	v_mul_f32_e32 v108, 0xbfb8aa3b, v93
	v_exp_f32_e32 v99, v99
	v_exp_f32_e32 v102, v102
	v_exp_f32_e32 v103, v103
	v_exp_f32_e32 v104, v104
	v_exp_f32_e32 v105, v105
	v_exp_f32_e32 v106, v106
	v_exp_f32_e32 v107, v107
	v_exp_f32_e32 v108, v108
	v_add_f32_e32 v99, 1.0, v99
	v_add_f32_e32 v109, 1.0, v102
	v_add_f32_e32 v111, 1.0, v103
	v_add_f32_e32 v112, 1.0, v104
	v_add_f32_e32 v113, 1.0, v105
	v_add_f32_e32 v114, 1.0, v106
	v_add_f32_e32 v115, 1.0, v107
	v_add_f32_e32 v116, 1.0, v108
	v_rcp_f32_e32 v102, v99
	v_rcp_f32_e32 v103, v109
	v_rcp_f32_e32 v104, v111
	v_rcp_f32_e32 v105, v112
	v_rcp_f32_e32 v106, v113
	v_rcp_f32_e32 v107, v114
	v_rcp_f32_e32 v108, v115
	v_rcp_f32_e32 v109, v116
	v_pk_mul_f32 v[94:95], v[94:95], v[102:103]
	v_pk_mul_f32 v[96:97], v[96:97], v[104:105]
	v_pk_mul_f32 v[90:91], v[90:91], v[106:107]
	v_pk_mul_f32 v[92:93], v[92:93], v[108:109]
	v_pk_mul_f32 v[86:87], v[86:87], v[94:95]
	v_pk_mul_f32 v[88:89], v[88:89], v[96:97]
	v_pk_mul_f32 v[90:91], v[82:83], v[90:91]
	v_pk_mul_f32 v[92:93], v[84:85], v[92:93]
	v_cvt_pk_bf16_f32 v82, v86, v87
	v_cvt_pk_bf16_f32 v83, v88, v89
	v_cvt_pk_bf16_f32 v84, v90, v91
	v_cvt_pk_bf16_f32 v85, v92, v93
	global_store_dwordx4 v110, v[82:85], s[40:41] sc1
	s_nop 0
	s_nop 0
	v_lshlrev_b32_e32 v84, 6, v98
	v_and_or_b32 v84, v84, s64, v152
	v_lshlrev_b32_e32 v90, 1, v84
	v_mov_b32_e32 v82, v177
	v_fmamk_f32 v82, v82, 0x39800000, v156
	v_mul_f32_e32 v83, 0x4f800000, v82
	v_cmp_gt_f32_e32 vcc, s61, v82
	s_nop 1
	v_cndmask_b32_e32 v82, v82, v83, vcc
	v_sqrt_f32_e32 v83, v82
	s_nop 0
	v_add_u32_e32 v85, -1, v83
	v_add_u32_e32 v86, 1, v83
	v_fma_f32 v87, -v85, v83, v82
	v_fma_f32 v88, -v86, v83, v82
; __host__ __device__ __forceinline__ size_t blk(int r, int k, int K) { return (((size_t)((r >> 8) * (K >> 6) + (k >> 6))) << 14) + (size_t)(((r & 255) << 6) + (k & 63)); }
; __device__ __forceinline__ unsigned pk2(float lo, float hi) { f32x2 v = {lo, hi}; bf16x2_t b = __builtin_convertvector(v, bf16x2_t); return __builtin_bit_cast(unsigned, b); }
; __device__ __forceinline__ float fsilu(float x) { return x * fsigmoid(x); }
;     __device__ __forceinline__ void operator()(const f32x4 (&acc)[2][2][4][2], const Unit& u, int wr, int wc, int fr, int fq) const {
;     ...
;             for (int m = 0; m < 4; ++m) { const int row = row0 + ai * HALF + m * 16; bf16_t* rowp = O + blk(row, col0, ldc);
;                 const float rs = ssq ? 1.0f / sqrtf(ssq[row] * (1.0f / D) + RMS_EPS) : 1.0f;
;                 const f32x4 a0 = acc[ai][0][m][0] * rs, a1 = acc[ai][0][m][1] * rs, b0 = acc[ai][1][m][0] * rs, b1 = acc[ai][1][m][1] * rs;
;                 u32x4 w; w.x = pk2(fsilu(a0[0]) * b0[0], fsilu(a0[1]) * b0[1]); w.y = pk2(fsilu(a0[2]) * b0[2], fsilu(a0[3]) * b0[3]);
;                 w.z = pk2(fsilu(a1[0]) * b1[0], fsilu(a1[1]) * b1[1]); w.w = pk2(fsilu(a1[2]) * b1[2], fsilu(a1[3]) * b1[3]);
;                 *(u32x4*)rowp = w; }
	v_cmp_ge_f32_e64 s[4:5], 0, v87
	s_nop 1
	v_cndmask_b32_e64 v83, v83, v85, s[4:5]
	v_cmp_lt_f32_e64 s[4:5], 0, v88
	s_nop 1
	v_cndmask_b32_e64 v83, v83, v86, s[4:5]
	v_mul_f32_e32 v85, 0x37800000, v83
	v_cndmask_b32_e32 v83, v83, v85, vcc
	v_cmp_class_f32_e32 vcc, v82, v157
	s_nop 1
	v_cndmask_b32_e32 v82, v83, v82, vcc
	v_div_scale_f32 v83, s[4:5], v82, v82, 1.0
	v_rcp_f32_e32 v85, v83
	v_div_scale_f32 v84, vcc, 1.0, v82, 1.0
	v_fma_f32 v86, -v83, v85, 1.0
	v_fmac_f32_e32 v85, v86, v85
	v_mul_f32_e32 v86, v84, v85
	v_fma_f32 v87, -v83, v86, v84
	v_fmac_f32_e32 v86, v87, v85
	v_fma_f32 v83, -v83, v86, v84
	v_div_fmas_f32 v83, v83, v85, v86
	v_div_fixup_f32 v82, v83, v82, 1.0
	v_pk_mul_f32 v[80:81], v[80:81], v[82:83] op_sel_hi:[1,0]
	v_pk_mul_f32 v[78:79], v[78:79], v[82:83] op_sel_hi:[1,0]
	v_pk_mul_f32 v[76:77], v[76:77], v[82:83] op_sel_hi:[1,0]
	v_pk_mul_f32 v[74:75], v[74:75], v[82:83] op_sel_hi:[1,0]
	v_pk_mul_f32 v[72:73], v[72:73], v[82:83] op_sel_hi:[1,0]
	v_pk_mul_f32 v[70:71], v[70:71], v[82:83] op_sel_hi:[1,0]
	v_pk_mul_f32 v[68:69], v[68:69], v[82:83] op_sel_hi:[1,0]
	v_pk_mul_f32 v[66:67], v[66:67], v[82:83] op_sel_hi:[1,0]
	v_mul_f32_e32 v82, 0xbfb8aa3b, v78
	v_mul_f32_e32 v83, 0xbfb8aa3b, v79
	v_mul_f32_e32 v84, 0xbfb8aa3b, v80
	v_mul_f32_e32 v85, 0xbfb8aa3b, v81
	v_mul_f32_e32 v86, 0xbfb8aa3b, v74
	v_mul_f32_e32 v87, 0xbfb8aa3b, v75
	v_mul_f32_e32 v88, 0xbfb8aa3b, v76
	v_mul_f32_e32 v89, 0xbfb8aa3b, v77
	v_exp_f32_e32 v82, v82
	v_exp_f32_e32 v83, v83
	v_exp_f32_e32 v84, v84
	v_exp_f32_e32 v85, v85
	v_exp_f32_e32 v86, v86
	v_exp_f32_e32 v87, v87
	v_exp_f32_e32 v88, v88
	v_exp_f32_e32 v89, v89
	v_add_f32_e32 v82, 1.0, v82
	v_add_f32_e32 v83, 1.0, v83
	v_add_f32_e32 v84, 1.0, v84
	v_add_f32_e32 v85, 1.0, v85
	v_add_f32_e32 v86, 1.0, v86
	v_add_f32_e32 v87, 1.0, v87
	v_add_f32_e32 v88, 1.0, v88
	v_add_f32_e32 v89, 1.0, v89
	v_rcp_f32_e32 v82, v82
	v_rcp_f32_e32 v83, v83
	v_rcp_f32_e32 v84, v84
	v_rcp_f32_e32 v85, v85
	v_rcp_f32_e32 v86, v86
	v_rcp_f32_e32 v87, v87
	v_rcp_f32_e32 v88, v88
	v_rcp_f32_e32 v89, v89
	v_pk_mul_f32 v[78:79], v[78:79], v[82:83]
	v_pk_mul_f32 v[80:81], v[80:81], v[84:85]
	v_pk_mul_f32 v[74:75], v[74:75], v[86:87]
	v_pk_mul_f32 v[76:77], v[76:77], v[88:89]
	v_pk_mul_f32 v[70:71], v[70:71], v[78:79]
	v_pk_mul_f32 v[72:73], v[72:73], v[80:81]
	v_pk_mul_f32 v[74:75], v[66:67], v[74:75]
	v_pk_mul_f32 v[76:77], v[68:69], v[76:77]
	v_cvt_pk_bf16_f32 v66, v70, v71
	v_cvt_pk_bf16_f32 v67, v72, v73
	v_cvt_pk_bf16_f32 v68, v74, v75
	v_cvt_pk_bf16_f32 v69, v76, v77
	global_store_dwordx4 v90, v[66:69], s[40:41] sc1
	s_nop 0
	s_nop 0
	v_add_u32_e32 v66, 0x80, v150
	v_mov_b32_e32 v67, s17
	v_lshrrev_b32_e32 v69, 8, v66
	v_lshlrev_b32_e32 v70, 6, v66
	v_mad_i32_i24 v66, v69, s58, v67
	v_and_or_b32 v69, v70, s59, v152
	v_lshlrev_b32_e32 v138, 1, v69
	v_ashrrev_i32_e32 v67, 31, v66
	v_lshlrev_b64 v[66:67], 15, v[66:67]
	v_lshl_add_u64 v[66:67], s[20:21], 0, v[66:67]
	v_mov_b32_e32 v68, v180
	v_fmamk_f32 v68, v68, 0x39800000, v156
	v_mul_f32_e32 v70, 0x4f800000, v68
	v_cmp_gt_f32_e32 vcc, s61, v68
	s_nop 1
	v_cndmask_b32_e32 v68, v68, v70, vcc
	v_sqrt_f32_e32 v70, v68
	s_nop 0
	v_add_u32_e32 v69, -1, v70
	v_add_u32_e32 v71, 1, v70
	v_fma_f32 v72, -v69, v70, v68
	v_fma_f32 v73, -v71, v70, v68
	v_cmp_ge_f32_e64 s[4:5], 0, v72
	s_nop 1
	v_cndmask_b32_e64 v69, v70, v69, s[4:5]
	v_cmp_lt_f32_e64 s[4:5], 0, v73
	s_nop 1
	v_cndmask_b32_e64 v69, v69, v71, s[4:5]
	v_mul_f32_e32 v70, 0x37800000, v69
	v_cndmask_b32_e32 v69, v69, v70, vcc
	v_cmp_class_f32_e32 vcc, v68, v157
	s_nop 1
	v_cndmask_b32_e32 v70, v69, v68, vcc
	v_div_scale_f32 v71, s[4:5], v70, v70, 1.0
	v_rcp_f32_e32 v72, v71
	v_div_scale_f32 v73, vcc, 1.0, v70, 1.0
	v_lshl_add_u64 v[68:69], v[66:67], 0, v[138:139]
	v_fma_f32 v74, -v71, v72, 1.0
	v_fmac_f32_e32 v72, v74, v72
	v_mul_f32_e32 v74, v73, v72
	v_fma_f32 v75, -v71, v74, v73
	v_fmac_f32_e32 v74, v75, v72
	v_fma_f32 v71, -v71, v74, v73
	v_div_fmas_f32 v71, v71, v72, v74
	v_div_fixup_f32 v70, v71, v70, 1.0
	v_pk_mul_f32 v[64:65], v[64:65], v[70:71] op_sel_hi:[1,0]
	v_pk_mul_f32 v[62:63], v[62:63], v[70:71] op_sel_hi:[1,0]
	v_pk_mul_f32 v[60:61], v[60:61], v[70:71] op_sel_hi:[1,0]
	v_pk_mul_f32 v[58:59], v[58:59], v[70:71] op_sel_hi:[1,0]
	v_pk_mul_f32 v[56:57], v[56:57], v[70:71] op_sel_hi:[1,0]
	v_pk_mul_f32 v[54:55], v[54:55], v[70:71] op_sel_hi:[1,0]
	v_pk_mul_f32 v[52:53], v[52:53], v[70:71] op_sel_hi:[1,0]
	v_pk_mul_f32 v[50:51], v[50:51], v[70:71] op_sel_hi:[1,0]
	v_mul_f32_e32 v70, 0xbfb8aa3b, v62
	v_mul_f32_e32 v71, 0xbfb8aa3b, v63
	v_mul_f32_e32 v72, 0xbfb8aa3b, v64
	v_mul_f32_e32 v73, 0xbfb8aa3b, v65
	v_mul_f32_e32 v74, 0xbfb8aa3b, v58
	v_mul_f32_e32 v75, 0xbfb8aa3b, v59
	v_mul_f32_e32 v76, 0xbfb8aa3b, v60
	v_mul_f32_e32 v77, 0xbfb8aa3b, v61
	v_exp_f32_e32 v70, v70
	v_exp_f32_e32 v71, v71
	v_exp_f32_e32 v72, v72
	v_exp_f32_e32 v73, v73
	v_exp_f32_e32 v74, v74
	v_exp_f32_e32 v75, v75
	v_exp_f32_e32 v76, v76
	v_exp_f32_e32 v77, v77
	v_add_f32_e32 v70, 1.0, v70
	v_add_f32_e32 v71, 1.0, v71
	v_add_f32_e32 v72, 1.0, v72
	v_add_f32_e32 v73, 1.0, v73
	v_add_f32_e32 v74, 1.0, v74
	v_add_f32_e32 v75, 1.0, v75
	v_add_f32_e32 v76, 1.0, v76
	v_add_f32_e32 v77, 1.0, v77
	v_rcp_f32_e32 v70, v70
	v_rcp_f32_e32 v71, v71
	v_rcp_f32_e32 v72, v72
	v_rcp_f32_e32 v73, v73
	v_rcp_f32_e32 v74, v74
	v_rcp_f32_e32 v75, v75
	v_rcp_f32_e32 v76, v76
	v_rcp_f32_e32 v77, v77
	v_pk_mul_f32 v[62:63], v[62:63], v[70:71]
	v_pk_mul_f32 v[64:65], v[64:65], v[72:73]
	v_pk_mul_f32 v[58:59], v[58:59], v[74:75]
	v_pk_mul_f32 v[60:61], v[60:61], v[76:77]
	v_pk_mul_f32 v[54:55], v[54:55], v[62:63]
	v_pk_mul_f32 v[56:57], v[56:57], v[64:65]
; __host__ __device__ __forceinline__ size_t blk(int r, int k, int K) { return (((size_t)((r >> 8) * (K >> 6) + (k >> 6))) << 14) + (size_t)(((r & 255) << 6) + (k & 63)); }
; __device__ __forceinline__ unsigned pk2(float lo, float hi) { f32x2 v = {lo, hi}; bf16x2_t b = __builtin_convertvector(v, bf16x2_t); return __builtin_bit_cast(unsigned, b); }
; __device__ __forceinline__ float fsilu(float x) { return x * fsigmoid(x); }
;     __device__ __forceinline__ void operator()(const f32x4 (&acc)[2][2][4][2], const Unit& u, int wr, int wc, int fr, int fq) const {
;     ...
;             for (int m = 0; m < 4; ++m) { const int row = row0 + ai * HALF + m * 16; bf16_t* rowp = O + blk(row, col0, ldc);
;                 const float rs = ssq ? 1.0f / sqrtf(ssq[row] * (1.0f / D) + RMS_EPS) : 1.0f;
;                 const f32x4 a0 = acc[ai][0][m][0] * rs, a1 = acc[ai][0][m][1] * rs, b0 = acc[ai][1][m][0] * rs, b1 = acc[ai][1][m][1] * rs;
;                 u32x4 w; w.x = pk2(fsilu(a0[0]) * b0[0], fsilu(a0[1]) * b0[1]); w.y = pk2(fsilu(a0[2]) * b0[2], fsilu(a0[3]) * b0[3]);
;                 w.z = pk2(fsilu(a1[0]) * b1[0], fsilu(a1[1]) * b1[1]); w.w = pk2(fsilu(a1[2]) * b1[2], fsilu(a1[3]) * b1[3]);
;                 *(u32x4*)rowp = w; }
	v_pk_mul_f32 v[58:59], v[50:51], v[58:59]
	v_pk_mul_f32 v[60:61], v[52:53], v[60:61]
	v_cvt_pk_bf16_f32 v50, v54, v55
	v_cvt_pk_bf16_f32 v51, v56, v57
	v_cvt_pk_bf16_f32 v52, v58, v59
	v_cvt_pk_bf16_f32 v53, v60, v61
	global_store_dwordx4 v[68:69], v[50:53], off sc1
	s_nop 0
	s_nop 0
	v_add_u32_e32 v52, 0x2400, v151
	v_and_or_b32 v52, v52, s62, v152
	v_lshlrev_b32_e32 v138, 1, v52
	v_mov_b32_e32 v50, v181
	v_fmamk_f32 v50, v50, 0x39800000, v156
	v_mul_f32_e32 v51, 0x4f800000, v50
	v_cmp_gt_f32_e32 vcc, s61, v50
	s_nop 1
	v_cndmask_b32_e32 v50, v50, v51, vcc
	v_sqrt_f32_e32 v51, v50
	s_nop 0
	v_add_u32_e32 v52, -1, v51
	v_add_u32_e32 v53, 1, v51
	v_fma_f32 v54, -v52, v51, v50
	v_fma_f32 v55, -v53, v51, v50
	v_cmp_ge_f32_e64 s[4:5], 0, v54
	s_nop 1
	v_cndmask_b32_e64 v51, v51, v52, s[4:5]
	v_cmp_lt_f32_e64 s[4:5], 0, v55
	s_nop 1
	v_cndmask_b32_e64 v51, v51, v53, s[4:5]
	v_mul_f32_e32 v52, 0x37800000, v51
	v_cndmask_b32_e32 v51, v51, v52, vcc
	v_cmp_class_f32_e32 vcc, v50, v157
	s_nop 1
	v_cndmask_b32_e32 v52, v51, v50, vcc
	v_div_scale_f32 v53, s[4:5], v52, v52, 1.0
	v_rcp_f32_e32 v54, v53
	v_div_scale_f32 v55, vcc, 1.0, v52, 1.0
	v_lshl_add_u64 v[50:51], v[66:67], 0, v[138:139]
	v_fma_f32 v56, -v53, v54, 1.0
	v_fmac_f32_e32 v54, v56, v54
	v_mul_f32_e32 v56, v55, v54
	v_fma_f32 v57, -v53, v56, v55
	v_fmac_f32_e32 v56, v57, v54
	v_fma_f32 v53, -v53, v56, v55
	v_div_fmas_f32 v53, v53, v54, v56
	v_div_fixup_f32 v52, v53, v52, 1.0
	v_pk_mul_f32 v[48:49], v[48:49], v[52:53] op_sel_hi:[1,0]
	v_pk_mul_f32 v[46:47], v[46:47], v[52:53] op_sel_hi:[1,0]
	v_pk_mul_f32 v[44:45], v[44:45], v[52:53] op_sel_hi:[1,0]
	v_pk_mul_f32 v[42:43], v[42:43], v[52:53] op_sel_hi:[1,0]
	v_pk_mul_f32 v[40:41], v[40:41], v[52:53] op_sel_hi:[1,0]
	v_pk_mul_f32 v[38:39], v[38:39], v[52:53] op_sel_hi:[1,0]
	v_pk_mul_f32 v[36:37], v[36:37], v[52:53] op_sel_hi:[1,0]
	v_pk_mul_f32 v[34:35], v[34:35], v[52:53] op_sel_hi:[1,0]
	v_mul_f32_e32 v52, 0xbfb8aa3b, v46
	v_mul_f32_e32 v53, 0xbfb8aa3b, v47
	v_mul_f32_e32 v54, 0xbfb8aa3b, v48
	v_mul_f32_e32 v55, 0xbfb8aa3b, v49
	v_mul_f32_e32 v56, 0xbfb8aa3b, v42
	v_mul_f32_e32 v57, 0xbfb8aa3b, v43
	v_mul_f32_e32 v58, 0xbfb8aa3b, v44
	v_mul_f32_e32 v59, 0xbfb8aa3b, v45
	v_exp_f32_e32 v52, v52
	v_exp_f32_e32 v53, v53
	v_exp_f32_e32 v54, v54
	v_exp_f32_e32 v55, v55
	v_exp_f32_e32 v56, v56
	v_exp_f32_e32 v57, v57
	v_exp_f32_e32 v58, v58
	v_exp_f32_e32 v59, v59
	v_add_f32_e32 v52, 1.0, v52
	v_add_f32_e32 v53, 1.0, v53
	v_add_f32_e32 v54, 1.0, v54
	v_add_f32_e32 v55, 1.0, v55
	v_add_f32_e32 v56, 1.0, v56
	v_add_f32_e32 v57, 1.0, v57
	v_add_f32_e32 v58, 1.0, v58
	v_add_f32_e32 v59, 1.0, v59
	v_rcp_f32_e32 v52, v52
	v_rcp_f32_e32 v53, v53
	v_rcp_f32_e32 v54, v54
	v_rcp_f32_e32 v55, v55
	v_rcp_f32_e32 v56, v56
	v_rcp_f32_e32 v57, v57
	v_rcp_f32_e32 v58, v58
	v_rcp_f32_e32 v59, v59
	v_pk_mul_f32 v[46:47], v[46:47], v[52:53]
	v_pk_mul_f32 v[48:49], v[48:49], v[54:55]
	v_pk_mul_f32 v[42:43], v[42:43], v[56:57]
	v_pk_mul_f32 v[44:45], v[44:45], v[58:59]
	v_pk_mul_f32 v[38:39], v[38:39], v[46:47]
	v_pk_mul_f32 v[40:41], v[40:41], v[48:49]
	v_pk_mul_f32 v[42:43], v[34:35], v[42:43]
	v_pk_mul_f32 v[44:45], v[36:37], v[44:45]
	v_cvt_pk_bf16_f32 v34, v38, v39
	v_cvt_pk_bf16_f32 v35, v40, v41
	v_cvt_pk_bf16_f32 v36, v42, v43
	v_cvt_pk_bf16_f32 v37, v44, v45
	global_store_dwordx4 v[50:51], v[34:37], off sc1
	s_nop 0
	s_nop 0
	v_add_u32_e32 v36, 0x2800, v151
	v_and_or_b32 v36, v36, s63, v152
	v_lshlrev_b32_e32 v138, 1, v36
	v_mov_b32_e32 v34, v182
	v_fmamk_f32 v34, v34, 0x39800000, v156
	v_mul_f32_e32 v35, 0x4f800000, v34
	v_cmp_gt_f32_e32 vcc, s61, v34
	s_nop 1
	v_cndmask_b32_e32 v34, v34, v35, vcc
	v_sqrt_f32_e32 v35, v34
	s_nop 0
	v_add_u32_e32 v36, -1, v35
	v_add_u32_e32 v37, 1, v35
	v_fma_f32 v38, -v36, v35, v34
	v_fma_f32 v39, -v37, v35, v34
	v_cmp_ge_f32_e64 s[4:5], 0, v38
	s_nop 1
	v_cndmask_b32_e64 v35, v35, v36, s[4:5]
	v_cmp_lt_f32_e64 s[4:5], 0, v39
	s_nop 1
	v_cndmask_b32_e64 v35, v35, v37, s[4:5]
	v_mul_f32_e32 v36, 0x37800000, v35
	v_cndmask_b32_e32 v35, v35, v36, vcc
	v_cmp_class_f32_e32 vcc, v34, v157
	s_nop 1
	v_cndmask_b32_e32 v36, v35, v34, vcc
	v_div_scale_f32 v37, s[4:5], v36, v36, 1.0
	v_rcp_f32_e32 v38, v37
	v_div_scale_f32 v39, vcc, 1.0, v36, 1.0
	v_lshl_add_u64 v[34:35], v[66:67], 0, v[138:139]
	v_fma_f32 v40, -v37, v38, 1.0
	v_fmac_f32_e32 v38, v40, v38
	v_mul_f32_e32 v40, v39, v38
	v_fma_f32 v41, -v37, v40, v39
	v_fmac_f32_e32 v40, v41, v38
	v_fma_f32 v37, -v37, v40, v39
	v_div_fmas_f32 v37, v37, v38, v40
	v_div_fixup_f32 v36, v37, v36, 1.0
	v_pk_mul_f32 v[32:33], v[32:33], v[36:37] op_sel_hi:[1,0]
	v_pk_mul_f32 v[30:31], v[30:31], v[36:37] op_sel_hi:[1,0]
	v_pk_mul_f32 v[28:29], v[28:29], v[36:37] op_sel_hi:[1,0]
	v_pk_mul_f32 v[26:27], v[26:27], v[36:37] op_sel_hi:[1,0]
	v_pk_mul_f32 v[24:25], v[24:25], v[36:37] op_sel_hi:[1,0]
; __host__ __device__ __forceinline__ size_t blk(int r, int k, int K) { return (((size_t)((r >> 8) * (K >> 6) + (k >> 6))) << 14) + (size_t)(((r & 255) << 6) + (k & 63)); }
; __device__ __forceinline__ unsigned pk2(float lo, float hi) { f32x2 v = {lo, hi}; bf16x2_t b = __builtin_convertvector(v, bf16x2_t); return __builtin_bit_cast(unsigned, b); }
; __device__ __forceinline__ float fsilu(float x) { return x * fsigmoid(x); }
; #define PG8_BAR __builtin_amdgcn_s_barrier()
;     __device__ __forceinline__ void operator()(const f32x4 (&acc)[2][2][4][2], const Unit& u, int wr, int wc, int fr, int fq) const {
;     ...
;             for (int m = 0; m < 4; ++m) { const int row = row0 + ai * HALF + m * 16; bf16_t* rowp = O + blk(row, col0, ldc);
;                 const float rs = ssq ? 1.0f / sqrtf(ssq[row] * (1.0f / D) + RMS_EPS) : 1.0f;
;                 const f32x4 a0 = acc[ai][0][m][0] * rs, a1 = acc[ai][0][m][1] * rs, b0 = acc[ai][1][m][0] * rs, b1 = acc[ai][1][m][1] * rs;
;                 u32x4 w; w.x = pk2(fsilu(a0[0]) * b0[0], fsilu(a0[1]) * b0[1]); w.y = pk2(fsilu(a0[2]) * b0[2], fsilu(a0[3]) * b0[3]);
;                 w.z = pk2(fsilu(a1[0]) * b1[0], fsilu(a1[1]) * b1[1]); w.w = pk2(fsilu(a1[2]) * b1[2], fsilu(a1[3]) * b1[3]);
;                 *(u32x4*)rowp = w; }
; template <class Epi, class Sched, bool ALIGN_EPI = false, bool SP2 = false>
; __device__ __forceinline__ void gemm_phase(PG8_LAS unsigned char* lds, const Gemm g, const Sched& S, const Epi& E) {
;     ...
;         if constexpr (ALIGN_EPI) { if (wr == 0) PG8_BAR; }
;         if constexpr (!Epi::AFTER_DRAIN) { E(acc, cur, wr, wc, fr, fq); S.done(cur); }
;         if (!has_next) break;
; #pragma unroll
;         for (int a = 0; a < 2; ++a)
; #pragma unroll
;             for (int b = 0; b < 2; ++b)
; #pragma unroll
;                 for (int m = 0; m < 4; ++m)
; #pragma unroll
;                     for (int n = 0; n < 2; ++n) acc[a][b][m][n] = (f32x4){0.f, 0.f, 0.f, 0.f};
;         cur = nxt; cA = nA; cB = nB; ++ui;
;         if constexpr (ALIGN_EPI) { if (wr == 1) PG8_BAR; }
	v_pk_mul_f32 v[22:23], v[22:23], v[36:37] op_sel_hi:[1,0]
	v_pk_mul_f32 v[20:21], v[20:21], v[36:37] op_sel_hi:[1,0]
	v_pk_mul_f32 v[18:19], v[18:19], v[36:37] op_sel_hi:[1,0]
	v_mul_f32_e32 v36, 0xbfb8aa3b, v30
	v_mul_f32_e32 v37, 0xbfb8aa3b, v31
	v_mul_f32_e32 v38, 0xbfb8aa3b, v32
	v_mul_f32_e32 v39, 0xbfb8aa3b, v33
	v_mul_f32_e32 v40, 0xbfb8aa3b, v26
	v_mul_f32_e32 v41, 0xbfb8aa3b, v27
	v_mul_f32_e32 v42, 0xbfb8aa3b, v28
	v_mul_f32_e32 v43, 0xbfb8aa3b, v29
	v_exp_f32_e32 v36, v36
	v_exp_f32_e32 v37, v37
	v_exp_f32_e32 v38, v38
	v_exp_f32_e32 v39, v39
	v_exp_f32_e32 v40, v40
	v_exp_f32_e32 v41, v41
	v_exp_f32_e32 v42, v42
	v_exp_f32_e32 v43, v43
	v_add_f32_e32 v36, 1.0, v36
	v_add_f32_e32 v37, 1.0, v37
	v_add_f32_e32 v38, 1.0, v38
	v_add_f32_e32 v39, 1.0, v39
	v_add_f32_e32 v40, 1.0, v40
	v_add_f32_e32 v41, 1.0, v41
	v_add_f32_e32 v42, 1.0, v42
	v_add_f32_e32 v43, 1.0, v43
	v_rcp_f32_e32 v36, v36
	v_rcp_f32_e32 v37, v37
	v_rcp_f32_e32 v38, v38
	v_rcp_f32_e32 v39, v39
	v_rcp_f32_e32 v40, v40
	v_rcp_f32_e32 v41, v41
	v_rcp_f32_e32 v42, v42
	v_rcp_f32_e32 v43, v43
	v_pk_mul_f32 v[30:31], v[30:31], v[36:37]
	v_pk_mul_f32 v[32:33], v[32:33], v[38:39]
	v_pk_mul_f32 v[26:27], v[26:27], v[40:41]
	v_pk_mul_f32 v[28:29], v[28:29], v[42:43]
	v_pk_mul_f32 v[22:23], v[22:23], v[30:31]
	v_pk_mul_f32 v[24:25], v[24:25], v[32:33]
	v_pk_mul_f32 v[26:27], v[18:19], v[26:27]
	v_pk_mul_f32 v[28:29], v[20:21], v[28:29]
	v_cvt_pk_bf16_f32 v18, v22, v23
	v_cvt_pk_bf16_f32 v19, v24, v25
	v_cvt_pk_bf16_f32 v20, v26, v27
	v_cvt_pk_bf16_f32 v21, v28, v29
	global_store_dwordx4 v[34:35], v[18:21], off sc1
	s_nop 0
	s_nop 0
	v_add_u32_e32 v20, 0x2c00, v151
	v_and_or_b32 v20, v20, s64, v152
	v_lshlrev_b32_e32 v138, 1, v20
	v_mov_b32_e32 v18, v183
	v_fmamk_f32 v18, v18, 0x39800000, v156
	v_mul_f32_e32 v19, 0x4f800000, v18
	v_cmp_gt_f32_e32 vcc, s61, v18
	s_nop 1
	v_cndmask_b32_e32 v18, v18, v19, vcc
	v_sqrt_f32_e32 v19, v18
	s_nop 0
	v_add_u32_e32 v20, -1, v19
	v_add_u32_e32 v21, 1, v19
	v_fma_f32 v22, -v20, v19, v18
	v_fma_f32 v23, -v21, v19, v18
	v_cmp_ge_f32_e64 s[4:5], 0, v22
	s_nop 1
	v_cndmask_b32_e64 v19, v19, v20, s[4:5]
	v_cmp_lt_f32_e64 s[4:5], 0, v23
	s_nop 1
	v_cndmask_b32_e64 v19, v19, v21, s[4:5]
	v_mul_f32_e32 v20, 0x37800000, v19
	v_cndmask_b32_e32 v19, v19, v20, vcc
	v_cmp_class_f32_e32 vcc, v18, v157
	s_nop 1
	v_cndmask_b32_e32 v20, v19, v18, vcc
	v_div_scale_f32 v21, s[4:5], v20, v20, 1.0
	v_rcp_f32_e32 v22, v21
	v_div_scale_f32 v23, vcc, 1.0, v20, 1.0
	v_lshl_add_u64 v[18:19], v[66:67], 0, v[138:139]
	v_fma_f32 v24, -v21, v22, 1.0
	v_fmac_f32_e32 v22, v24, v22
	v_mul_f32_e32 v24, v23, v22
	v_fma_f32 v25, -v21, v24, v23
	v_fmac_f32_e32 v24, v25, v22
	v_fma_f32 v21, -v21, v24, v23
	v_div_fmas_f32 v21, v21, v22, v24
	v_div_fixup_f32 v20, v21, v20, 1.0
	v_pk_mul_f32 v[16:17], v[16:17], v[20:21] op_sel_hi:[1,0]
	v_pk_mul_f32 v[14:15], v[14:15], v[20:21] op_sel_hi:[1,0]
	v_pk_mul_f32 v[12:13], v[12:13], v[20:21] op_sel_hi:[1,0]
	v_pk_mul_f32 v[10:11], v[10:11], v[20:21] op_sel_hi:[1,0]
	v_pk_mul_f32 v[8:9], v[8:9], v[20:21] op_sel_hi:[1,0]
	v_pk_mul_f32 v[6:7], v[6:7], v[20:21] op_sel_hi:[1,0]
	v_pk_mul_f32 v[4:5], v[4:5], v[20:21] op_sel_hi:[1,0]
	v_pk_mul_f32 v[2:3], v[2:3], v[20:21] op_sel_hi:[1,0]
	v_mul_f32_e32 v20, 0xbfb8aa3b, v14
	v_mul_f32_e32 v21, 0xbfb8aa3b, v15
	v_mul_f32_e32 v22, 0xbfb8aa3b, v16
	v_mul_f32_e32 v23, 0xbfb8aa3b, v17
	v_mul_f32_e32 v24, 0xbfb8aa3b, v10
	v_mul_f32_e32 v25, 0xbfb8aa3b, v11
	v_mul_f32_e32 v26, 0xbfb8aa3b, v12
	v_mul_f32_e32 v27, 0xbfb8aa3b, v13
	v_exp_f32_e32 v20, v20
	v_exp_f32_e32 v21, v21
	v_exp_f32_e32 v22, v22
	v_exp_f32_e32 v23, v23
	v_exp_f32_e32 v24, v24
	v_exp_f32_e32 v25, v25
	v_exp_f32_e32 v26, v26
	v_exp_f32_e32 v27, v27
	v_add_f32_e32 v20, 1.0, v20
	v_add_f32_e32 v21, 1.0, v21
	v_add_f32_e32 v22, 1.0, v22
	v_add_f32_e32 v23, 1.0, v23
	v_add_f32_e32 v24, 1.0, v24
	v_add_f32_e32 v25, 1.0, v25
	v_add_f32_e32 v26, 1.0, v26
	v_add_f32_e32 v27, 1.0, v27
	v_rcp_f32_e32 v20, v20
	v_rcp_f32_e32 v21, v21
	v_rcp_f32_e32 v22, v22
	v_rcp_f32_e32 v23, v23
	v_rcp_f32_e32 v24, v24
	v_rcp_f32_e32 v25, v25
	v_rcp_f32_e32 v26, v26
	v_rcp_f32_e32 v27, v27
	v_pk_mul_f32 v[14:15], v[14:15], v[20:21]
	v_pk_mul_f32 v[16:17], v[16:17], v[22:23]
	v_pk_mul_f32 v[10:11], v[10:11], v[24:25]
	v_pk_mul_f32 v[12:13], v[12:13], v[26:27]
	v_pk_mul_f32 v[6:7], v[6:7], v[14:15]
	v_pk_mul_f32 v[8:9], v[8:9], v[16:17]
	v_pk_mul_f32 v[10:11], v[2:3], v[10:11]
	v_pk_mul_f32 v[12:13], v[4:5], v[12:13]
	s_andn2_b64 vcc, exec, s[0:1]
	v_cvt_pk_bf16_f32 v2, v6, v7
	v_cvt_pk_bf16_f32 v3, v8, v9
	v_cvt_pk_bf16_f32 v4, v10, v11
	v_cvt_pk_bf16_f32 v5, v12, v13
	s_mov_b64 s[0:1], -1
	global_store_dwordx4 v[18:19], v[2:5], off sc1
	s_cbranch_vccnz .LBB0_836
	s_andn2_b64 vcc, exec, s[10:11]
	s_cbranch_vccnz .LBB0_835
	s_barrier
	s_branch .LBB0_835
